# hand-pipelined k-loops for in_gemm/out_gemm/moe_up (counted lgkmcnt/vmcnt, refill mid-stream) and hand-written combine(+modulate) row loops with prefetched row pairs and batched expert rows
# speedup vs baseline: 1.2481x; 1.0195x over previous
; template <bool COMBINE, bool MOD>
; __device__ __forceinline__ void phase_combine_modulate(const Params& p, int lprev, int lnext, const float* xlat, const float* xctx,
;                                                        float* olat, float* octx, int nrows) {
;     ...
;   for (int row0 = gw * R; row0 < nrows; row0 += nw * R) {
;     const bool lat = row0 < T_LAT;
;     const float* xr = lat ? xlat + (size_t)row0 * DM : xctx + (size_t)(row0 - T_LAT) * DM;
;     const int cond = row_cond(row0);
;     float4 v[R][4];
; #pragma unroll
;     for (int r = 0; r < R; ++r)
; #pragma unroll
;       for (int i = 0; i < 4; ++i) v[r][i] = *(const float4*)(xr + (size_t)r * DM + i * 256 + lane * 4);
;     ...
;     if (MOD) {
;       const float* sh = p.mada + (size_t)(lnext * 3 + cond) * 6144;
;       const float* sc = sh + 1024;
;       float rstd[R];
; #pragma unroll
;       for (int r = 0; r < R; ++r) {
;         float ss = 0.f;
; #pragma unroll
;         for (int i = 0; i < 4; ++i) ss += v[r][i].x * v[r][i].x + v[r][i].y * v[r][i].y + v[r][i].z * v[r][i].z + v[r][i].w * v[r][i].w;
;         rstd[r] = rsqrtf(wave_sum(ss) * (1.f / 1024.f) + 1e-6f);
;       }
; #pragma unroll
;       for (int i = 0; i < 4; ++i) {
;         const int col = i * 256 + lane * 4;
;         const float4 s4 = *(const float4*)(sc + col);
;         const float4 h4 = *(const float4*)(sh + col);
; #pragma unroll
;         for (int r = 0; r < R; ++r) {
;           u32x2 pk;
;           pk.x = pack2(v[r][i].x * rstd[r] * (1.f + s4.x) + h4.x, v[r][i].y * rstd[r] * (1.f + s4.y) + h4.y);
;           pk.y = pack2(v[r][i].z * rstd[r] * (1.f + s4.z) + h4.z, v[r][i].w * rstd[r] * (1.f + s4.w) + h4.w);
;           *(u32x2*)(p.H + (size_t)(row0 + r) * DM + col) = pk;
;         }
;       }
.Lmd0_loop:
	s_add_i32 s100, s38, s39
	s_cmp_lt_i32 s100, s68
	s_cbranch_scc0 .Lmd0_last_a
	s_min_i32 s0, s38, 0x4000
	s_ashr_i32 s0, s0, 13
	s_mul_i32 s0, s0, 0x6000
	s_add_u32 s56, s48, s0
	s_addc_u32 s57, s49, 0
	s_lshl_b32 s0, s38, 11
	s_add_u32 s98, s50, s0
	s_addc_u32 s99, s51, 0
	global_load_dwordx4 v[20:23], v80, s[56:57]
	global_load_dwordx4 v[24:27], v80, s[56:57] offset:1024
	global_load_dwordx4 v[28:31], v80, s[56:57] offset:2048
	global_load_dwordx4 v[32:35], v80, s[56:57] offset:3072
	global_load_dwordx4 v[36:39], v81, s[56:57]
	global_load_dwordx4 v[40:43], v81, s[56:57] offset:1024
	global_load_dwordx4 v[44:47], v81, s[56:57] offset:2048
	global_load_dwordx4 v[48:51], v81, s[56:57] offset:3072
	s_cmpk_lt_i32 s100, 0x4000
	s_cselect_b32 s0, s8, s34
	s_cselect_b32 s1, s9, s35
	s_cselect_b32 s56, 0, 0x4000
	s_sub_i32 s56, s100, s56
	s_lshl_b32 s56, s56, 12
	s_add_u32 s52, s0, s56
	s_addc_u32 s53, s1, 0
	global_load_dwordx4 v[132:135], v80, s[52:53]
	global_load_dwordx4 v[136:139], v80, s[52:53] offset:1024
	global_load_dwordx4 v[140:143], v80, s[52:53] offset:2048
	global_load_dwordx4 v[144:147], v80, s[52:53] offset:3072
	global_load_dwordx4 v[148:151], v81, s[52:53]
	global_load_dwordx4 v[152:155], v81, s[52:53] offset:1024
	global_load_dwordx4 v[156:159], v81, s[52:53] offset:2048
	global_load_dwordx4 v[160:163], v81, s[52:53] offset:3072
	s_waitcnt vmcnt(16)
	v_pk_mul_f32 v[8:9], v[100:101], v[100:101]
	v_pk_fma_f32 v[8:9], v[102:103], v[102:103], v[8:9]
	v_pk_fma_f32 v[8:9], v[104:105], v[104:105], v[8:9]
	v_pk_fma_f32 v[8:9], v[106:107], v[106:107], v[8:9]
	v_pk_fma_f32 v[8:9], v[108:109], v[108:109], v[8:9]
	v_pk_fma_f32 v[8:9], v[110:111], v[110:111], v[8:9]
	v_pk_fma_f32 v[8:9], v[112:113], v[112:113], v[8:9]
	v_pk_fma_f32 v[8:9], v[114:115], v[114:115], v[8:9]
	v_pk_mul_f32 v[10:11], v[116:117], v[116:117]
	v_pk_fma_f32 v[10:11], v[118:119], v[118:119], v[10:11]
	v_pk_fma_f32 v[10:11], v[120:121], v[120:121], v[10:11]
	v_pk_fma_f32 v[10:11], v[122:123], v[122:123], v[10:11]
	v_pk_fma_f32 v[10:11], v[124:125], v[124:125], v[10:11]
	v_pk_fma_f32 v[10:11], v[126:127], v[126:127], v[10:11]
	v_pk_fma_f32 v[10:11], v[128:129], v[128:129], v[10:11]
	v_pk_fma_f32 v[10:11], v[130:131], v[130:131], v[10:11]
	v_add_f32_e32 v6, v8, v9
	v_add_f32_e32 v7, v10, v11
	s_nop 1
	v_add_f32_dpp v6, v6, v6 quad_perm:[1,0,3,2] row_mask:0xf bank_mask:0xf
	v_add_f32_dpp v7, v7, v7 quad_perm:[1,0,3,2] row_mask:0xf bank_mask:0xf
	s_nop 1
	v_add_f32_dpp v6, v6, v6 quad_perm:[2,3,0,1] row_mask:0xf bank_mask:0xf
	v_add_f32_dpp v7, v7, v7 quad_perm:[2,3,0,1] row_mask:0xf bank_mask:0xf
	s_nop 1
	v_add_f32_dpp v6, v6, v6 row_half_mirror row_mask:0xf bank_mask:0xf
	v_add_f32_dpp v7, v7, v7 row_half_mirror row_mask:0xf bank_mask:0xf
	s_nop 1
	v_add_f32_dpp v6, v6, v6 row_mirror row_mask:0xf bank_mask:0xf
	v_add_f32_dpp v7, v7, v7 row_mirror row_mask:0xf bank_mask:0xf
	ds_bpermute_b32 v8, v83, v6
	ds_bpermute_b32 v9, v83, v7
	s_waitcnt lgkmcnt(0)
	v_pk_add_f32 v[6:7], v[6:7], v[8:9]
	ds_bpermute_b32 v8, v84, v6
	ds_bpermute_b32 v9, v84, v7
	s_waitcnt lgkmcnt(0)
	v_pk_add_f32 v[6:7], v[6:7], v[8:9]
	s_nop 0
	v_fma_f32 v6, v6, s101, v224
	v_fma_f32 v7, v7, s101, v224
	v_cmp_gt_f32_e32 vcc, s85, v6
	v_mul_f32_e32 v2, 0x4b800000, v6
	s_nop 1
	v_cndmask_b32_e32 v2, v6, v2, vcc
	v_rsq_f32_e32 v2, v2
	s_nop 0
	v_mul_f32_e32 v6, 0x45800000, v2
	v_cndmask_b32_e32 v2, v2, v6, vcc
	v_cmp_gt_f32_e32 vcc, s85, v7
	v_mul_f32_e32 v4, 0x4b800000, v7
	s_nop 1
	v_cndmask_b32_e32 v4, v7, v4, vcc
	v_rsq_f32_e32 v4, v4
	s_nop 0
	v_mul_f32_e32 v7, 0x45800000, v4
	v_cndmask_b32_e32 v4, v4, v7, vcc
	s_waitcnt vmcnt(8)
	v_pk_add_f32 v[36:37], v[36:37], 1.0 op_sel_hi:[1,0]
	v_pk_add_f32 v[38:39], v[38:39], 1.0 op_sel_hi:[1,0]
	v_pk_mul_f32 v[8:9], v[100:101], v[2:3] op_sel_hi:[1,0]
	v_pk_mul_f32 v[10:11], v[102:103], v[2:3] op_sel_hi:[1,0]
	v_pk_fma_f32 v[8:9], v[36:37], v[8:9], v[20:21]
	v_pk_fma_f32 v[10:11], v[38:39], v[10:11], v[22:23]
	v_cvt_pk_bf16_f32 v52, v8, v9
	v_cvt_pk_bf16_f32 v53, v10, v11
	global_store_dwordx2 v82, v[52:53], s[98:99]
	v_pk_mul_f32 v[12:13], v[116:117], v[4:5] op_sel_hi:[1,0]
	v_pk_mul_f32 v[14:15], v[118:119], v[4:5] op_sel_hi:[1,0]
	v_pk_fma_f32 v[12:13], v[36:37], v[12:13], v[20:21]
	v_pk_fma_f32 v[14:15], v[38:39], v[14:15], v[22:23]
	v_cvt_pk_bf16_f32 v54, v12, v13
	v_cvt_pk_bf16_f32 v55, v14, v15
	global_store_dwordx2 v82, v[54:55], s[98:99] offset:2048
	v_pk_add_f32 v[40:41], v[40:41], 1.0 op_sel_hi:[1,0]
	v_pk_add_f32 v[42:43], v[42:43], 1.0 op_sel_hi:[1,0]
	v_pk_mul_f32 v[8:9], v[104:105], v[2:3] op_sel_hi:[1,0]
	v_pk_mul_f32 v[10:11], v[106:107], v[2:3] op_sel_hi:[1,0]
	v_pk_fma_f32 v[8:9], v[40:41], v[8:9], v[24:25]
	v_pk_fma_f32 v[10:11], v[42:43], v[10:11], v[26:27]
	v_cvt_pk_bf16_f32 v56, v8, v9
	v_cvt_pk_bf16_f32 v57, v10, v11
	global_store_dwordx2 v82, v[56:57], s[98:99] offset:512
	v_pk_mul_f32 v[12:13], v[120:121], v[4:5] op_sel_hi:[1,0]
	v_pk_mul_f32 v[14:15], v[122:123], v[4:5] op_sel_hi:[1,0]
	v_pk_fma_f32 v[12:13], v[40:41], v[12:13], v[24:25]
	v_pk_fma_f32 v[14:15], v[42:43], v[14:15], v[26:27]
	v_cvt_pk_bf16_f32 v58, v12, v13
	v_cvt_pk_bf16_f32 v59, v14, v15
	global_store_dwordx2 v82, v[58:59], s[98:99] offset:2560
	v_pk_add_f32 v[44:45], v[44:45], 1.0 op_sel_hi:[1,0]
	v_pk_add_f32 v[46:47], v[46:47], 1.0 op_sel_hi:[1,0]
	v_pk_mul_f32 v[8:9], v[108:109], v[2:3] op_sel_hi:[1,0]
	v_pk_mul_f32 v[10:11], v[110:111], v[2:3] op_sel_hi:[1,0]
	v_pk_fma_f32 v[8:9], v[44:45], v[8:9], v[28:29]
	v_pk_fma_f32 v[10:11], v[46:47], v[10:11], v[30:31]
	v_cvt_pk_bf16_f32 v60, v8, v9
	v_cvt_pk_bf16_f32 v61, v10, v11
	global_store_dwordx2 v82, v[60:61], s[98:99] offset:1024
	v_pk_mul_f32 v[12:13], v[124:125], v[4:5] op_sel_hi:[1,0]
	v_pk_mul_f32 v[14:15], v[126:127], v[4:5] op_sel_hi:[1,0]
	v_pk_fma_f32 v[12:13], v[44:45], v[12:13], v[28:29]
	v_pk_fma_f32 v[14:15], v[46:47], v[14:15], v[30:31]
	v_cvt_pk_bf16_f32 v62, v12, v13
	v_cvt_pk_bf16_f32 v63, v14, v15
	global_store_dwordx2 v82, v[62:63], s[98:99] offset:3072
	v_pk_add_f32 v[48:49], v[48:49], 1.0 op_sel_hi:[1,0]
	v_pk_add_f32 v[50:51], v[50:51], 1.0 op_sel_hi:[1,0]
	v_pk_mul_f32 v[8:9], v[112:113], v[2:3] op_sel_hi:[1,0]
	v_pk_mul_f32 v[10:11], v[114:115], v[2:3] op_sel_hi:[1,0]
	v_pk_fma_f32 v[8:9], v[48:49], v[8:9], v[32:33]
	v_pk_fma_f32 v[10:11], v[50:51], v[10:11], v[34:35]
	v_cvt_pk_bf16_f32 v64, v8, v9
	v_cvt_pk_bf16_f32 v65, v10, v11
	global_store_dwordx2 v82, v[64:65], s[98:99] offset:1536
	v_pk_mul_f32 v[12:13], v[128:129], v[4:5] op_sel_hi:[1,0]
	v_pk_mul_f32 v[14:15], v[130:131], v[4:5] op_sel_hi:[1,0]
	v_pk_fma_f32 v[12:13], v[48:49], v[12:13], v[32:33]
	v_pk_fma_f32 v[14:15], v[50:51], v[14:15], v[34:35]
	v_cvt_pk_bf16_f32 v66, v12, v13
	v_cvt_pk_bf16_f32 v67, v14, v15
	global_store_dwordx2 v82, v[66:67], s[98:99] offset:3584
	s_mov_b32 s38, s100
	s_add_i32 s100, s38, s39
	s_cmp_lt_i32 s100, s68
	s_cbranch_scc0 .Lmd0_last_b
; template <bool COMBINE, bool MOD>
; __device__ __forceinline__ void phase_combine_modulate(const Params& p, int lprev, int lnext, const float* xlat, const float* xctx,
;                                                        float* olat, float* octx, int nrows) {
;     ...
;   for (int row0 = gw * R; row0 < nrows; row0 += nw * R) {
;     const bool lat = row0 < T_LAT;
;     const float* xr = lat ? xlat + (size_t)row0 * DM : xctx + (size_t)(row0 - T_LAT) * DM;
;     const int cond = row_cond(row0);
;     float4 v[R][4];
; #pragma unroll
;     for (int r = 0; r < R; ++r)
; #pragma unroll
;       for (int i = 0; i < 4; ++i) v[r][i] = *(const float4*)(xr + (size_t)r * DM + i * 256 + lane * 4);
;     ...
;       const float* sh = p.mada + (size_t)(lnext * 3 + cond) * 6144;
;       const float* sc = sh + 1024;
;       float rstd[R];
; #pragma unroll
;       for (int r = 0; r < R; ++r) {
;         float ss = 0.f;
; #pragma unroll
;         for (int i = 0; i < 4; ++i) ss += v[r][i].x * v[r][i].x + v[r][i].y * v[r][i].y + v[r][i].z * v[r][i].z + v[r][i].w * v[r][i].w;
;         rstd[r] = rsqrtf(wave_sum(ss) * (1.f / 1024.f) + 1e-6f);
;       }
; #pragma unroll
;       for (int i = 0; i < 4; ++i) {
;         const int col = i * 256 + lane * 4;
;         const float4 s4 = *(const float4*)(sc + col);
;         const float4 h4 = *(const float4*)(sh + col);
; #pragma unroll
;         for (int r = 0; r < R; ++r) {
;           u32x2 pk;
;           pk.x = pack2(v[r][i].x * rstd[r] * (1.f + s4.x) + h4.x, v[r][i].y * rstd[r] * (1.f + s4.y) + h4.y);
;           pk.y = pack2(v[r][i].z * rstd[r] * (1.f + s4.z) + h4.z, v[r][i].w * rstd[r] * (1.f + s4.w) + h4.w);
;           *(u32x2*)(p.H + (size_t)(row0 + r) * DM + col) = pk;
;         }
;       }
	s_min_i32 s0, s38, 0x4000
	s_ashr_i32 s0, s0, 13
	s_mul_i32 s0, s0, 0x6000
	s_add_u32 s56, s48, s0
	s_addc_u32 s57, s49, 0
	s_lshl_b32 s0, s38, 11
	s_add_u32 s98, s50, s0
	s_addc_u32 s99, s51, 0
	global_load_dwordx4 v[20:23], v80, s[56:57]
	global_load_dwordx4 v[24:27], v80, s[56:57] offset:1024
	global_load_dwordx4 v[28:31], v80, s[56:57] offset:2048
	global_load_dwordx4 v[32:35], v80, s[56:57] offset:3072
	global_load_dwordx4 v[36:39], v81, s[56:57]
	global_load_dwordx4 v[40:43], v81, s[56:57] offset:1024
	global_load_dwordx4 v[44:47], v81, s[56:57] offset:2048
	global_load_dwordx4 v[48:51], v81, s[56:57] offset:3072
	s_cmpk_lt_i32 s100, 0x4000
	s_cselect_b32 s0, s8, s34
	s_cselect_b32 s1, s9, s35
	s_cselect_b32 s56, 0, 0x4000
	s_sub_i32 s56, s100, s56
	s_lshl_b32 s56, s56, 12
	s_add_u32 s52, s0, s56
	s_addc_u32 s53, s1, 0
	global_load_dwordx4 v[100:103], v80, s[52:53]
	global_load_dwordx4 v[104:107], v80, s[52:53] offset:1024
	global_load_dwordx4 v[108:111], v80, s[52:53] offset:2048
	global_load_dwordx4 v[112:115], v80, s[52:53] offset:3072
	global_load_dwordx4 v[116:119], v81, s[52:53]
	global_load_dwordx4 v[120:123], v81, s[52:53] offset:1024
	global_load_dwordx4 v[124:127], v81, s[52:53] offset:2048
	global_load_dwordx4 v[128:131], v81, s[52:53] offset:3072
	s_waitcnt vmcnt(16)
	v_pk_mul_f32 v[8:9], v[132:133], v[132:133]
	v_pk_fma_f32 v[8:9], v[134:135], v[134:135], v[8:9]
	v_pk_fma_f32 v[8:9], v[136:137], v[136:137], v[8:9]
	v_pk_fma_f32 v[8:9], v[138:139], v[138:139], v[8:9]
	v_pk_fma_f32 v[8:9], v[140:141], v[140:141], v[8:9]
	v_pk_fma_f32 v[8:9], v[142:143], v[142:143], v[8:9]
	v_pk_fma_f32 v[8:9], v[144:145], v[144:145], v[8:9]
	v_pk_fma_f32 v[8:9], v[146:147], v[146:147], v[8:9]
	v_pk_mul_f32 v[10:11], v[148:149], v[148:149]
	v_pk_fma_f32 v[10:11], v[150:151], v[150:151], v[10:11]
	v_pk_fma_f32 v[10:11], v[152:153], v[152:153], v[10:11]
	v_pk_fma_f32 v[10:11], v[154:155], v[154:155], v[10:11]
	v_pk_fma_f32 v[10:11], v[156:157], v[156:157], v[10:11]
	v_pk_fma_f32 v[10:11], v[158:159], v[158:159], v[10:11]
	v_pk_fma_f32 v[10:11], v[160:161], v[160:161], v[10:11]
	v_pk_fma_f32 v[10:11], v[162:163], v[162:163], v[10:11]
	v_add_f32_e32 v6, v8, v9
	v_add_f32_e32 v7, v10, v11
	s_nop 1
	v_add_f32_dpp v6, v6, v6 quad_perm:[1,0,3,2] row_mask:0xf bank_mask:0xf
	v_add_f32_dpp v7, v7, v7 quad_perm:[1,0,3,2] row_mask:0xf bank_mask:0xf
	s_nop 1
	v_add_f32_dpp v6, v6, v6 quad_perm:[2,3,0,1] row_mask:0xf bank_mask:0xf
	v_add_f32_dpp v7, v7, v7 quad_perm:[2,3,0,1] row_mask:0xf bank_mask:0xf
	s_nop 1
	v_add_f32_dpp v6, v6, v6 row_half_mirror row_mask:0xf bank_mask:0xf
	v_add_f32_dpp v7, v7, v7 row_half_mirror row_mask:0xf bank_mask:0xf
	s_nop 1
	v_add_f32_dpp v6, v6, v6 row_mirror row_mask:0xf bank_mask:0xf
	v_add_f32_dpp v7, v7, v7 row_mirror row_mask:0xf bank_mask:0xf
	ds_bpermute_b32 v8, v83, v6
	ds_bpermute_b32 v9, v83, v7
	s_waitcnt lgkmcnt(0)
	v_pk_add_f32 v[6:7], v[6:7], v[8:9]
	ds_bpermute_b32 v8, v84, v6
	ds_bpermute_b32 v9, v84, v7
	s_waitcnt lgkmcnt(0)
	v_pk_add_f32 v[6:7], v[6:7], v[8:9]
	s_nop 0
	v_fma_f32 v6, v6, s101, v224
	v_fma_f32 v7, v7, s101, v224
	v_cmp_gt_f32_e32 vcc, s85, v6
	v_mul_f32_e32 v2, 0x4b800000, v6
	s_nop 1
	v_cndmask_b32_e32 v2, v6, v2, vcc
	v_rsq_f32_e32 v2, v2
	s_nop 0
	v_mul_f32_e32 v6, 0x45800000, v2
	v_cndmask_b32_e32 v2, v2, v6, vcc
	v_cmp_gt_f32_e32 vcc, s85, v7
	v_mul_f32_e32 v4, 0x4b800000, v7
	s_nop 1
	v_cndmask_b32_e32 v4, v7, v4, vcc
	v_rsq_f32_e32 v4, v4
	s_nop 0
	v_mul_f32_e32 v7, 0x45800000, v4
	v_cndmask_b32_e32 v4, v4, v7, vcc
	s_waitcnt vmcnt(8)
	v_pk_add_f32 v[36:37], v[36:37], 1.0 op_sel_hi:[1,0]
	v_pk_add_f32 v[38:39], v[38:39], 1.0 op_sel_hi:[1,0]
	v_pk_mul_f32 v[8:9], v[132:133], v[2:3] op_sel_hi:[1,0]
	v_pk_mul_f32 v[10:11], v[134:135], v[2:3] op_sel_hi:[1,0]
	v_pk_fma_f32 v[8:9], v[36:37], v[8:9], v[20:21]
	v_pk_fma_f32 v[10:11], v[38:39], v[10:11], v[22:23]
	v_cvt_pk_bf16_f32 v52, v8, v9
	v_cvt_pk_bf16_f32 v53, v10, v11
	global_store_dwordx2 v82, v[52:53], s[98:99]
	v_pk_mul_f32 v[12:13], v[148:149], v[4:5] op_sel_hi:[1,0]
	v_pk_mul_f32 v[14:15], v[150:151], v[4:5] op_sel_hi:[1,0]
	v_pk_fma_f32 v[12:13], v[36:37], v[12:13], v[20:21]
	v_pk_fma_f32 v[14:15], v[38:39], v[14:15], v[22:23]
	v_cvt_pk_bf16_f32 v54, v12, v13
	v_cvt_pk_bf16_f32 v55, v14, v15
	global_store_dwordx2 v82, v[54:55], s[98:99] offset:2048
	v_pk_add_f32 v[40:41], v[40:41], 1.0 op_sel_hi:[1,0]
	v_pk_add_f32 v[42:43], v[42:43], 1.0 op_sel_hi:[1,0]
	v_pk_mul_f32 v[8:9], v[136:137], v[2:3] op_sel_hi:[1,0]
	v_pk_mul_f32 v[10:11], v[138:139], v[2:3] op_sel_hi:[1,0]
	v_pk_fma_f32 v[8:9], v[40:41], v[8:9], v[24:25]
	v_pk_fma_f32 v[10:11], v[42:43], v[10:11], v[26:27]
	v_cvt_pk_bf16_f32 v56, v8, v9
	v_cvt_pk_bf16_f32 v57, v10, v11
	global_store_dwordx2 v82, v[56:57], s[98:99] offset:512
	v_pk_mul_f32 v[12:13], v[152:153], v[4:5] op_sel_hi:[1,0]
	v_pk_mul_f32 v[14:15], v[154:155], v[4:5] op_sel_hi:[1,0]
	v_pk_fma_f32 v[12:13], v[40:41], v[12:13], v[24:25]
	v_pk_fma_f32 v[14:15], v[42:43], v[14:15], v[26:27]
	v_cvt_pk_bf16_f32 v58, v12, v13
	v_cvt_pk_bf16_f32 v59, v14, v15
	global_store_dwordx2 v82, v[58:59], s[98:99] offset:2560
	v_pk_add_f32 v[44:45], v[44:45], 1.0 op_sel_hi:[1,0]
	v_pk_add_f32 v[46:47], v[46:47], 1.0 op_sel_hi:[1,0]
	v_pk_mul_f32 v[8:9], v[140:141], v[2:3] op_sel_hi:[1,0]
	v_pk_mul_f32 v[10:11], v[142:143], v[2:3] op_sel_hi:[1,0]
	v_pk_fma_f32 v[8:9], v[44:45], v[8:9], v[28:29]
	v_pk_fma_f32 v[10:11], v[46:47], v[10:11], v[30:31]
	v_cvt_pk_bf16_f32 v60, v8, v9
	v_cvt_pk_bf16_f32 v61, v10, v11
	global_store_dwordx2 v82, v[60:61], s[98:99] offset:1024
	v_pk_mul_f32 v[12:13], v[156:157], v[4:5] op_sel_hi:[1,0]
	v_pk_mul_f32 v[14:15], v[158:159], v[4:5] op_sel_hi:[1,0]
	v_pk_fma_f32 v[12:13], v[44:45], v[12:13], v[28:29]
	v_pk_fma_f32 v[14:15], v[46:47], v[14:15], v[30:31]
	v_cvt_pk_bf16_f32 v62, v12, v13
	v_cvt_pk_bf16_f32 v63, v14, v15
	global_store_dwordx2 v82, v[62:63], s[98:99] offset:3072
	v_pk_add_f32 v[48:49], v[48:49], 1.0 op_sel_hi:[1,0]
	v_pk_add_f32 v[50:51], v[50:51], 1.0 op_sel_hi:[1,0]
	v_pk_mul_f32 v[8:9], v[144:145], v[2:3] op_sel_hi:[1,0]
	v_pk_mul_f32 v[10:11], v[146:147], v[2:3] op_sel_hi:[1,0]
	v_pk_fma_f32 v[8:9], v[48:49], v[8:9], v[32:33]
	v_pk_fma_f32 v[10:11], v[50:51], v[10:11], v[34:35]
	v_cvt_pk_bf16_f32 v64, v8, v9
	v_cvt_pk_bf16_f32 v65, v10, v11
	global_store_dwordx2 v82, v[64:65], s[98:99] offset:1536
	v_pk_mul_f32 v[12:13], v[160:161], v[4:5] op_sel_hi:[1,0]
	v_pk_mul_f32 v[14:15], v[162:163], v[4:5] op_sel_hi:[1,0]
	v_pk_fma_f32 v[12:13], v[48:49], v[12:13], v[32:33]
	v_pk_fma_f32 v[14:15], v[50:51], v[14:15], v[34:35]
	v_cvt_pk_bf16_f32 v66, v12, v13
	v_cvt_pk_bf16_f32 v67, v14, v15
	global_store_dwordx2 v82, v[66:67], s[98:99] offset:3584
	s_mov_b32 s38, s100
	s_branch .Lmd0_loop
; template <bool COMBINE, bool MOD>
; __device__ __forceinline__ void phase_combine_modulate(const Params& p, int lprev, int lnext, const float* xlat, const float* xctx,
;                                                        float* olat, float* octx, int nrows) {
;     ...
;   for (int row0 = gw * R; row0 < nrows; row0 += nw * R) {
;     const bool lat = row0 < T_LAT;
;     const float* xr = lat ? xlat + (size_t)row0 * DM : xctx + (size_t)(row0 - T_LAT) * DM;
;     const int cond = row_cond(row0);
;     float4 v[R][4];
; #pragma unroll
;     for (int r = 0; r < R; ++r)
; #pragma unroll
;       for (int i = 0; i < 4; ++i) v[r][i] = *(const float4*)(xr + (size_t)r * DM + i * 256 + lane * 4);
;     ...
;       const float* sh = p.mada + (size_t)(lnext * 3 + cond) * 6144;
;       const float* sc = sh + 1024;
;       float rstd[R];
; #pragma unroll
;       for (int r = 0; r < R; ++r) {
;         float ss = 0.f;
; #pragma unroll
;         for (int i = 0; i < 4; ++i) ss += v[r][i].x * v[r][i].x + v[r][i].y * v[r][i].y + v[r][i].z * v[r][i].z + v[r][i].w * v[r][i].w;
;         rstd[r] = rsqrtf(wave_sum(ss) * (1.f / 1024.f) + 1e-6f);
;       }
; #pragma unroll
;       for (int i = 0; i < 4; ++i) {
;         const int col = i * 256 + lane * 4;
;         const float4 s4 = *(const float4*)(sc + col);
;         const float4 h4 = *(const float4*)(sh + col);
; #pragma unroll
;         for (int r = 0; r < R; ++r) {
;           u32x2 pk;
;           pk.x = pack2(v[r][i].x * rstd[r] * (1.f + s4.x) + h4.x, v[r][i].y * rstd[r] * (1.f + s4.y) + h4.y);
;           pk.y = pack2(v[r][i].z * rstd[r] * (1.f + s4.z) + h4.z, v[r][i].w * rstd[r] * (1.f + s4.w) + h4.w);
;           *(u32x2*)(p.H + (size_t)(row0 + r) * DM + col) = pk;
;         }
;       }
.Lmd0_last_a:
	s_min_i32 s0, s38, 0x4000
	s_ashr_i32 s0, s0, 13
	s_mul_i32 s0, s0, 0x6000
	s_add_u32 s56, s48, s0
	s_addc_u32 s57, s49, 0
	s_lshl_b32 s0, s38, 11
	s_add_u32 s98, s50, s0
	s_addc_u32 s99, s51, 0
	global_load_dwordx4 v[20:23], v80, s[56:57]
	global_load_dwordx4 v[24:27], v80, s[56:57] offset:1024
	global_load_dwordx4 v[28:31], v80, s[56:57] offset:2048
	global_load_dwordx4 v[32:35], v80, s[56:57] offset:3072
	global_load_dwordx4 v[36:39], v81, s[56:57]
	global_load_dwordx4 v[40:43], v81, s[56:57] offset:1024
	global_load_dwordx4 v[44:47], v81, s[56:57] offset:2048
	global_load_dwordx4 v[48:51], v81, s[56:57] offset:3072
	s_waitcnt vmcnt(8)
	v_pk_mul_f32 v[8:9], v[100:101], v[100:101]
	v_pk_fma_f32 v[8:9], v[102:103], v[102:103], v[8:9]
	v_pk_fma_f32 v[8:9], v[104:105], v[104:105], v[8:9]
	v_pk_fma_f32 v[8:9], v[106:107], v[106:107], v[8:9]
	v_pk_fma_f32 v[8:9], v[108:109], v[108:109], v[8:9]
	v_pk_fma_f32 v[8:9], v[110:111], v[110:111], v[8:9]
	v_pk_fma_f32 v[8:9], v[112:113], v[112:113], v[8:9]
	v_pk_fma_f32 v[8:9], v[114:115], v[114:115], v[8:9]
	v_pk_mul_f32 v[10:11], v[116:117], v[116:117]
	v_pk_fma_f32 v[10:11], v[118:119], v[118:119], v[10:11]
	v_pk_fma_f32 v[10:11], v[120:121], v[120:121], v[10:11]
	v_pk_fma_f32 v[10:11], v[122:123], v[122:123], v[10:11]
	v_pk_fma_f32 v[10:11], v[124:125], v[124:125], v[10:11]
	v_pk_fma_f32 v[10:11], v[126:127], v[126:127], v[10:11]
	v_pk_fma_f32 v[10:11], v[128:129], v[128:129], v[10:11]
	v_pk_fma_f32 v[10:11], v[130:131], v[130:131], v[10:11]
	v_add_f32_e32 v6, v8, v9
	v_add_f32_e32 v7, v10, v11
	s_nop 1
	v_add_f32_dpp v6, v6, v6 quad_perm:[1,0,3,2] row_mask:0xf bank_mask:0xf
	v_add_f32_dpp v7, v7, v7 quad_perm:[1,0,3,2] row_mask:0xf bank_mask:0xf
	s_nop 1
	v_add_f32_dpp v6, v6, v6 quad_perm:[2,3,0,1] row_mask:0xf bank_mask:0xf
	v_add_f32_dpp v7, v7, v7 quad_perm:[2,3,0,1] row_mask:0xf bank_mask:0xf
	s_nop 1
	v_add_f32_dpp v6, v6, v6 row_half_mirror row_mask:0xf bank_mask:0xf
	v_add_f32_dpp v7, v7, v7 row_half_mirror row_mask:0xf bank_mask:0xf
	s_nop 1
	v_add_f32_dpp v6, v6, v6 row_mirror row_mask:0xf bank_mask:0xf
	v_add_f32_dpp v7, v7, v7 row_mirror row_mask:0xf bank_mask:0xf
	ds_bpermute_b32 v8, v83, v6
	ds_bpermute_b32 v9, v83, v7
	s_waitcnt lgkmcnt(0)
	v_pk_add_f32 v[6:7], v[6:7], v[8:9]
	ds_bpermute_b32 v8, v84, v6
	ds_bpermute_b32 v9, v84, v7
	s_waitcnt lgkmcnt(0)
	v_pk_add_f32 v[6:7], v[6:7], v[8:9]
	s_nop 0
	v_fma_f32 v6, v6, s101, v224
	v_fma_f32 v7, v7, s101, v224
	v_cmp_gt_f32_e32 vcc, s85, v6
	v_mul_f32_e32 v2, 0x4b800000, v6
	s_nop 1
	v_cndmask_b32_e32 v2, v6, v2, vcc
	v_rsq_f32_e32 v2, v2
	s_nop 0
	v_mul_f32_e32 v6, 0x45800000, v2
	v_cndmask_b32_e32 v2, v2, v6, vcc
	v_cmp_gt_f32_e32 vcc, s85, v7
	v_mul_f32_e32 v4, 0x4b800000, v7
	s_nop 1
	v_cndmask_b32_e32 v4, v7, v4, vcc
	v_rsq_f32_e32 v4, v4
	s_nop 0
	v_mul_f32_e32 v7, 0x45800000, v4
	v_cndmask_b32_e32 v4, v4, v7, vcc
	s_waitcnt vmcnt(0)
	v_pk_add_f32 v[36:37], v[36:37], 1.0 op_sel_hi:[1,0]
	v_pk_add_f32 v[38:39], v[38:39], 1.0 op_sel_hi:[1,0]
	v_pk_mul_f32 v[8:9], v[100:101], v[2:3] op_sel_hi:[1,0]
	v_pk_mul_f32 v[10:11], v[102:103], v[2:3] op_sel_hi:[1,0]
	v_pk_fma_f32 v[8:9], v[36:37], v[8:9], v[20:21]
	v_pk_fma_f32 v[10:11], v[38:39], v[10:11], v[22:23]
	v_cvt_pk_bf16_f32 v52, v8, v9
	v_cvt_pk_bf16_f32 v53, v10, v11
	global_store_dwordx2 v82, v[52:53], s[98:99]
	v_pk_mul_f32 v[12:13], v[116:117], v[4:5] op_sel_hi:[1,0]
	v_pk_mul_f32 v[14:15], v[118:119], v[4:5] op_sel_hi:[1,0]
	v_pk_fma_f32 v[12:13], v[36:37], v[12:13], v[20:21]
	v_pk_fma_f32 v[14:15], v[38:39], v[14:15], v[22:23]
	v_cvt_pk_bf16_f32 v54, v12, v13
	v_cvt_pk_bf16_f32 v55, v14, v15
	global_store_dwordx2 v82, v[54:55], s[98:99] offset:2048
	v_pk_add_f32 v[40:41], v[40:41], 1.0 op_sel_hi:[1,0]
	v_pk_add_f32 v[42:43], v[42:43], 1.0 op_sel_hi:[1,0]
	v_pk_mul_f32 v[8:9], v[104:105], v[2:3] op_sel_hi:[1,0]
	v_pk_mul_f32 v[10:11], v[106:107], v[2:3] op_sel_hi:[1,0]
	v_pk_fma_f32 v[8:9], v[40:41], v[8:9], v[24:25]
	v_pk_fma_f32 v[10:11], v[42:43], v[10:11], v[26:27]
	v_cvt_pk_bf16_f32 v56, v8, v9
	v_cvt_pk_bf16_f32 v57, v10, v11
	global_store_dwordx2 v82, v[56:57], s[98:99] offset:512
	v_pk_mul_f32 v[12:13], v[120:121], v[4:5] op_sel_hi:[1,0]
	v_pk_mul_f32 v[14:15], v[122:123], v[4:5] op_sel_hi:[1,0]
	v_pk_fma_f32 v[12:13], v[40:41], v[12:13], v[24:25]
	v_pk_fma_f32 v[14:15], v[42:43], v[14:15], v[26:27]
	v_cvt_pk_bf16_f32 v58, v12, v13
	v_cvt_pk_bf16_f32 v59, v14, v15
	global_store_dwordx2 v82, v[58:59], s[98:99] offset:2560
	v_pk_add_f32 v[44:45], v[44:45], 1.0 op_sel_hi:[1,0]
	v_pk_add_f32 v[46:47], v[46:47], 1.0 op_sel_hi:[1,0]
	v_pk_mul_f32 v[8:9], v[108:109], v[2:3] op_sel_hi:[1,0]
	v_pk_mul_f32 v[10:11], v[110:111], v[2:3] op_sel_hi:[1,0]
	v_pk_fma_f32 v[8:9], v[44:45], v[8:9], v[28:29]
	v_pk_fma_f32 v[10:11], v[46:47], v[10:11], v[30:31]
	v_cvt_pk_bf16_f32 v60, v8, v9
	v_cvt_pk_bf16_f32 v61, v10, v11
	global_store_dwordx2 v82, v[60:61], s[98:99] offset:1024
	v_pk_mul_f32 v[12:13], v[124:125], v[4:5] op_sel_hi:[1,0]
	v_pk_mul_f32 v[14:15], v[126:127], v[4:5] op_sel_hi:[1,0]
	v_pk_fma_f32 v[12:13], v[44:45], v[12:13], v[28:29]
	v_pk_fma_f32 v[14:15], v[46:47], v[14:15], v[30:31]
	v_cvt_pk_bf16_f32 v62, v12, v13
	v_cvt_pk_bf16_f32 v63, v14, v15
	global_store_dwordx2 v82, v[62:63], s[98:99] offset:3072
	v_pk_add_f32 v[48:49], v[48:49], 1.0 op_sel_hi:[1,0]
	v_pk_add_f32 v[50:51], v[50:51], 1.0 op_sel_hi:[1,0]
	v_pk_mul_f32 v[8:9], v[112:113], v[2:3] op_sel_hi:[1,0]
	v_pk_mul_f32 v[10:11], v[114:115], v[2:3] op_sel_hi:[1,0]
	v_pk_fma_f32 v[8:9], v[48:49], v[8:9], v[32:33]
	v_pk_fma_f32 v[10:11], v[50:51], v[10:11], v[34:35]
	v_cvt_pk_bf16_f32 v64, v8, v9
	v_cvt_pk_bf16_f32 v65, v10, v11
	global_store_dwordx2 v82, v[64:65], s[98:99] offset:1536
	v_pk_mul_f32 v[12:13], v[128:129], v[4:5] op_sel_hi:[1,0]
	v_pk_mul_f32 v[14:15], v[130:131], v[4:5] op_sel_hi:[1,0]
	v_pk_fma_f32 v[12:13], v[48:49], v[12:13], v[32:33]
	v_pk_fma_f32 v[14:15], v[50:51], v[14:15], v[34:35]
	v_cvt_pk_bf16_f32 v66, v12, v13
	v_cvt_pk_bf16_f32 v67, v14, v15
	global_store_dwordx2 v82, v[66:67], s[98:99] offset:3584
	s_branch .Lmd0_done
; template <bool COMBINE, bool MOD>
; __device__ __forceinline__ void phase_combine_modulate(const Params& p, int lprev, int lnext, const float* xlat, const float* xctx,
;                                                        float* olat, float* octx, int nrows) {
;     ...
;   for (int row0 = gw * R; row0 < nrows; row0 += nw * R) {
;     const bool lat = row0 < T_LAT;
;     const float* xr = lat ? xlat + (size_t)row0 * DM : xctx + (size_t)(row0 - T_LAT) * DM;
;     const int cond = row_cond(row0);
;     float4 v[R][4];
; #pragma unroll
;     for (int r = 0; r < R; ++r)
; #pragma unroll
;       for (int i = 0; i < 4; ++i) v[r][i] = *(const float4*)(xr + (size_t)r * DM + i * 256 + lane * 4);
;     ...
;       const float* sh = p.mada + (size_t)(lnext * 3 + cond) * 6144;
;       const float* sc = sh + 1024;
;       float rstd[R];
; #pragma unroll
;       for (int r = 0; r < R; ++r) {
;         float ss = 0.f;
; #pragma unroll
;         for (int i = 0; i < 4; ++i) ss += v[r][i].x * v[r][i].x + v[r][i].y * v[r][i].y + v[r][i].z * v[r][i].z + v[r][i].w * v[r][i].w;
;         rstd[r] = rsqrtf(wave_sum(ss) * (1.f / 1024.f) + 1e-6f);
;       }
; #pragma unroll
;       for (int i = 0; i < 4; ++i) {
;         const int col = i * 256 + lane * 4;
;         const float4 s4 = *(const float4*)(sc + col);
;         const float4 h4 = *(const float4*)(sh + col);
; #pragma unroll
;         for (int r = 0; r < R; ++r) {
;           u32x2 pk;
;           pk.x = pack2(v[r][i].x * rstd[r] * (1.f + s4.x) + h4.x, v[r][i].y * rstd[r] * (1.f + s4.y) + h4.y);
;           pk.y = pack2(v[r][i].z * rstd[r] * (1.f + s4.z) + h4.z, v[r][i].w * rstd[r] * (1.f + s4.w) + h4.w);
;           *(u32x2*)(p.H + (size_t)(row0 + r) * DM + col) = pk;
;         }
;       }
.Lmd0_last_b:
	s_min_i32 s0, s38, 0x4000
	s_ashr_i32 s0, s0, 13
	s_mul_i32 s0, s0, 0x6000
	s_add_u32 s56, s48, s0
	s_addc_u32 s57, s49, 0
	s_lshl_b32 s0, s38, 11
	s_add_u32 s98, s50, s0
	s_addc_u32 s99, s51, 0
	global_load_dwordx4 v[20:23], v80, s[56:57]
	global_load_dwordx4 v[24:27], v80, s[56:57] offset:1024
	global_load_dwordx4 v[28:31], v80, s[56:57] offset:2048
	global_load_dwordx4 v[32:35], v80, s[56:57] offset:3072
	global_load_dwordx4 v[36:39], v81, s[56:57]
	global_load_dwordx4 v[40:43], v81, s[56:57] offset:1024
	global_load_dwordx4 v[44:47], v81, s[56:57] offset:2048
	global_load_dwordx4 v[48:51], v81, s[56:57] offset:3072
	s_waitcnt vmcnt(8)
	v_pk_mul_f32 v[8:9], v[132:133], v[132:133]
	v_pk_fma_f32 v[8:9], v[134:135], v[134:135], v[8:9]
	v_pk_fma_f32 v[8:9], v[136:137], v[136:137], v[8:9]
	v_pk_fma_f32 v[8:9], v[138:139], v[138:139], v[8:9]
	v_pk_fma_f32 v[8:9], v[140:141], v[140:141], v[8:9]
	v_pk_fma_f32 v[8:9], v[142:143], v[142:143], v[8:9]
	v_pk_fma_f32 v[8:9], v[144:145], v[144:145], v[8:9]
	v_pk_fma_f32 v[8:9], v[146:147], v[146:147], v[8:9]
	v_pk_mul_f32 v[10:11], v[148:149], v[148:149]
	v_pk_fma_f32 v[10:11], v[150:151], v[150:151], v[10:11]
	v_pk_fma_f32 v[10:11], v[152:153], v[152:153], v[10:11]
	v_pk_fma_f32 v[10:11], v[154:155], v[154:155], v[10:11]
	v_pk_fma_f32 v[10:11], v[156:157], v[156:157], v[10:11]
	v_pk_fma_f32 v[10:11], v[158:159], v[158:159], v[10:11]
	v_pk_fma_f32 v[10:11], v[160:161], v[160:161], v[10:11]
	v_pk_fma_f32 v[10:11], v[162:163], v[162:163], v[10:11]
	v_add_f32_e32 v6, v8, v9
	v_add_f32_e32 v7, v10, v11
	s_nop 1
	v_add_f32_dpp v6, v6, v6 quad_perm:[1,0,3,2] row_mask:0xf bank_mask:0xf
	v_add_f32_dpp v7, v7, v7 quad_perm:[1,0,3,2] row_mask:0xf bank_mask:0xf
	s_nop 1
	v_add_f32_dpp v6, v6, v6 quad_perm:[2,3,0,1] row_mask:0xf bank_mask:0xf
	v_add_f32_dpp v7, v7, v7 quad_perm:[2,3,0,1] row_mask:0xf bank_mask:0xf
	s_nop 1
	v_add_f32_dpp v6, v6, v6 row_half_mirror row_mask:0xf bank_mask:0xf
	v_add_f32_dpp v7, v7, v7 row_half_mirror row_mask:0xf bank_mask:0xf
	s_nop 1
	v_add_f32_dpp v6, v6, v6 row_mirror row_mask:0xf bank_mask:0xf
	v_add_f32_dpp v7, v7, v7 row_mirror row_mask:0xf bank_mask:0xf
	ds_bpermute_b32 v8, v83, v6
	ds_bpermute_b32 v9, v83, v7
	s_waitcnt lgkmcnt(0)
	v_pk_add_f32 v[6:7], v[6:7], v[8:9]
	ds_bpermute_b32 v8, v84, v6
	ds_bpermute_b32 v9, v84, v7
	s_waitcnt lgkmcnt(0)
	v_pk_add_f32 v[6:7], v[6:7], v[8:9]
	s_nop 0
	v_fma_f32 v6, v6, s101, v224
	v_fma_f32 v7, v7, s101, v224
	v_cmp_gt_f32_e32 vcc, s85, v6
	v_mul_f32_e32 v2, 0x4b800000, v6
	s_nop 1
	v_cndmask_b32_e32 v2, v6, v2, vcc
	v_rsq_f32_e32 v2, v2
	s_nop 0
	v_mul_f32_e32 v6, 0x45800000, v2
	v_cndmask_b32_e32 v2, v2, v6, vcc
	v_cmp_gt_f32_e32 vcc, s85, v7
	v_mul_f32_e32 v4, 0x4b800000, v7
	s_nop 1
	v_cndmask_b32_e32 v4, v7, v4, vcc
	v_rsq_f32_e32 v4, v4
	s_nop 0
	v_mul_f32_e32 v7, 0x45800000, v4
	v_cndmask_b32_e32 v4, v4, v7, vcc
	s_waitcnt vmcnt(0)
	v_pk_add_f32 v[36:37], v[36:37], 1.0 op_sel_hi:[1,0]
	v_pk_add_f32 v[38:39], v[38:39], 1.0 op_sel_hi:[1,0]
	v_pk_mul_f32 v[8:9], v[132:133], v[2:3] op_sel_hi:[1,0]
	v_pk_mul_f32 v[10:11], v[134:135], v[2:3] op_sel_hi:[1,0]
	v_pk_fma_f32 v[8:9], v[36:37], v[8:9], v[20:21]
	v_pk_fma_f32 v[10:11], v[38:39], v[10:11], v[22:23]
	v_cvt_pk_bf16_f32 v52, v8, v9
	v_cvt_pk_bf16_f32 v53, v10, v11
	global_store_dwordx2 v82, v[52:53], s[98:99]
	v_pk_mul_f32 v[12:13], v[148:149], v[4:5] op_sel_hi:[1,0]
	v_pk_mul_f32 v[14:15], v[150:151], v[4:5] op_sel_hi:[1,0]
	v_pk_fma_f32 v[12:13], v[36:37], v[12:13], v[20:21]
	v_pk_fma_f32 v[14:15], v[38:39], v[14:15], v[22:23]
	v_cvt_pk_bf16_f32 v54, v12, v13
	v_cvt_pk_bf16_f32 v55, v14, v15
	global_store_dwordx2 v82, v[54:55], s[98:99] offset:2048
	v_pk_add_f32 v[40:41], v[40:41], 1.0 op_sel_hi:[1,0]
	v_pk_add_f32 v[42:43], v[42:43], 1.0 op_sel_hi:[1,0]
	v_pk_mul_f32 v[8:9], v[136:137], v[2:3] op_sel_hi:[1,0]
	v_pk_mul_f32 v[10:11], v[138:139], v[2:3] op_sel_hi:[1,0]
	v_pk_fma_f32 v[8:9], v[40:41], v[8:9], v[24:25]
	v_pk_fma_f32 v[10:11], v[42:43], v[10:11], v[26:27]
	v_cvt_pk_bf16_f32 v56, v8, v9
	v_cvt_pk_bf16_f32 v57, v10, v11
	global_store_dwordx2 v82, v[56:57], s[98:99] offset:512
	v_pk_mul_f32 v[12:13], v[152:153], v[4:5] op_sel_hi:[1,0]
	v_pk_mul_f32 v[14:15], v[154:155], v[4:5] op_sel_hi:[1,0]
	v_pk_fma_f32 v[12:13], v[40:41], v[12:13], v[24:25]
	v_pk_fma_f32 v[14:15], v[42:43], v[14:15], v[26:27]
	v_cvt_pk_bf16_f32 v58, v12, v13
	v_cvt_pk_bf16_f32 v59, v14, v15
	global_store_dwordx2 v82, v[58:59], s[98:99] offset:2560
	v_pk_add_f32 v[44:45], v[44:45], 1.0 op_sel_hi:[1,0]
	v_pk_add_f32 v[46:47], v[46:47], 1.0 op_sel_hi:[1,0]
	v_pk_mul_f32 v[8:9], v[140:141], v[2:3] op_sel_hi:[1,0]
	v_pk_mul_f32 v[10:11], v[142:143], v[2:3] op_sel_hi:[1,0]
	v_pk_fma_f32 v[8:9], v[44:45], v[8:9], v[28:29]
	v_pk_fma_f32 v[10:11], v[46:47], v[10:11], v[30:31]
	v_cvt_pk_bf16_f32 v60, v8, v9
	v_cvt_pk_bf16_f32 v61, v10, v11
	global_store_dwordx2 v82, v[60:61], s[98:99] offset:1024
	v_pk_mul_f32 v[12:13], v[156:157], v[4:5] op_sel_hi:[1,0]
	v_pk_mul_f32 v[14:15], v[158:159], v[4:5] op_sel_hi:[1,0]
	v_pk_fma_f32 v[12:13], v[44:45], v[12:13], v[28:29]
	v_pk_fma_f32 v[14:15], v[46:47], v[14:15], v[30:31]
	v_cvt_pk_bf16_f32 v62, v12, v13
	v_cvt_pk_bf16_f32 v63, v14, v15
	global_store_dwordx2 v82, v[62:63], s[98:99] offset:3072
	v_pk_add_f32 v[48:49], v[48:49], 1.0 op_sel_hi:[1,0]
	v_pk_add_f32 v[50:51], v[50:51], 1.0 op_sel_hi:[1,0]
	v_pk_mul_f32 v[8:9], v[144:145], v[2:3] op_sel_hi:[1,0]
	v_pk_mul_f32 v[10:11], v[146:147], v[2:3] op_sel_hi:[1,0]
	v_pk_fma_f32 v[8:9], v[48:49], v[8:9], v[32:33]
	v_pk_fma_f32 v[10:11], v[50:51], v[10:11], v[34:35]
	v_cvt_pk_bf16_f32 v64, v8, v9
	v_cvt_pk_bf16_f32 v65, v10, v11
	global_store_dwordx2 v82, v[64:65], s[98:99] offset:1536
	v_pk_mul_f32 v[12:13], v[160:161], v[4:5] op_sel_hi:[1,0]
	v_pk_mul_f32 v[14:15], v[162:163], v[4:5] op_sel_hi:[1,0]
	v_pk_fma_f32 v[12:13], v[48:49], v[12:13], v[32:33]
	v_pk_fma_f32 v[14:15], v[50:51], v[14:15], v[34:35]
	v_cvt_pk_bf16_f32 v66, v12, v13
	v_cvt_pk_bf16_f32 v67, v14, v15
	global_store_dwordx2 v82, v[66:67], s[98:99] offset:3584

; __device__ __forceinline__ int tid_() { int t = threadIdx.x; asm volatile("" : "+v"(t)); return t; }
; __device__ __forceinline__ int bid_() { int b = blockIdx.x; asm volatile("" : "+s"(b)); return b; }
; template <bool COMBINE, bool MOD>
; __device__ __forceinline__ void phase_combine_modulate(const Params& p, int lprev, int lnext, const float* xlat, const float* xctx,
;                                                        float* olat, float* octx, int nrows) {
;     ...
;   const int t = tid_(), lane = t & 63, wid = t >> 6;
;   const int gw = bid_() * 4 + wid, nw = gridDim.x * 4;
;   for (int row0 = gw * R; row0 < nrows; row0 += nw * R) {
;     const bool lat = row0 < T_LAT;
;     const float* xr = lat ? xlat + (size_t)row0 * DM : xctx + (size_t)(row0 - T_LAT) * DM;
;     const int cond = row_cond(row0);
;     float4 v[R][4];
; #pragma unroll
;     for (int r = 0; r < R; ++r)
; #pragma unroll
;       for (int i = 0; i < 4; ++i) v[r][i] = *(const float4*)(xr + (size_t)r * DM + i * 256 + lane * 4);
;     if (COMBINE) {
;       const int b = row_batch(row0);
;       const int myinv = p.INV[(size_t)row0 * 16 + (lane & 31)];
;       const float* g2 = p.mada + (size_t)(lprev * 3 + cond) * 6144 + 5 * 1024;
;       float* orow = lat ? olat + (size_t)row0 * DM : octx + (size_t)(row0 - T_LAT) * DM;
; #pragma unroll
;       for (int r = 0; r < R; ++r) {
;         float4 s[4];
; #pragma unroll
;         for (int i = 0; i < 4; ++i) s[i] = make_float4(0.f, 0.f, 0.f, 0.f);
;         unsigned mask = (unsigned)((__ballot(myinv >= 0) >> (16 * r)) & 0xFFFFull);
;         while (mask) {
;           const int e0 = __builtin_ctz(mask);
;           mask &= mask - 1;
;           const bool two = mask != 0u;
;           const int e1 = two ? __builtin_ctz(mask) : e0;
;           mask &= mask - 1;
;           const int s0 = __shfl(myinv, 16 * r + e0), s1 = __shfl(myinv, 16 * r + e1);
;           const size_t y0 = lat ? (size_t)(b * 16 + e0) * 1024 + s0 : (size_t)32768 + (size_t)(b * 16 + e0) * 128 + s0;
;           const size_t y1 = lat ? (size_t)(b * 16 + e1) * 1024 + s1 : (size_t)32768 + (size_t)(b * 16 + e1) * 128 + s1;
;           u32x2 a0[4], a1[4];
; #pragma unroll
;           for (int i = 0; i < 4; ++i) { a0[i] = *(const u32x2*)(p.YB + y0 * 1024 + lane * 4 + i * 256); a1[i] = *(const u32x2*)(p.YB + y1 * 1024 + lane * 4 + i * 256); }
.LBB0_156:
	s_and_b64 vcc, exec, s[0:1]
	s_cbranch_vccz .LBB0_188
	s_mov_b64 s[42:43], s[64:65]
	v_mov_b32_e32 v0, v187
	s_mov_b32 s0, s2
	v_ashrrev_i32_e32 v2, 5, v0
	v_and_b32_e32 v2, -2, v2
	s_nop 0
	v_lshl_add_u32 v34, s0, 3, v2
	v_cmp_gt_i32_e32 vcc, s68, v34
	s_and_saveexec_b64 s[44:45], vcc
	s_cbranch_execz .LBB0_187
	s_load_dwordx2 s[8:9], s[64:65], 0xa8
	s_load_dwordx2 s[34:35], s[64:65], 0x110
	s_load_dwordx2 s[38:39], s[64:65], 0x1a0
	s_load_dwordx2 s[40:41], s[64:65], 0xb8
	s_load_dwordx2 s[48:49], s[64:65], 0x1a8
	s_load_dwordx2 s[50:51], s[64:65], 0x118
	v_readfirstlane_b32 s52, v34
	v_readlane_b32 s53, v254, 54
	s_mov_b32 s18, 0x3a800000
	v_and_b32_e32 v0, 63, v187
	v_lshlrev_b32_e32 v188, 4, v0
	v_or_b32_e32 v189, 0x1000, v188
	v_lshlrev_b32_e32 v190, 3, v0
	v_xor_b32_e32 v208, 16, v0
	v_xor_b32_e32 v209, 32, v0
	v_lshlrev_b32_e32 v208, 2, v208
	v_lshlrev_b32_e32 v209, 2, v209
	v_and_b32_e32 v210, 31, v0
	v_lshlrev_b32_e32 v210, 2, v210
	v_and_b32_e32 v246, 15, v0
	s_waitcnt lgkmcnt(0)
	s_cmpk_lt_i32 s52, 0x4000
	s_cselect_b32 s0, s8, s34
	s_cselect_b32 s1, s9, s35
	s_cselect_b32 s98, 0, 0x4000
	s_sub_i32 s98, s52, s98
	s_lshl_b32 s98, s98, 12
	s_add_u32 s98, s0, s98
	s_addc_u32 s99, s1, 0
	global_load_dwordx4 v[100:103], v188, s[98:99]
	global_load_dwordx4 v[104:107], v188, s[98:99] offset:1024
	global_load_dwordx4 v[108:111], v188, s[98:99] offset:2048
	global_load_dwordx4 v[112:115], v188, s[98:99] offset:3072
	global_load_dwordx4 v[116:119], v189, s[98:99]
	global_load_dwordx4 v[120:123], v189, s[98:99] offset:1024
	global_load_dwordx4 v[124:127], v189, s[98:99] offset:2048
	global_load_dwordx4 v[128:131], v189, s[98:99] offset:3072
	s_lshl_b32 s0, s52, 6
	s_add_u32 s0, s38, s0
	s_addc_u32 s1, s39, 0
	global_load_dword v199, v210, s[0:1]
.Lcb1_loop:
	s_add_i32 s94, s52, s53
	s_cmp_lt_i32 s94, s68
	s_cselect_b32 s32, s94, s52
	s_min_i32 s0, s52, 0x4000
	s_ashr_i32 s0, s0, 13
	s_mul_i32 s0, s0, 0x6000
	s_add_u32 s56, s40, s0
	s_addc_u32 s57, s41, 0
	s_add_u32 s88, s56, 0x12000
	s_addc_u32 s89, s57, 0
	s_lshl_b32 s0, s52, 11
	s_add_u32 s46, s50, s0
	s_addc_u32 s47, s51, 0
	s_add_u32 s56, s56, 0x5000
	s_addc_u32 s57, s57, 0
	global_load_dwordx4 v[34:37], v188, s[56:57]
	global_load_dwordx4 v[38:41], v188, s[56:57] offset:1024
	global_load_dwordx4 v[42:45], v188, s[56:57] offset:2048
	global_load_dwordx4 v[46:49], v188, s[56:57] offset:3072
	global_load_dwordx4 v[50:53], v188, s[88:89]
	global_load_dwordx4 v[54:57], v188, s[88:89] offset:1024
	global_load_dwordx4 v[58:61], v188, s[88:89] offset:2048
	global_load_dwordx4 v[62:65], v188, s[88:89] offset:3072
	global_load_dwordx4 v[66:69], v189, s[88:89]
	global_load_dwordx4 v[70:73], v189, s[88:89] offset:1024
	global_load_dwordx4 v[74:77], v189, s[88:89] offset:2048
	global_load_dwordx4 v[78:81], v189, s[88:89] offset:3072
	s_cmpk_lt_i32 s32, 0x4000
	s_cselect_b32 s0, s8, s34
	s_cselect_b32 s1, s9, s35
	s_cselect_b32 s100, 0, 0x4000
	s_sub_i32 s100, s32, s100
	s_lshl_b32 s100, s100, 12
	s_add_u32 s100, s0, s100
	s_addc_u32 s101, s1, 0
	global_load_dwordx4 v[132:135], v188, s[100:101]
	global_load_dwordx4 v[136:139], v188, s[100:101] offset:1024
	global_load_dwordx4 v[140:143], v188, s[100:101] offset:2048
	global_load_dwordx4 v[144:147], v188, s[100:101] offset:3072
	global_load_dwordx4 v[148:151], v189, s[100:101]
	global_load_dwordx4 v[152:155], v189, s[100:101] offset:1024
	global_load_dwordx4 v[156:159], v189, s[100:101] offset:2048
	global_load_dwordx4 v[160:163], v189, s[100:101] offset:3072
	s_lshl_b32 s0, s32, 6
	s_add_u32 s0, s38, s0
	s_addc_u32 s1, s39, 0
	global_load_dword v211, v210, s[0:1]
	s_cmpk_lt_i32 s52, 0x4000
	s_cselect_b32 s1, 10, 7
	s_cselect_b32 s0, 13, 8
	s_cselect_b32 s37, 0, 0x4000
	s_cselect_b32 s71, 0, 0x8000
	s_sub_i32 s37, s52, s37
	s_lshr_b32 s37, s37, s0
	s_lshl_b32 s37, s37, 4
	s_lshl_b32 s37, s37, s1
	s_add_i32 s37, s37, s71
	v_mov_b32_e32 v2, 0
	v_mov_b32_e32 v3, 0
	v_mov_b32_e32 v4, 0
	v_mov_b32_e32 v5, 0
	v_mov_b32_e32 v6, 0
	v_mov_b32_e32 v7, 0
	v_mov_b32_e32 v8, 0
	v_mov_b32_e32 v9, 0
	v_mov_b32_e32 v10, 0
	v_mov_b32_e32 v11, 0
	v_mov_b32_e32 v12, 0
	v_mov_b32_e32 v13, 0
	v_mov_b32_e32 v14, 0
	v_mov_b32_e32 v15, 0
	v_mov_b32_e32 v16, 0
	v_mov_b32_e32 v17, 0
	v_mov_b32_e32 v18, 0
	v_mov_b32_e32 v19, 0
	v_mov_b32_e32 v20, 0
	v_mov_b32_e32 v21, 0
	v_mov_b32_e32 v22, 0
	v_mov_b32_e32 v23, 0
	v_mov_b32_e32 v24, 0
	v_mov_b32_e32 v25, 0
	v_mov_b32_e32 v26, 0
	v_mov_b32_e32 v27, 0
	v_mov_b32_e32 v28, 0
	v_mov_b32_e32 v29, 0
	v_mov_b32_e32 v30, 0
	v_mov_b32_e32 v31, 0
	v_mov_b32_e32 v32, 0
	v_mov_b32_e32 v33, 0
	s_waitcnt vmcnt(21)
	v_cmp_lt_i32_e32 vcc, -1, v199
	v_lshlrev_b32_e32 v184, s1, v246
	v_add3_u32 v184, v184, s37, v199
	s_and_b32 s59, vcc_lo, 0xffff
	s_lshr_b32 s60, vcc_lo, 16
	s_mov_b32 s71, 0
	s_mov_b32 s32, 0
	s_cmp_eq_u32 s59, 0
	s_cbranch_scc1 .Lcb1_iss0
	s_ff1_i32_b32 s0, s59
	s_bitset0_b32 s59, s0
	v_readlane_b32 s1, v184, s0
	s_lshl_b32 s1, s1, 11
	s_add_u32 s0, s48, s1
	s_addc_u32 s1, s49, 0
	global_load_dwordx2 v[164:165], v190, s[0:1]
	global_load_dwordx2 v[166:167], v190, s[0:1] offset:512
	global_load_dwordx2 v[168:169], v190, s[0:1] offset:1024
	global_load_dwordx2 v[170:171], v190, s[0:1] offset:1536
	s_add_i32 s71, s71, 1
	s_cmp_eq_u32 s59, 0
	s_cbranch_scc1 .Lcb1_iss0
	s_ff1_i32_b32 s0, s59
	s_bitset0_b32 s59, s0
	v_readlane_b32 s1, v184, s0
	s_lshl_b32 s1, s1, 11
	s_add_u32 s0, s48, s1
	s_addc_u32 s1, s49, 0
	global_load_dwordx2 v[172:173], v190, s[0:1]
	global_load_dwordx2 v[174:175], v190, s[0:1] offset:512
	global_load_dwordx2 v[176:177], v190, s[0:1] offset:1024
	global_load_dwordx2 v[178:179], v190, s[0:1] offset:1536
	s_add_i32 s71, s71, 1
	s_cmp_eq_u32 s59, 0
	s_cbranch_scc1 .Lcb1_iss0
	s_ff1_i32_b32 s0, s59
	s_bitset0_b32 s59, s0
	v_readlane_b32 s1, v184, s0
	s_lshl_b32 s1, s1, 11
	s_add_u32 s0, s48, s1
	s_addc_u32 s1, s49, 0
	global_load_dwordx2 v[82:83], v190, s[0:1]
	global_load_dwordx2 v[84:85], v190, s[0:1] offset:512
	global_load_dwordx2 v[86:87], v190, s[0:1] offset:1024
	global_load_dwordx2 v[88:89], v190, s[0:1] offset:1536
	s_add_i32 s71, s71, 1
	s_cmp_eq_u32 s59, 0
	s_cbranch_scc1 .Lcb1_iss0
	s_ff1_i32_b32 s0, s59
	s_bitset0_b32 s59, s0
	v_readlane_b32 s1, v184, s0
	s_lshl_b32 s1, s1, 11
	s_add_u32 s0, s48, s1
	s_addc_u32 s1, s49, 0
	global_load_dwordx2 v[90:91], v190, s[0:1]
	global_load_dwordx2 v[92:93], v190, s[0:1] offset:512
	global_load_dwordx2 v[94:95], v190, s[0:1] offset:1024
	global_load_dwordx2 v[96:97], v190, s[0:1] offset:1536
	s_add_i32 s71, s71, 1
; __device__ __forceinline__ float bf2f(u16 b) { return __uint_as_float(((unsigned)b) << 16); }
; template <bool COMBINE, bool MOD>
; __device__ __forceinline__ void phase_combine_modulate(const Params& p, int lprev, int lnext, const float* xlat, const float* xctx,
;                                                        float* olat, float* octx, int nrows) {
;     ...
;         unsigned mask = (unsigned)((__ballot(myinv >= 0) >> (16 * r)) & 0xFFFFull);
;         while (mask) {
;           const int e0 = __builtin_ctz(mask);
;           mask &= mask - 1;
;           const bool two = mask != 0u;
;           const int e1 = two ? __builtin_ctz(mask) : e0;
;           mask &= mask - 1;
;           const int s0 = __shfl(myinv, 16 * r + e0), s1 = __shfl(myinv, 16 * r + e1);
;           const size_t y0 = lat ? (size_t)(b * 16 + e0) * 1024 + s0 : (size_t)32768 + (size_t)(b * 16 + e0) * 128 + s0;
;           const size_t y1 = lat ? (size_t)(b * 16 + e1) * 1024 + s1 : (size_t)32768 + (size_t)(b * 16 + e1) * 128 + s1;
;           u32x2 a0[4], a1[4];
; #pragma unroll
;           for (int i = 0; i < 4; ++i) { a0[i] = *(const u32x2*)(p.YB + y0 * 1024 + lane * 4 + i * 256); a1[i] = *(const u32x2*)(p.YB + y1 * 1024 + lane * 4 + i * 256); }
;           const float w1 = two ? 1.f : 0.f;
; #pragma unroll
;           for (int i = 0; i < 4; ++i) {
;             s[i].x += bf2f((u16)(a0[i].x & 0xffffu)); s[i].y += bf2f((u16)(a0[i].x >> 16));
;             s[i].z += bf2f((u16)(a0[i].y & 0xffffu)); s[i].w += bf2f((u16)(a0[i].y >> 16));
;             s[i].x += w1 * bf2f((u16)(a1[i].x & 0xffffu)); s[i].y += w1 * bf2f((u16)(a1[i].x >> 16));
;             s[i].z += w1 * bf2f((u16)(a1[i].y & 0xffffu)); s[i].w += w1 * bf2f((u16)(a1[i].y >> 16));
;           }
.Lcb1_iss0:
	s_cmp_eq_u32 s60, 0
	s_cbranch_scc1 .Lcb1_iss1
	s_ff1_i32_b32 s0, s60
	s_bitset0_b32 s60, s0
	s_add_i32 s0, s0, 16
	v_readlane_b32 s1, v184, s0
	s_lshl_b32 s1, s1, 11
	s_add_u32 s0, s48, s1
	s_addc_u32 s1, s49, 0
	global_load_dwordx2 v[200:201], v190, s[0:1]
	global_load_dwordx2 v[202:203], v190, s[0:1] offset:512
	global_load_dwordx2 v[204:205], v190, s[0:1] offset:1024
	global_load_dwordx2 v[206:207], v190, s[0:1] offset:1536
	s_add_i32 s32, s32, 1
	s_cmp_eq_u32 s60, 0
	s_cbranch_scc1 .Lcb1_iss1
	s_ff1_i32_b32 s0, s60
	s_bitset0_b32 s60, s0
	s_add_i32 s0, s0, 16
	v_readlane_b32 s1, v184, s0
	s_lshl_b32 s1, s1, 11
	s_add_u32 s0, s48, s1
	s_addc_u32 s1, s49, 0
	global_load_dwordx2 v[216:217], v190, s[0:1]
	global_load_dwordx2 v[218:219], v190, s[0:1] offset:512
	global_load_dwordx2 v[220:221], v190, s[0:1] offset:1024
	global_load_dwordx2 v[222:223], v190, s[0:1] offset:1536
	s_add_i32 s32, s32, 1
	s_cmp_eq_u32 s60, 0
	s_cbranch_scc1 .Lcb1_iss1
	s_ff1_i32_b32 s0, s60
	s_bitset0_b32 s60, s0
	s_add_i32 s0, s0, 16
	v_readlane_b32 s1, v184, s0
	s_lshl_b32 s1, s1, 11
	s_add_u32 s0, s48, s1
	s_addc_u32 s1, s49, 0
	global_load_dwordx2 v[230:231], v190, s[0:1]
	global_load_dwordx2 v[232:233], v190, s[0:1] offset:512
	global_load_dwordx2 v[234:235], v190, s[0:1] offset:1024
	global_load_dwordx2 v[236:237], v190, s[0:1] offset:1536
	s_add_i32 s32, s32, 1
	s_cmp_eq_u32 s60, 0
	s_cbranch_scc1 .Lcb1_iss1
	s_ff1_i32_b32 s0, s60
	s_bitset0_b32 s60, s0
	s_add_i32 s0, s0, 16
	v_readlane_b32 s1, v184, s0
	s_lshl_b32 s1, s1, 11
	s_add_u32 s0, s48, s1
	s_addc_u32 s1, s49, 0
	global_load_dwordx2 v[238:239], v190, s[0:1]
	global_load_dwordx2 v[240:241], v190, s[0:1] offset:512
	global_load_dwordx2 v[242:243], v190, s[0:1] offset:1024
	global_load_dwordx2 v[244:245], v190, s[0:1] offset:1536
	s_add_i32 s32, s32, 1
.Lcb1_iss1:
	s_waitcnt vmcnt(0)
	s_cmp_le_u32 s71, 0
	s_cbranch_scc1 .Lcb1_acc0
	v_lshlrev_b32_e32 v180, 16, v164
	v_and_b32_e32 v181, 0xffff0000, v164
	v_lshlrev_b32_e32 v182, 16, v165
	v_and_b32_e32 v183, 0xffff0000, v165
	v_pk_add_f32 v[2:3], v[2:3], v[180:181]
	v_pk_add_f32 v[4:5], v[4:5], v[182:183]
	v_lshlrev_b32_e32 v180, 16, v166
	v_and_b32_e32 v181, 0xffff0000, v166
	v_lshlrev_b32_e32 v182, 16, v167
	v_and_b32_e32 v183, 0xffff0000, v167
	v_pk_add_f32 v[6:7], v[6:7], v[180:181]
	v_pk_add_f32 v[8:9], v[8:9], v[182:183]
	v_lshlrev_b32_e32 v180, 16, v168
	v_and_b32_e32 v181, 0xffff0000, v168
	v_lshlrev_b32_e32 v182, 16, v169
	v_and_b32_e32 v183, 0xffff0000, v169
	v_pk_add_f32 v[10:11], v[10:11], v[180:181]
	v_pk_add_f32 v[12:13], v[12:13], v[182:183]
	v_lshlrev_b32_e32 v180, 16, v170
	v_and_b32_e32 v181, 0xffff0000, v170
	v_lshlrev_b32_e32 v182, 16, v171
	v_and_b32_e32 v183, 0xffff0000, v171
	v_pk_add_f32 v[14:15], v[14:15], v[180:181]
	v_pk_add_f32 v[16:17], v[16:17], v[182:183]
	s_cmp_le_u32 s71, 1
	s_cbranch_scc1 .Lcb1_acc0
	v_lshlrev_b32_e32 v180, 16, v172
	v_and_b32_e32 v181, 0xffff0000, v172
	v_lshlrev_b32_e32 v182, 16, v173
	v_and_b32_e32 v183, 0xffff0000, v173
	v_pk_add_f32 v[2:3], v[2:3], v[180:181]
	v_pk_add_f32 v[4:5], v[4:5], v[182:183]
	v_lshlrev_b32_e32 v180, 16, v174
	v_and_b32_e32 v181, 0xffff0000, v174
	v_lshlrev_b32_e32 v182, 16, v175
	v_and_b32_e32 v183, 0xffff0000, v175
	v_pk_add_f32 v[6:7], v[6:7], v[180:181]
	v_pk_add_f32 v[8:9], v[8:9], v[182:183]
	v_lshlrev_b32_e32 v180, 16, v176
	v_and_b32_e32 v181, 0xffff0000, v176
	v_lshlrev_b32_e32 v182, 16, v177
	v_and_b32_e32 v183, 0xffff0000, v177
	v_pk_add_f32 v[10:11], v[10:11], v[180:181]
	v_pk_add_f32 v[12:13], v[12:13], v[182:183]
	v_lshlrev_b32_e32 v180, 16, v178
	v_and_b32_e32 v181, 0xffff0000, v178
	v_lshlrev_b32_e32 v182, 16, v179
	v_and_b32_e32 v183, 0xffff0000, v179
	v_pk_add_f32 v[14:15], v[14:15], v[180:181]
	v_pk_add_f32 v[16:17], v[16:17], v[182:183]
	s_cmp_le_u32 s71, 2
	s_cbranch_scc1 .Lcb1_acc0
	v_lshlrev_b32_e32 v180, 16, v82
	v_and_b32_e32 v181, 0xffff0000, v82
	v_lshlrev_b32_e32 v182, 16, v83
	v_and_b32_e32 v183, 0xffff0000, v83
	v_pk_add_f32 v[2:3], v[2:3], v[180:181]
	v_pk_add_f32 v[4:5], v[4:5], v[182:183]
	v_lshlrev_b32_e32 v180, 16, v84
	v_and_b32_e32 v181, 0xffff0000, v84
	v_lshlrev_b32_e32 v182, 16, v85
	v_and_b32_e32 v183, 0xffff0000, v85
	v_pk_add_f32 v[6:7], v[6:7], v[180:181]
	v_pk_add_f32 v[8:9], v[8:9], v[182:183]
	v_lshlrev_b32_e32 v180, 16, v86
	v_and_b32_e32 v181, 0xffff0000, v86
	v_lshlrev_b32_e32 v182, 16, v87
	v_and_b32_e32 v183, 0xffff0000, v87
	v_pk_add_f32 v[10:11], v[10:11], v[180:181]
	v_pk_add_f32 v[12:13], v[12:13], v[182:183]
	v_lshlrev_b32_e32 v180, 16, v88
	v_and_b32_e32 v181, 0xffff0000, v88
	v_lshlrev_b32_e32 v182, 16, v89
	v_and_b32_e32 v183, 0xffff0000, v89
	v_pk_add_f32 v[14:15], v[14:15], v[180:181]
	v_pk_add_f32 v[16:17], v[16:17], v[182:183]
	s_cmp_le_u32 s71, 3
	s_cbranch_scc1 .Lcb1_acc0
	v_lshlrev_b32_e32 v180, 16, v90
	v_and_b32_e32 v181, 0xffff0000, v90
	v_lshlrev_b32_e32 v182, 16, v91
	v_and_b32_e32 v183, 0xffff0000, v91
	v_pk_add_f32 v[2:3], v[2:3], v[180:181]
	v_pk_add_f32 v[4:5], v[4:5], v[182:183]
	v_lshlrev_b32_e32 v180, 16, v92
	v_and_b32_e32 v181, 0xffff0000, v92
	v_lshlrev_b32_e32 v182, 16, v93
	v_and_b32_e32 v183, 0xffff0000, v93
	v_pk_add_f32 v[6:7], v[6:7], v[180:181]
	v_pk_add_f32 v[8:9], v[8:9], v[182:183]
	v_lshlrev_b32_e32 v180, 16, v94
	v_and_b32_e32 v181, 0xffff0000, v94
	v_lshlrev_b32_e32 v182, 16, v95
	v_and_b32_e32 v183, 0xffff0000, v95
	v_pk_add_f32 v[10:11], v[10:11], v[180:181]
	v_pk_add_f32 v[12:13], v[12:13], v[182:183]
	v_lshlrev_b32_e32 v180, 16, v96
	v_and_b32_e32 v181, 0xffff0000, v96
	v_lshlrev_b32_e32 v182, 16, v97
	v_and_b32_e32 v183, 0xffff0000, v97
	v_pk_add_f32 v[14:15], v[14:15], v[180:181]
	v_pk_add_f32 v[16:17], v[16:17], v[182:183]
; __device__ __forceinline__ float bf2f(u16 b) { return __uint_as_float(((unsigned)b) << 16); }
; template <bool COMBINE, bool MOD>
; __device__ __forceinline__ void phase_combine_modulate(const Params& p, int lprev, int lnext, const float* xlat, const float* xctx,
;                                                        float* olat, float* octx, int nrows) {
;     ...
;         while (mask) {
;           const int e0 = __builtin_ctz(mask);
;           mask &= mask - 1;
;           const bool two = mask != 0u;
;           const int e1 = two ? __builtin_ctz(mask) : e0;
;           mask &= mask - 1;
;           const int s0 = __shfl(myinv, 16 * r + e0), s1 = __shfl(myinv, 16 * r + e1);
;           const size_t y0 = lat ? (size_t)(b * 16 + e0) * 1024 + s0 : (size_t)32768 + (size_t)(b * 16 + e0) * 128 + s0;
;           const size_t y1 = lat ? (size_t)(b * 16 + e1) * 1024 + s1 : (size_t)32768 + (size_t)(b * 16 + e1) * 128 + s1;
;           u32x2 a0[4], a1[4];
; #pragma unroll
;           for (int i = 0; i < 4; ++i) { a0[i] = *(const u32x2*)(p.YB + y0 * 1024 + lane * 4 + i * 256); a1[i] = *(const u32x2*)(p.YB + y1 * 1024 + lane * 4 + i * 256); }
;           const float w1 = two ? 1.f : 0.f;
; #pragma unroll
;           for (int i = 0; i < 4; ++i) {
;             s[i].x += bf2f((u16)(a0[i].x & 0xffffu)); s[i].y += bf2f((u16)(a0[i].x >> 16));
;             s[i].z += bf2f((u16)(a0[i].y & 0xffffu)); s[i].w += bf2f((u16)(a0[i].y >> 16));
;             s[i].x += w1 * bf2f((u16)(a1[i].x & 0xffffu)); s[i].y += w1 * bf2f((u16)(a1[i].x >> 16));
;             s[i].z += w1 * bf2f((u16)(a1[i].y & 0xffffu)); s[i].w += w1 * bf2f((u16)(a1[i].y >> 16));
;           }
.Lcb1_left0:
	s_cmp_eq_u32 s59, 0
	s_cbranch_scc1 .Lcb1_acc0
	s_ff1_i32_b32 s0, s59
	s_bitset0_b32 s59, s0
	v_readlane_b32 s1, v184, s0
	s_lshl_b32 s1, s1, 11
	s_add_u32 s0, s48, s1
	s_addc_u32 s1, s49, 0
	global_load_dwordx2 v[164:165], v190, s[0:1]
	global_load_dwordx2 v[166:167], v190, s[0:1] offset:512
	global_load_dwordx2 v[168:169], v190, s[0:1] offset:1024
	global_load_dwordx2 v[170:171], v190, s[0:1] offset:1536
	s_waitcnt vmcnt(0)
	v_lshlrev_b32_e32 v180, 16, v164
	v_and_b32_e32 v181, 0xffff0000, v164
	v_lshlrev_b32_e32 v182, 16, v165
	v_and_b32_e32 v183, 0xffff0000, v165
	v_pk_add_f32 v[2:3], v[2:3], v[180:181]
	v_pk_add_f32 v[4:5], v[4:5], v[182:183]
	v_lshlrev_b32_e32 v180, 16, v166
	v_and_b32_e32 v181, 0xffff0000, v166
	v_lshlrev_b32_e32 v182, 16, v167
	v_and_b32_e32 v183, 0xffff0000, v167
	v_pk_add_f32 v[6:7], v[6:7], v[180:181]
	v_pk_add_f32 v[8:9], v[8:9], v[182:183]
	v_lshlrev_b32_e32 v180, 16, v168
	v_and_b32_e32 v181, 0xffff0000, v168
	v_lshlrev_b32_e32 v182, 16, v169
	v_and_b32_e32 v183, 0xffff0000, v169
	v_pk_add_f32 v[10:11], v[10:11], v[180:181]
	v_pk_add_f32 v[12:13], v[12:13], v[182:183]
	v_lshlrev_b32_e32 v180, 16, v170
	v_and_b32_e32 v181, 0xffff0000, v170
	v_lshlrev_b32_e32 v182, 16, v171
	v_and_b32_e32 v183, 0xffff0000, v171
	v_pk_add_f32 v[14:15], v[14:15], v[180:181]
	v_pk_add_f32 v[16:17], v[16:17], v[182:183]
	s_branch .Lcb1_left0
.Lcb1_acc0:
	s_cmp_le_u32 s32, 0
	s_cbranch_scc1 .Lcb1_acc1
	v_lshlrev_b32_e32 v180, 16, v200
	v_and_b32_e32 v181, 0xffff0000, v200
	v_lshlrev_b32_e32 v182, 16, v201
	v_and_b32_e32 v183, 0xffff0000, v201
	v_pk_add_f32 v[18:19], v[18:19], v[180:181]
	v_pk_add_f32 v[20:21], v[20:21], v[182:183]
	v_lshlrev_b32_e32 v180, 16, v202
	v_and_b32_e32 v181, 0xffff0000, v202
	v_lshlrev_b32_e32 v182, 16, v203
	v_and_b32_e32 v183, 0xffff0000, v203
	v_pk_add_f32 v[22:23], v[22:23], v[180:181]
	v_pk_add_f32 v[24:25], v[24:25], v[182:183]
	v_lshlrev_b32_e32 v180, 16, v204
	v_and_b32_e32 v181, 0xffff0000, v204
	v_lshlrev_b32_e32 v182, 16, v205
	v_and_b32_e32 v183, 0xffff0000, v205
	v_pk_add_f32 v[26:27], v[26:27], v[180:181]
	v_pk_add_f32 v[28:29], v[28:29], v[182:183]
	v_lshlrev_b32_e32 v180, 16, v206
	v_and_b32_e32 v181, 0xffff0000, v206
	v_lshlrev_b32_e32 v182, 16, v207
	v_and_b32_e32 v183, 0xffff0000, v207
	v_pk_add_f32 v[30:31], v[30:31], v[180:181]
	v_pk_add_f32 v[32:33], v[32:33], v[182:183]
	s_cmp_le_u32 s32, 1
	s_cbranch_scc1 .Lcb1_acc1
	v_lshlrev_b32_e32 v180, 16, v216
	v_and_b32_e32 v181, 0xffff0000, v216
	v_lshlrev_b32_e32 v182, 16, v217
	v_and_b32_e32 v183, 0xffff0000, v217
	v_pk_add_f32 v[18:19], v[18:19], v[180:181]
	v_pk_add_f32 v[20:21], v[20:21], v[182:183]
	v_lshlrev_b32_e32 v180, 16, v218
	v_and_b32_e32 v181, 0xffff0000, v218
	v_lshlrev_b32_e32 v182, 16, v219
	v_and_b32_e32 v183, 0xffff0000, v219
	v_pk_add_f32 v[22:23], v[22:23], v[180:181]
	v_pk_add_f32 v[24:25], v[24:25], v[182:183]
	v_lshlrev_b32_e32 v180, 16, v220
	v_and_b32_e32 v181, 0xffff0000, v220
	v_lshlrev_b32_e32 v182, 16, v221
	v_and_b32_e32 v183, 0xffff0000, v221
	v_pk_add_f32 v[26:27], v[26:27], v[180:181]
	v_pk_add_f32 v[28:29], v[28:29], v[182:183]
	v_lshlrev_b32_e32 v180, 16, v222
	v_and_b32_e32 v181, 0xffff0000, v222
	v_lshlrev_b32_e32 v182, 16, v223
	v_and_b32_e32 v183, 0xffff0000, v223
	v_pk_add_f32 v[30:31], v[30:31], v[180:181]
	v_pk_add_f32 v[32:33], v[32:33], v[182:183]
	s_cmp_le_u32 s32, 2
	s_cbranch_scc1 .Lcb1_acc1
	v_lshlrev_b32_e32 v180, 16, v230
	v_and_b32_e32 v181, 0xffff0000, v230
	v_lshlrev_b32_e32 v182, 16, v231
	v_and_b32_e32 v183, 0xffff0000, v231
	v_pk_add_f32 v[18:19], v[18:19], v[180:181]
	v_pk_add_f32 v[20:21], v[20:21], v[182:183]
	v_lshlrev_b32_e32 v180, 16, v232
	v_and_b32_e32 v181, 0xffff0000, v232
	v_lshlrev_b32_e32 v182, 16, v233
	v_and_b32_e32 v183, 0xffff0000, v233
	v_pk_add_f32 v[22:23], v[22:23], v[180:181]
	v_pk_add_f32 v[24:25], v[24:25], v[182:183]
	v_lshlrev_b32_e32 v180, 16, v234
	v_and_b32_e32 v181, 0xffff0000, v234
	v_lshlrev_b32_e32 v182, 16, v235
	v_and_b32_e32 v183, 0xffff0000, v235
	v_pk_add_f32 v[26:27], v[26:27], v[180:181]
	v_pk_add_f32 v[28:29], v[28:29], v[182:183]
	v_lshlrev_b32_e32 v180, 16, v236
	v_and_b32_e32 v181, 0xffff0000, v236
	v_lshlrev_b32_e32 v182, 16, v237
	v_and_b32_e32 v183, 0xffff0000, v237
	v_pk_add_f32 v[30:31], v[30:31], v[180:181]
	v_pk_add_f32 v[32:33], v[32:33], v[182:183]
	s_cmp_le_u32 s32, 3
	s_cbranch_scc1 .Lcb1_acc1
	v_lshlrev_b32_e32 v180, 16, v238
	v_and_b32_e32 v181, 0xffff0000, v238
	v_lshlrev_b32_e32 v182, 16, v239
	v_and_b32_e32 v183, 0xffff0000, v239
	v_pk_add_f32 v[18:19], v[18:19], v[180:181]
	v_pk_add_f32 v[20:21], v[20:21], v[182:183]
	v_lshlrev_b32_e32 v180, 16, v240
	v_and_b32_e32 v181, 0xffff0000, v240
	v_lshlrev_b32_e32 v182, 16, v241
	v_and_b32_e32 v183, 0xffff0000, v241
	v_pk_add_f32 v[22:23], v[22:23], v[180:181]
	v_pk_add_f32 v[24:25], v[24:25], v[182:183]
	v_lshlrev_b32_e32 v180, 16, v242
	v_and_b32_e32 v181, 0xffff0000, v242
	v_lshlrev_b32_e32 v182, 16, v243
	v_and_b32_e32 v183, 0xffff0000, v243
	v_pk_add_f32 v[26:27], v[26:27], v[180:181]
	v_pk_add_f32 v[28:29], v[28:29], v[182:183]
	v_lshlrev_b32_e32 v180, 16, v244
	v_and_b32_e32 v181, 0xffff0000, v244
	v_lshlrev_b32_e32 v182, 16, v245
	v_and_b32_e32 v183, 0xffff0000, v245
	v_pk_add_f32 v[30:31], v[30:31], v[180:181]
	v_pk_add_f32 v[32:33], v[32:33], v[182:183]
; template <bool COMBINE, bool MOD>
; __device__ __forceinline__ void phase_combine_modulate(const Params& p, int lprev, int lnext, const float* xlat, const float* xctx,
;                                                        float* olat, float* octx, int nrows) {
;     ...
; #pragma unroll
;         for (int i = 0; i < 4; ++i) {
;           const int col = i * 256 + lane * 4;
;           const float4 g4 = *(const float4*)(g2 + col);
;           v[r][i].x += g4.x * s[i].x; v[r][i].y += g4.y * s[i].y; v[r][i].z += g4.z * s[i].z; v[r][i].w += g4.w * s[i].w;
;           *(float4*)(orow + (size_t)r * DM + col) = v[r][i];
;         }
;       }
;     }
;     if (MOD) {
;       const float* sh = p.mada + (size_t)(lnext * 3 + cond) * 6144;
;       const float* sc = sh + 1024;
;       float rstd[R];
; #pragma unroll
;       for (int r = 0; r < R; ++r) {
;         float ss = 0.f;
; #pragma unroll
;         for (int i = 0; i < 4; ++i) ss += v[r][i].x * v[r][i].x + v[r][i].y * v[r][i].y + v[r][i].z * v[r][i].z + v[r][i].w * v[r][i].w;
;         rstd[r] = rsqrtf(wave_sum(ss) * (1.f / 1024.f) + 1e-6f);
.Lcb1_left1:
	s_cmp_eq_u32 s60, 0
	s_cbranch_scc1 .Lcb1_acc1
	s_ff1_i32_b32 s0, s60
	s_bitset0_b32 s60, s0
	s_add_i32 s0, s0, 16
	v_readlane_b32 s1, v184, s0
	s_lshl_b32 s1, s1, 11
	s_add_u32 s0, s48, s1
	s_addc_u32 s1, s49, 0
	global_load_dwordx2 v[200:201], v190, s[0:1]
	global_load_dwordx2 v[202:203], v190, s[0:1] offset:512
	global_load_dwordx2 v[204:205], v190, s[0:1] offset:1024
	global_load_dwordx2 v[206:207], v190, s[0:1] offset:1536
	s_waitcnt vmcnt(0)
	v_lshlrev_b32_e32 v180, 16, v200
	v_and_b32_e32 v181, 0xffff0000, v200
	v_lshlrev_b32_e32 v182, 16, v201
	v_and_b32_e32 v183, 0xffff0000, v201
	v_pk_add_f32 v[18:19], v[18:19], v[180:181]
	v_pk_add_f32 v[20:21], v[20:21], v[182:183]
	v_lshlrev_b32_e32 v180, 16, v202
	v_and_b32_e32 v181, 0xffff0000, v202
	v_lshlrev_b32_e32 v182, 16, v203
	v_and_b32_e32 v183, 0xffff0000, v203
	v_pk_add_f32 v[22:23], v[22:23], v[180:181]
	v_pk_add_f32 v[24:25], v[24:25], v[182:183]
	v_lshlrev_b32_e32 v180, 16, v204
	v_and_b32_e32 v181, 0xffff0000, v204
	v_lshlrev_b32_e32 v182, 16, v205
	v_and_b32_e32 v183, 0xffff0000, v205
	v_pk_add_f32 v[26:27], v[26:27], v[180:181]
	v_pk_add_f32 v[28:29], v[28:29], v[182:183]
	v_lshlrev_b32_e32 v180, 16, v206
	v_and_b32_e32 v181, 0xffff0000, v206
	v_lshlrev_b32_e32 v182, 16, v207
	v_and_b32_e32 v183, 0xffff0000, v207
	v_pk_add_f32 v[30:31], v[30:31], v[180:181]
	v_pk_add_f32 v[32:33], v[32:33], v[182:183]
	s_branch .Lcb1_left1
.Lcb1_acc1:
	v_pk_fma_f32 v[100:101], v[34:35], v[2:3], v[100:101]
	v_pk_fma_f32 v[102:103], v[36:37], v[4:5], v[102:103]
	global_store_dwordx4 v188, v[100:103], s[98:99]
	v_pk_fma_f32 v[104:105], v[38:39], v[6:7], v[104:105]
	v_pk_fma_f32 v[106:107], v[40:41], v[8:9], v[106:107]
	global_store_dwordx4 v188, v[104:107], s[98:99] offset:1024
	v_pk_fma_f32 v[108:109], v[42:43], v[10:11], v[108:109]
	v_pk_fma_f32 v[110:111], v[44:45], v[12:13], v[110:111]
	global_store_dwordx4 v188, v[108:111], s[98:99] offset:2048
	v_pk_fma_f32 v[112:113], v[46:47], v[14:15], v[112:113]
	v_pk_fma_f32 v[114:115], v[48:49], v[16:17], v[114:115]
	global_store_dwordx4 v188, v[112:115], s[98:99] offset:3072
	v_pk_fma_f32 v[116:117], v[34:35], v[18:19], v[116:117]
	v_pk_fma_f32 v[118:119], v[36:37], v[20:21], v[118:119]
	global_store_dwordx4 v189, v[116:119], s[98:99]
	v_pk_fma_f32 v[120:121], v[38:39], v[22:23], v[120:121]
	v_pk_fma_f32 v[122:123], v[40:41], v[24:25], v[122:123]
	global_store_dwordx4 v189, v[120:123], s[98:99] offset:1024
	v_pk_fma_f32 v[124:125], v[42:43], v[26:27], v[124:125]
	v_pk_fma_f32 v[126:127], v[44:45], v[28:29], v[126:127]
	global_store_dwordx4 v189, v[124:127], s[98:99] offset:2048
	v_pk_fma_f32 v[128:129], v[46:47], v[30:31], v[128:129]
	v_pk_fma_f32 v[130:131], v[48:49], v[32:33], v[130:131]
	global_store_dwordx4 v189, v[128:131], s[98:99] offset:3072
	v_pk_mul_f32 v[2:3], v[100:101], v[100:101]
	v_pk_fma_f32 v[2:3], v[102:103], v[102:103], v[2:3]
	v_pk_fma_f32 v[2:3], v[104:105], v[104:105], v[2:3]
	v_pk_fma_f32 v[2:3], v[106:107], v[106:107], v[2:3]
	v_pk_fma_f32 v[2:3], v[108:109], v[108:109], v[2:3]
	v_pk_fma_f32 v[2:3], v[110:111], v[110:111], v[2:3]
	v_pk_fma_f32 v[2:3], v[112:113], v[112:113], v[2:3]
	v_pk_fma_f32 v[2:3], v[114:115], v[114:115], v[2:3]
	v_pk_mul_f32 v[4:5], v[116:117], v[116:117]
	v_pk_fma_f32 v[4:5], v[118:119], v[118:119], v[4:5]
	v_pk_fma_f32 v[4:5], v[120:121], v[120:121], v[4:5]
	v_pk_fma_f32 v[4:5], v[122:123], v[122:123], v[4:5]
	v_pk_fma_f32 v[4:5], v[124:125], v[124:125], v[4:5]
	v_pk_fma_f32 v[4:5], v[126:127], v[126:127], v[4:5]
	v_pk_fma_f32 v[4:5], v[128:129], v[128:129], v[4:5]
	v_pk_fma_f32 v[4:5], v[130:131], v[130:131], v[4:5]
	v_add_f32_e32 v6, v2, v3
	v_add_f32_e32 v7, v4, v5
	s_nop 1
	v_add_f32_dpp v6, v6, v6 quad_perm:[1,0,3,2] row_mask:0xf bank_mask:0xf
	v_add_f32_dpp v7, v7, v7 quad_perm:[1,0,3,2] row_mask:0xf bank_mask:0xf
	s_nop 1
	v_add_f32_dpp v6, v6, v6 quad_perm:[2,3,0,1] row_mask:0xf bank_mask:0xf
	v_add_f32_dpp v7, v7, v7 quad_perm:[2,3,0,1] row_mask:0xf bank_mask:0xf
	s_nop 1
	v_add_f32_dpp v6, v6, v6 row_half_mirror row_mask:0xf bank_mask:0xf
	v_add_f32_dpp v7, v7, v7 row_half_mirror row_mask:0xf bank_mask:0xf
	s_nop 1
	v_add_f32_dpp v6, v6, v6 row_mirror row_mask:0xf bank_mask:0xf
	v_add_f32_dpp v7, v7, v7 row_mirror row_mask:0xf bank_mask:0xf
	ds_bpermute_b32 v8, v208, v6
	ds_bpermute_b32 v9, v208, v7
	s_waitcnt lgkmcnt(0)
	v_pk_add_f32 v[6:7], v[6:7], v[8:9]
	ds_bpermute_b32 v8, v209, v6
	ds_bpermute_b32 v9, v209, v7
	s_waitcnt lgkmcnt(0)
; template <bool COMBINE, bool MOD>
; __device__ __forceinline__ void phase_combine_modulate(const Params& p, int lprev, int lnext, const float* xlat, const float* xctx,
;                                                        float* olat, float* octx, int nrows) {
;     ...
;       for (int r = 0; r < R; ++r) {
;         float ss = 0.f;
; #pragma unroll
;         for (int i = 0; i < 4; ++i) ss += v[r][i].x * v[r][i].x + v[r][i].y * v[r][i].y + v[r][i].z * v[r][i].z + v[r][i].w * v[r][i].w;
;         rstd[r] = rsqrtf(wave_sum(ss) * (1.f / 1024.f) + 1e-6f);
;       }
; #pragma unroll
;       for (int i = 0; i < 4; ++i) {
;         const int col = i * 256 + lane * 4;
;         const float4 s4 = *(const float4*)(sc + col);
;         const float4 h4 = *(const float4*)(sh + col);
; #pragma unroll
;         for (int r = 0; r < R; ++r) {
;           u32x2 pk;
;           pk.x = pack2(v[r][i].x * rstd[r] * (1.f + s4.x) + h4.x, v[r][i].y * rstd[r] * (1.f + s4.y) + h4.y);
;           pk.y = pack2(v[r][i].z * rstd[r] * (1.f + s4.z) + h4.z, v[r][i].w * rstd[r] * (1.f + s4.w) + h4.w);
;           *(u32x2*)(p.H + (size_t)(row0 + r) * DM + col) = pk;
;         }
;       }
	v_pk_add_f32 v[6:7], v[6:7], v[8:9]
	s_nop 0
	v_fma_f32 v6, v6, s18, v224
	v_fma_f32 v7, v7, s18, v224
	v_cmp_gt_f32_e32 vcc, s85, v6
	v_mul_f32_e32 v10, 0x4b800000, v6
	s_nop 1
	v_cndmask_b32_e32 v10, v6, v10, vcc
	v_rsq_f32_e32 v10, v10
	s_nop 0
	v_mul_f32_e32 v6, 0x45800000, v10
	v_cndmask_b32_e32 v10, v10, v6, vcc
	v_cmp_gt_f32_e32 vcc, s85, v7
	v_mul_f32_e32 v12, 0x4b800000, v7
	s_nop 1
	v_cndmask_b32_e32 v12, v7, v12, vcc
	v_rsq_f32_e32 v12, v12
	s_nop 0
	v_mul_f32_e32 v7, 0x45800000, v12
	v_cndmask_b32_e32 v12, v12, v7, vcc
	v_pk_add_f32 v[66:67], v[66:67], 1.0 op_sel_hi:[1,0]
	v_pk_add_f32 v[68:69], v[68:69], 1.0 op_sel_hi:[1,0]
	v_pk_mul_f32 v[14:15], v[100:101], v[10:11] op_sel_hi:[1,0]
	v_pk_mul_f32 v[16:17], v[102:103], v[10:11] op_sel_hi:[1,0]
	v_pk_fma_f32 v[14:15], v[66:67], v[14:15], v[50:51]
	v_pk_fma_f32 v[16:17], v[68:69], v[16:17], v[52:53]
	v_cvt_pk_bf16_f32 v164, v14, v15
	v_cvt_pk_bf16_f32 v165, v16, v17
	global_store_dwordx2 v190, v[164:165], s[46:47]
	v_pk_mul_f32 v[18:19], v[116:117], v[12:13] op_sel_hi:[1,0]
	v_pk_mul_f32 v[20:21], v[118:119], v[12:13] op_sel_hi:[1,0]
	v_pk_fma_f32 v[18:19], v[66:67], v[18:19], v[50:51]
	v_pk_fma_f32 v[20:21], v[68:69], v[20:21], v[52:53]
	v_cvt_pk_bf16_f32 v166, v18, v19
	v_cvt_pk_bf16_f32 v167, v20, v21
	global_store_dwordx2 v190, v[166:167], s[46:47] offset:2048
	v_pk_add_f32 v[70:71], v[70:71], 1.0 op_sel_hi:[1,0]
	v_pk_add_f32 v[72:73], v[72:73], 1.0 op_sel_hi:[1,0]
	v_pk_mul_f32 v[14:15], v[104:105], v[10:11] op_sel_hi:[1,0]
	v_pk_mul_f32 v[16:17], v[106:107], v[10:11] op_sel_hi:[1,0]
	v_pk_fma_f32 v[14:15], v[70:71], v[14:15], v[54:55]
	v_pk_fma_f32 v[16:17], v[72:73], v[16:17], v[56:57]
	v_cvt_pk_bf16_f32 v168, v14, v15
	v_cvt_pk_bf16_f32 v169, v16, v17
	global_store_dwordx2 v190, v[168:169], s[46:47] offset:512
	v_pk_mul_f32 v[18:19], v[120:121], v[12:13] op_sel_hi:[1,0]
	v_pk_mul_f32 v[20:21], v[122:123], v[12:13] op_sel_hi:[1,0]
	v_pk_fma_f32 v[18:19], v[70:71], v[18:19], v[54:55]
	v_pk_fma_f32 v[20:21], v[72:73], v[20:21], v[56:57]
	v_cvt_pk_bf16_f32 v170, v18, v19
	v_cvt_pk_bf16_f32 v171, v20, v21
	global_store_dwordx2 v190, v[170:171], s[46:47] offset:2560
	v_pk_add_f32 v[74:75], v[74:75], 1.0 op_sel_hi:[1,0]
	v_pk_add_f32 v[76:77], v[76:77], 1.0 op_sel_hi:[1,0]
	v_pk_mul_f32 v[14:15], v[108:109], v[10:11] op_sel_hi:[1,0]
	v_pk_mul_f32 v[16:17], v[110:111], v[10:11] op_sel_hi:[1,0]
	v_pk_fma_f32 v[14:15], v[74:75], v[14:15], v[58:59]
	v_pk_fma_f32 v[16:17], v[76:77], v[16:17], v[60:61]
	v_cvt_pk_bf16_f32 v172, v14, v15
	v_cvt_pk_bf16_f32 v173, v16, v17
	global_store_dwordx2 v190, v[172:173], s[46:47] offset:1024
	v_pk_mul_f32 v[18:19], v[124:125], v[12:13] op_sel_hi:[1,0]
	v_pk_mul_f32 v[20:21], v[126:127], v[12:13] op_sel_hi:[1,0]
	v_pk_fma_f32 v[18:19], v[74:75], v[18:19], v[58:59]
	v_pk_fma_f32 v[20:21], v[76:77], v[20:21], v[60:61]
	v_cvt_pk_bf16_f32 v174, v18, v19
	v_cvt_pk_bf16_f32 v175, v20, v21
	global_store_dwordx2 v190, v[174:175], s[46:47] offset:3072
	v_pk_add_f32 v[78:79], v[78:79], 1.0 op_sel_hi:[1,0]
	v_pk_add_f32 v[80:81], v[80:81], 1.0 op_sel_hi:[1,0]
	v_pk_mul_f32 v[14:15], v[112:113], v[10:11] op_sel_hi:[1,0]
	v_pk_mul_f32 v[16:17], v[114:115], v[10:11] op_sel_hi:[1,0]
	v_pk_fma_f32 v[14:15], v[78:79], v[14:15], v[62:63]
	v_pk_fma_f32 v[16:17], v[80:81], v[16:17], v[64:65]
	v_cvt_pk_bf16_f32 v176, v14, v15
	v_cvt_pk_bf16_f32 v177, v16, v17
	global_store_dwordx2 v190, v[176:177], s[46:47] offset:1536
	v_pk_mul_f32 v[18:19], v[128:129], v[12:13] op_sel_hi:[1,0]
	v_pk_mul_f32 v[20:21], v[130:131], v[12:13] op_sel_hi:[1,0]
	v_pk_fma_f32 v[18:19], v[78:79], v[18:19], v[62:63]
	v_pk_fma_f32 v[20:21], v[80:81], v[20:21], v[64:65]
	v_cvt_pk_bf16_f32 v178, v18, v19
	v_cvt_pk_bf16_f32 v179, v20, v21
	global_store_dwordx2 v190, v[178:179], s[46:47] offset:3584
	v_mov_b32_e32 v100, v132
	v_mov_b32_e32 v101, v133
	v_mov_b32_e32 v102, v134
	v_mov_b32_e32 v103, v135
	v_mov_b32_e32 v104, v136
	v_mov_b32_e32 v105, v137
	v_mov_b32_e32 v106, v138
	v_mov_b32_e32 v107, v139
	v_mov_b32_e32 v108, v140
	v_mov_b32_e32 v109, v141
	v_mov_b32_e32 v110, v142
	v_mov_b32_e32 v111, v143
	v_mov_b32_e32 v112, v144
	v_mov_b32_e32 v113, v145
	v_mov_b32_e32 v114, v146
	v_mov_b32_e32 v115, v147
	v_mov_b32_e32 v116, v148
	v_mov_b32_e32 v117, v149
	v_mov_b32_e32 v118, v150
	v_mov_b32_e32 v119, v151
	v_mov_b32_e32 v120, v152
	v_mov_b32_e32 v121, v153
	v_mov_b32_e32 v122, v154
	v_mov_b32_e32 v123, v155
	v_mov_b32_e32 v124, v156
	v_mov_b32_e32 v125, v157
	v_mov_b32_e32 v126, v158
	v_mov_b32_e32 v127, v159
	v_mov_b32_e32 v128, v160
	v_mov_b32_e32 v129, v161
	v_mov_b32_e32 v130, v162
	v_mov_b32_e32 v131, v163
	v_mov_b32_e32 v199, v211
	s_mov_b64 s[98:99], s[100:101]
	s_mov_b32 s52, s94
	s_cmp_lt_i32 s52, s68
	s_cbranch_scc1 .Lcb1_loop
	s_waitcnt vmcnt(0)

; __device__ __forceinline__ int tid_() { int t = threadIdx.x; asm volatile("" : "+v"(t)); return t; }
; template <int NT, bool BKN, bool MASK = false, bool ROWSS = false, class Epi> ...
;     ...
;   const int t = tid_(), lane = t & 63, wid = t >> 6, wr = wid >> 1, wc = wid & 1, l16 = lane & 15, quad = lane >> 4;
;   const u16* ap[4];
;   const u16* bp[NT];
;   unsigned amask = 0u;
; #pragma unroll
;   for (int i = 0; i < 4; ++i) {
;     const int row = (t >> 3) + 32 * i;
;     const bool v = MASK ? (row < mvalid) : true;
;     amask |= v ? (1u << i) : 0u;
;     int r = v ? row : 0;
;     if (arows) r = arows[r];
;     ap[i] = A + (size_t)r * lda + (t & 7) * 8;
;   }
; #pragma unroll
;   for (int i = 0; i < NT; ++i) {
;     if (!BKN) bp[i] = B + (size_t)((t >> 3) + 32 * i) * ldb + (t & 7) * 8;
;     else { const int c = t + 256 * i; bp[i] = B + (size_t)(c / CPR) * ldb + (c % CPR) * 8; }
;   }
;     ...
;   float ss_[4] = {0.f, 0.f, 0.f, 0.f};
;   int stk_ = 0;
;   f32x4 acc[4][NT];
; #pragma unroll
;   for (int i = 0; i < 4; ++i)
; #pragma unroll
;     for (int j = 0; j < NT; ++j) acc[i][j] = (f32x4){0.f, 0.f, 0.f, 0.f};
;   const int nk = K >> 6;
;   const int nkm1 = nk - 1;
;   __syncthreads();
;   GEMM_LOAD(ra0, rb0, 0);
;   GEMM_LOAD(ra1, rb1, 1);
;   GEMM_STORE(ra0, rb0, 0);
;   GEMM_LOAD(ra0, rb0, (2 < nkm1 ? 2 : nkm1));
;   __syncthreads();
.LBB0_243:
	v_mov_b64_e32 v[2:3], s[4:5]
	s_load_dwordx2 s[100:101], s[4:5], 0x118
	s_mul_hi_i32 s0, s9, 0x2e8ba2e9
	s_lshr_b32 s1, s0, 31
	s_ashr_i32 s0, s0, 1
	s_add_i32 s0, s0, s1
	v_mov_b32_e32 v70, v187
	s_mul_i32 s1, s0, 11
	s_lshl_b32 s42, s0, 7
	s_sub_i32 s40, s9, s1
	v_ashrrev_i32_e32 v6, 3, v70
	s_ashr_i32 s43, s42, 31
	v_ashrrev_i32_e32 v7, 31, v6
	s_lshl_b64 s[0:1], s[42:43], 11
	s_ashr_i32 s41, s40, 31
	v_lshlrev_b32_e32 v72, 4, v70
	v_lshlrev_b64 v[68:69], 11, v[6:7]
	s_mov_b64 s[18:19], 0x20000
	s_lshl_b64 s[38:39], s[40:41], 18
	v_and_b32_e32 v0, 0x70, v72
	v_lshl_add_u64 v[8:9], v[68:69], 0, s[18:19]
	s_mov_b64 s[18:19], 0x30000
	v_lshl_add_u64 v[4:5], v[132:133], 0, s[38:39]
	v_lshl_add_u64 v[6:7], v[68:69], 0, s[12:13]
	v_lshl_add_u64 v[10:11], v[68:69], 0, s[18:19]
	s_waitcnt lgkmcnt(0)
	s_barrier
	v_lshrrev_b32_e32 v71, 4, v70
	v_and_b32_e32 v72, 0xffffff80, v72
	v_and_b32_e32 v157, 15, v70
	v_bfe_u32 v159, v70, 4, 2
	v_bfe_u32 v156, v70, 6, 1
	v_ashrrev_i32_e32 v158, 7, v70
	v_mov_b32_e32 v78, 0
	v_mov_b32_e32 v79, v78
	v_mov_b32_e32 v80, v78
	v_mov_b32_e32 v81, v78
	v_mov_b32_e32 v74, v78
	v_mov_b32_e32 v75, v78
	v_mov_b32_e32 v76, v78
	v_mov_b32_e32 v77, v78
	v_mov_b32_e32 v82, v78
	v_mov_b32_e32 v83, v78
	v_mov_b32_e32 v84, v78
	v_mov_b32_e32 v85, v78
	v_mov_b32_e32 v86, v78
	v_mov_b32_e32 v87, v78
	v_mov_b32_e32 v88, v78
	v_mov_b32_e32 v89, v78
	v_mov_b32_e32 v126, v78
	v_mov_b32_e32 v127, v78
	v_mov_b32_e32 v128, v78
	v_mov_b32_e32 v129, v78
	v_mov_b32_e32 v122, v78
	v_mov_b32_e32 v123, v78
	v_mov_b32_e32 v124, v78
	v_mov_b32_e32 v125, v78
	v_mov_b32_e32 v102, v78
	v_mov_b32_e32 v103, v78
	v_mov_b32_e32 v104, v78
	v_mov_b32_e32 v105, v78
	v_mov_b32_e32 v110, v78
	v_mov_b32_e32 v111, v78
	v_mov_b32_e32 v112, v78
	v_mov_b32_e32 v113, v78
	v_mov_b32_e32 v114, v78
	v_mov_b32_e32 v115, v78
	v_mov_b32_e32 v116, v78
	v_mov_b32_e32 v117, v78
	v_mov_b32_e32 v94, v78
	v_mov_b32_e32 v95, v78
	v_mov_b32_e32 v96, v78
	v_mov_b32_e32 v97, v78
	v_mov_b32_e32 v90, v78
	v_mov_b32_e32 v91, v78
	v_mov_b32_e32 v92, v78
	v_mov_b32_e32 v93, v78
	v_mov_b32_e32 v98, v78
	v_mov_b32_e32 v99, v78
	s_waitcnt lgkmcnt(0)
	v_mov_b32_e32 v66, s100
	v_mov_b32_e32 v67, s101
	v_lshl_add_u64 v[2:3], v[66:67], 0, s[0:1]
	v_lshl_add_u64 v[2:3], v[2:3], 0, v[0:1]
	v_lshl_add_u64 v[136:137], v[2:3], 0, v[68:69]
	v_lshl_add_u64 v[138:139], v[2:3], 0, v[6:7]
	v_lshl_add_u64 v[140:141], v[2:3], 0, v[8:9]
	v_lshl_add_u64 v[142:143], v[2:3], 0, v[10:11]
	v_lshl_add_u64 v[2:3], v[4:5], 0, v[0:1]
	v_lshl_add_u64 v[144:145], v[2:3], 0, v[68:69]
	v_lshl_add_u64 v[146:147], v[2:3], 0, v[6:7]
	v_lshl_add_u64 v[148:149], v[2:3], 0, v[8:9]
	v_lshl_add_u64 v[150:151], v[2:3], 0, v[10:11]
	global_load_dwordx4 v[34:37], v[136:137], off
	global_load_dwordx4 v[38:41], v[138:139], off
	global_load_dwordx4 v[42:45], v[140:141], off
	global_load_dwordx4 v[46:49], v[142:143], off
	global_load_dwordx4 v[50:53], v[144:145], off
	global_load_dwordx4 v[54:57], v[146:147], off
	global_load_dwordx4 v[58:61], v[148:149], off
	global_load_dwordx4 v[62:65], v[150:151], off
	global_load_dwordx4 v[2:5], v[136:137], off offset:128
	global_load_dwordx4 v[26:29], v[138:139], off offset:128
	global_load_dwordx4 v[22:25], v[140:141], off offset:128
	global_load_dwordx4 v[18:21], v[142:143], off offset:128
	global_load_dwordx4 v[6:9], v[144:145], off offset:128
	global_load_dwordx4 v[14:17], v[146:147], off offset:128
	global_load_dwordx4 v[10:13], v[148:149], off offset:128
	global_load_dwordx4 v[30:33], v[150:151], off offset:128
	v_xor_b32_e32 v0, v71, v70
	v_lshlrev_b32_e32 v0, 4, v0
	v_and_or_b32 v163, v0, s14, v72
	v_bfe_u32 v0, v70, 1, 3
	v_bitop3_b32 v71, v71, v0, 3 bitop3:0x6c
	v_lshlrev_b32_e32 v72, 7, v157
	v_bitop3_b32 v0, v159, v0, 4 bitop3:0x36
	v_lshlrev_b32_e32 v71, 4, v71
	v_lshl_or_b32 v73, v158, 13, v72
	v_lshl_or_b32 v72, v156, 13, v72
	v_lshlrev_b32_e32 v0, 4, v0
	v_or_b32_e32 v162, v71, v73
	v_or_b32_e32 v164, v71, v72
	v_or_b32_e32 v160, v0, v73
	v_or_b32_e32 v161, v0, v72
	v_and_b32_e32 v0, 7, v70
	v_lshl_add_u64 v[70:71], s[38:39], 0, v[68:69]
	v_lshl_add_u64 v[68:69], v[68:69], 0, s[0:1]
	v_lshlrev_b32_e32 v0, 4, v0
	v_lshl_add_u64 v[152:153], v[134:135], 0, v[70:71]
	v_lshl_add_u64 v[154:155], v[66:67], 0, v[68:69]
	s_mov_b32 s0, -2
	v_mov_b32_e32 v66, v78
	v_mov_b32_e32 v67, v78
	v_mov_b32_e32 v68, v78
	v_mov_b32_e32 v69, v78
	v_mov_b32_e32 v70, v78
	v_mov_b32_e32 v71, v78
	v_mov_b32_e32 v72, v78
	v_mov_b32_e32 v73, v78
	v_mov_b32_e32 v100, v78
	v_mov_b32_e32 v101, v78
	v_mov_b32_e32 v106, v78
	v_mov_b32_e32 v107, v78
	v_mov_b32_e32 v108, v78
	v_mov_b32_e32 v109, v78
	v_mov_b32_e32 v118, v78
	v_mov_b32_e32 v119, v78
	v_mov_b32_e32 v120, v78
	v_mov_b32_e32 v121, v78
	s_waitcnt vmcnt(0) lgkmcnt(0)
	ds_write_b128 v163, v[34:37]
	ds_write_b128 v163, v[38:41] offset:4096
	ds_write_b128 v163, v[42:45] offset:8192
	ds_write_b128 v163, v[46:49] offset:12288
	ds_write_b128 v163, v[50:53] offset:16384
	ds_write_b128 v163, v[54:57] offset:20480
	ds_write_b128 v163, v[58:61] offset:24576
	ds_write_b128 v163, v[62:65] offset:28672
	global_load_dwordx4 v[34:37], v[136:137], off offset:256
	global_load_dwordx4 v[38:41], v[138:139], off offset:256
	global_load_dwordx4 v[46:49], v[140:141], off offset:256
	global_load_dwordx4 v[42:45], v[142:143], off offset:256
	global_load_dwordx4 v[50:53], v[144:145], off offset:256
	global_load_dwordx4 v[58:61], v[146:147], off offset:256
	global_load_dwordx4 v[54:57], v[148:149], off offset:256
	global_load_dwordx4 v[62:65], v[150:151], off offset:256
	s_waitcnt lgkmcnt(0)
	s_barrier
	ds_read_b128 v[170:173], v162
	ds_read_b128 v[188:191], v164 offset:16384
	ds_read_b128 v[192:195], v164 offset:18432
	ds_read_b128 v[196:199], v164 offset:20480
	ds_read_b128 v[200:203], v164 offset:22528
	ds_read_b128 v[174:177], v162 offset:2048
	ds_read_b128 v[178:181], v162 offset:4096
	ds_read_b128 v[182:185], v162 offset:6144
; template <int NT, bool BKN, bool MASK = false, bool ROWSS = false, class Epi> ...
;     ...
;   for (int kt = 0; kt < nk - 2; kt += 2) {
;     GEMM_COMPUTE(0);
;     GEMM_STORE(ra1, rb1, 1);
;     GEMM_LOAD(ra1, rb1, kt + 3);
;     __syncthreads();
;     GEMM_COMPUTE(1);
;     GEMM_STORE(ra0, rb0, 0);
;     GEMM_LOAD(ra0, rb0, (kt + 4 < nkm1 ? kt + 4 : nkm1));
;     __syncthreads();
;   }
.LBB0_244:
	s_add_i32 s0, s0, 2
	s_min_u32 s1, s0, 11
	s_lshl_b32 s94, s1, 7
	s_cmp_lt_u32 s0, 12
	s_waitcnt lgkmcnt(3)
	v_mfma_f32_16x16x32_bf16 v[118:121], v[170:173], v[188:191], v[118:121]
	v_mfma_f32_16x16x32_bf16 v[106:109], v[170:173], v[192:195], v[106:109]
	v_mfma_f32_16x16x32_bf16 v[98:101], v[170:173], v[196:199], v[98:101]
	v_mfma_f32_16x16x32_bf16 v[90:93], v[170:173], v[200:203], v[90:93]
	ds_read_b128 v[230:233], v160
	ds_read_b128 v[204:207], v161 offset:16384
	ds_read_b128 v[208:211], v161 offset:18432
	ds_read_b128 v[216:219], v161 offset:20480
	ds_read_b128 v[220:223], v161 offset:22528
	s_waitcnt lgkmcnt(7)
	v_mfma_f32_16x16x32_bf16 v[94:97], v[174:177], v[188:191], v[94:97]
	v_mfma_f32_16x16x32_bf16 v[114:117], v[174:177], v[192:195], v[114:117]
	v_mfma_f32_16x16x32_bf16 v[110:113], v[174:177], v[196:199], v[110:113]
	v_mfma_f32_16x16x32_bf16 v[102:105], v[174:177], v[200:203], v[102:105]
	s_waitcnt lgkmcnt(6)
	v_mfma_f32_16x16x32_bf16 v[122:125], v[178:181], v[188:191], v[122:125]
	v_mfma_f32_16x16x32_bf16 v[126:129], v[178:181], v[192:195], v[126:129]
	v_mfma_f32_16x16x32_bf16 v[86:89], v[178:181], v[196:199], v[86:89]
	v_mfma_f32_16x16x32_bf16 v[82:85], v[178:181], v[200:203], v[82:85]
	ds_read_b128 v[242:245], v160 offset:2048
	ds_read_b128 v[234:237], v160 offset:4096
	ds_read_b128 v[238:241], v160 offset:6144
	s_waitcnt lgkmcnt(8)
	v_mfma_f32_16x16x32_bf16 v[74:77], v[182:185], v[188:191], v[74:77]
	v_mfma_f32_16x16x32_bf16 v[70:73], v[182:185], v[192:195], v[70:73]
	v_mfma_f32_16x16x32_bf16 v[66:69], v[182:185], v[196:199], v[66:69]
	v_mfma_f32_16x16x32_bf16 v[78:81], v[182:185], v[200:203], v[78:81]
	s_waitcnt lgkmcnt(3)
	v_mfma_f32_16x16x32_bf16 v[118:121], v[230:233], v[204:207], v[118:121]
	s_waitcnt vmcnt(8)
	ds_write_b128 v163, v[2:5] offset:32768
	ds_write_b128 v163, v[26:29] offset:36864
	ds_write_b128 v163, v[22:25] offset:40960
	ds_write_b128 v163, v[18:21] offset:45056
	v_mfma_f32_16x16x32_bf16 v[106:109], v[230:233], v[208:211], v[106:109]
	ds_write_b128 v163, v[6:9] offset:49152
	ds_write_b128 v163, v[14:17] offset:53248
	ds_write_b128 v163, v[10:13] offset:57344
	v_lshl_add_u64 v[6:7], v[154:155], 0, v[0:1]
	v_mfma_f32_16x16x32_bf16 v[98:101], v[230:233], v[216:219], v[98:101]
	v_add_co_u32_e32 v12, vcc, s15, v6
	v_lshl_add_u64 v[10:11], v[152:153], 0, v[0:1]
	s_nop 0
	v_addc_co_u32_e32 v13, vcc, 0, v7, vcc
	v_add_co_u32_e32 v14, vcc, s16, v6
	v_mfma_f32_16x16x32_bf16 v[90:93], v[230:233], v[220:223], v[90:93]
	ds_write_b128 v163, v[30:33] offset:61440
	s_nop 0
	v_addc_co_u32_e32 v15, vcc, 0, v7, vcc
	v_add_co_u32_e32 v16, vcc, s17, v6
	v_addc_co_u32_e32 v17, vcc, 0, v7, vcc
	s_waitcnt lgkmcnt(10)
	v_mfma_f32_16x16x32_bf16 v[94:97], v[242:245], v[204:207], v[94:97]
	v_add_co_u32_e32 v30, vcc, s15, v10
	v_addc_co_u32_e32 v31, vcc, 0, v11, vcc
	v_add_co_u32_e32 v32, vcc, s16, v10
	v_addc_co_u32_e32 v33, vcc, 0, v11, vcc
	v_mfma_f32_16x16x32_bf16 v[114:117], v[242:245], v[208:211], v[114:117]
	global_load_dwordx4 v[2:5], v[6:7], off offset:384
	v_add_co_u32_e32 v166, vcc, s17, v10
	global_load_dwordx4 v[6:9], v[10:11], off offset:384
	s_nop 0
	v_addc_co_u32_e32 v167, vcc, 0, v11, vcc
	v_mfma_f32_16x16x32_bf16 v[110:113], v[242:245], v[216:219], v[110:113]
	global_load_dwordx4 v[26:29], v[12:13], off offset:384
	global_load_dwordx4 v[22:25], v[14:15], off offset:384
	global_load_dwordx4 v[18:21], v[16:17], off offset:384
	s_nop 0
	global_load_dwordx4 v[14:17], v[30:31], off offset:384
	v_mfma_f32_16x16x32_bf16 v[102:105], v[242:245], v[220:223], v[102:105]
	global_load_dwordx4 v[10:13], v[32:33], off offset:384
	s_nop 0
	global_load_dwordx4 v[30:33], v[166:167], off offset:384
	s_waitcnt lgkmcnt(0)
	s_barrier
	ds_read_b128 v[170:173], v162 offset:32768
	ds_read_b128 v[188:191], v164 offset:49152
	ds_read_b128 v[192:195], v164 offset:51200
	ds_read_b128 v[196:199], v164 offset:53248
	ds_read_b128 v[200:203], v164 offset:55296
	ds_read_b128 v[174:177], v162 offset:34816
	ds_read_b128 v[178:181], v162 offset:36864
	ds_read_b128 v[182:185], v162 offset:38912
	v_mfma_f32_16x16x32_bf16 v[122:125], v[234:237], v[204:207], v[122:125]
	v_mfma_f32_16x16x32_bf16 v[126:129], v[234:237], v[208:211], v[126:129]
	v_mfma_f32_16x16x32_bf16 v[86:89], v[234:237], v[216:219], v[86:89]
	v_mfma_f32_16x16x32_bf16 v[82:85], v[234:237], v[220:223], v[82:85]
	v_mfma_f32_16x16x32_bf16 v[74:77], v[238:241], v[204:207], v[74:77]
	v_mfma_f32_16x16x32_bf16 v[70:73], v[238:241], v[208:211], v[70:73]
	v_mfma_f32_16x16x32_bf16 v[66:69], v[238:241], v[216:219], v[66:69]
	v_mfma_f32_16x16x32_bf16 v[78:81], v[238:241], v[220:223], v[78:81]
	s_waitcnt lgkmcnt(3)
	v_mfma_f32_16x16x32_bf16 v[118:121], v[170:173], v[188:191], v[118:121]
	v_mfma_f32_16x16x32_bf16 v[106:109], v[170:173], v[192:195], v[106:109]
	v_mfma_f32_16x16x32_bf16 v[98:101], v[170:173], v[196:199], v[98:101]
	v_mfma_f32_16x16x32_bf16 v[90:93], v[170:173], v[200:203], v[90:93]
	ds_read_b128 v[230:233], v160 offset:32768
	ds_read_b128 v[204:207], v161 offset:49152
	ds_read_b128 v[208:211], v161 offset:51200
	ds_read_b128 v[216:219], v161 offset:53248
	ds_read_b128 v[220:223], v161 offset:55296
	s_waitcnt lgkmcnt(7)
	v_mfma_f32_16x16x32_bf16 v[94:97], v[174:177], v[188:191], v[94:97]
	v_mfma_f32_16x16x32_bf16 v[114:117], v[174:177], v[192:195], v[114:117]
	v_mfma_f32_16x16x32_bf16 v[110:113], v[174:177], v[196:199], v[110:113]
	v_mfma_f32_16x16x32_bf16 v[102:105], v[174:177], v[200:203], v[102:105]
	s_waitcnt lgkmcnt(6)
; template <int NT, bool BKN, bool MASK = false, bool ROWSS = false, class Epi> ...
;     ...
;   for (int kt = 0; kt < nk - 2; kt += 2) {
;     GEMM_COMPUTE(0);
;     GEMM_STORE(ra1, rb1, 1);
;     GEMM_LOAD(ra1, rb1, kt + 3);
;     __syncthreads();
;     GEMM_COMPUTE(1);
;     GEMM_STORE(ra0, rb0, 0);
;     GEMM_LOAD(ra0, rb0, (kt + 4 < nkm1 ? kt + 4 : nkm1));
;     __syncthreads();
;   }
;   GEMM_COMPUTE(0);
;   GEMM_STORE(ra1, rb1, 1);
;   __syncthreads();
;   GEMM_COMPUTE(1);
	v_mfma_f32_16x16x32_bf16 v[122:125], v[178:181], v[188:191], v[122:125]
	v_mfma_f32_16x16x32_bf16 v[126:129], v[178:181], v[192:195], v[126:129]
	v_mfma_f32_16x16x32_bf16 v[86:89], v[178:181], v[196:199], v[86:89]
	v_mfma_f32_16x16x32_bf16 v[82:85], v[178:181], v[200:203], v[82:85]
	ds_read_b128 v[242:245], v160 offset:34816
	ds_read_b128 v[234:237], v160 offset:36864
	ds_read_b128 v[238:241], v160 offset:38912
	s_waitcnt lgkmcnt(8)
	v_mfma_f32_16x16x32_bf16 v[74:77], v[182:185], v[188:191], v[74:77]
	v_mfma_f32_16x16x32_bf16 v[70:73], v[182:185], v[192:195], v[70:73]
	v_mfma_f32_16x16x32_bf16 v[66:69], v[182:185], v[196:199], v[66:69]
	v_mfma_f32_16x16x32_bf16 v[78:81], v[182:185], v[200:203], v[78:81]
	s_waitcnt lgkmcnt(3)
	v_mfma_f32_16x16x32_bf16 v[118:121], v[230:233], v[204:207], v[118:121]
	v_lshl_add_u64 v[152:153], v[152:153], 0, s[6:7]
	v_lshl_add_u64 v[154:155], v[154:155], 0, s[6:7]
	s_waitcnt vmcnt(8)
	ds_write_b128 v163, v[34:37]
	ds_write_b128 v163, v[38:41] offset:4096
	v_mfma_f32_16x16x32_bf16 v[106:109], v[230:233], v[208:211], v[106:109]
	ds_write_b128 v163, v[46:49] offset:8192
	ds_write_b128 v163, v[42:45] offset:12288
	ds_write_b128 v163, v[50:53] offset:16384
	ds_write_b128 v163, v[58:61] offset:20480
	v_mfma_f32_16x16x32_bf16 v[98:101], v[230:233], v[216:219], v[98:101]
	ds_write_b128 v163, v[54:57] offset:24576
	ds_write_b128 v163, v[62:65] offset:28672
	v_lshl_add_u64 v[34:35], v[136:137], 0, s[94:95]
	v_lshl_add_u64 v[38:39], v[138:139], 0, s[94:95]
	v_mfma_f32_16x16x32_bf16 v[90:93], v[230:233], v[220:223], v[90:93]
	v_lshl_add_u64 v[42:43], v[140:141], 0, s[94:95]
	v_lshl_add_u64 v[44:45], v[142:143], 0, s[94:95]
	v_lshl_add_u64 v[50:51], v[144:145], 0, s[94:95]
	v_lshl_add_u64 v[54:55], v[146:147], 0, s[94:95]
	s_waitcnt lgkmcnt(10)
	v_mfma_f32_16x16x32_bf16 v[94:97], v[242:245], v[204:207], v[94:97]
	v_lshl_add_u64 v[56:57], v[148:149], 0, s[94:95]
	v_lshl_add_u64 v[62:63], v[150:151], 0, s[94:95]
	global_load_dwordx4 v[34:37], v[34:35], off offset:512
	s_nop 0
	global_load_dwordx4 v[38:41], v[38:39], off offset:512
	v_mfma_f32_16x16x32_bf16 v[114:117], v[242:245], v[208:211], v[114:117]
	s_nop 0
	global_load_dwordx4 v[46:49], v[42:43], off offset:512
	s_nop 0
	global_load_dwordx4 v[42:45], v[44:45], off offset:512
	s_nop 0
	global_load_dwordx4 v[50:53], v[50:51], off offset:512
	s_nop 0
	global_load_dwordx4 v[58:61], v[54:55], off offset:512
	v_mfma_f32_16x16x32_bf16 v[110:113], v[242:245], v[216:219], v[110:113]
	s_nop 0
	global_load_dwordx4 v[54:57], v[56:57], off offset:512
	global_load_dwordx4 v[62:65], v[62:63], off offset:512
	v_mfma_f32_16x16x32_bf16 v[102:105], v[242:245], v[220:223], v[102:105]
	s_waitcnt lgkmcnt(0)
	s_barrier
	ds_read_b128 v[170:173], v162
	ds_read_b128 v[188:191], v164 offset:16384
	ds_read_b128 v[192:195], v164 offset:18432
	ds_read_b128 v[196:199], v164 offset:20480
	ds_read_b128 v[200:203], v164 offset:22528
	ds_read_b128 v[174:177], v162 offset:2048
	ds_read_b128 v[178:181], v162 offset:4096
	ds_read_b128 v[182:185], v162 offset:6144
	v_mfma_f32_16x16x32_bf16 v[122:125], v[234:237], v[204:207], v[122:125]
	v_mfma_f32_16x16x32_bf16 v[126:129], v[234:237], v[208:211], v[126:129]
	v_mfma_f32_16x16x32_bf16 v[86:89], v[234:237], v[216:219], v[86:89]
	v_mfma_f32_16x16x32_bf16 v[82:85], v[234:237], v[220:223], v[82:85]
	v_mfma_f32_16x16x32_bf16 v[74:77], v[238:241], v[204:207], v[74:77]
	v_mfma_f32_16x16x32_bf16 v[70:73], v[238:241], v[208:211], v[70:73]
	v_mfma_f32_16x16x32_bf16 v[66:69], v[238:241], v[216:219], v[66:69]
	v_mfma_f32_16x16x32_bf16 v[78:81], v[238:241], v[220:223], v[78:81]
	s_cbranch_scc1 .LBB0_244
	s_waitcnt vmcnt(0)
	ds_read_b128 v[34:37], v162
	ds_read_b128 v[38:41], v164 offset:16384
	ds_read_b128 v[46:49], v164 offset:18432
	ds_read_b128 v[54:57], v164 offset:20480
	ds_read_b128 v[62:65], v164 offset:22528
	s_cmp_lt_i32 s40, 4
	s_waitcnt lgkmcnt(3)
	v_mfma_f32_16x16x32_bf16 v[42:45], v[34:37], v[38:41], v[118:121]
	s_cselect_b64 s[0:1], -1, 0
	s_cmp_gt_i32 s40, 3
	s_cselect_b64 s[46:47], -1, 0
	s_waitcnt lgkmcnt(2)
	v_mfma_f32_16x16x32_bf16 v[50:53], v[34:37], v[46:49], v[106:109]
	s_and_b64 vcc, exec, s[46:47]
	s_waitcnt lgkmcnt(1)
	v_mfma_f32_16x16x32_bf16 v[58:61], v[34:37], v[54:57], v[98:101]
	s_waitcnt lgkmcnt(0)
	v_mfma_f32_16x16x32_bf16 v[34:37], v[34:37], v[62:65], v[90:93]
	s_nop 2
	ds_read_b128 v[90:93], v162 offset:2048
	s_waitcnt lgkmcnt(0)
	v_mfma_f32_16x16x32_bf16 v[94:97], v[90:93], v[38:41], v[94:97]
	v_mfma_f32_16x16x32_bf16 v[98:101], v[90:93], v[46:49], v[114:117]
	v_mfma_f32_16x16x32_bf16 v[106:109], v[90:93], v[54:57], v[110:113]
	v_mfma_f32_16x16x32_bf16 v[90:93], v[90:93], v[62:65], v[102:105]
	s_nop 2
	ds_read_b128 v[102:105], v162 offset:4096
	s_waitcnt lgkmcnt(0)
	v_mfma_f32_16x16x32_bf16 v[110:113], v[102:105], v[38:41], v[122:125]
	v_mfma_f32_16x16x32_bf16 v[114:117], v[102:105], v[46:49], v[126:129]
	v_mfma_f32_16x16x32_bf16 v[86:89], v[102:105], v[54:57], v[86:89]
	v_mfma_f32_16x16x32_bf16 v[82:85], v[102:105], v[62:65], v[82:85]
	ds_read_b128 v[102:105], v162 offset:6144
	s_waitcnt lgkmcnt(0)
	v_mfma_f32_16x16x32_bf16 v[54:57], v[102:105], v[54:57], v[66:69]
	s_nop 2
	ds_read_b128 v[66:69], v160
	v_mfma_f32_16x16x32_bf16 v[38:41], v[102:105], v[38:41], v[74:77]
	v_mfma_f32_16x16x32_bf16 v[46:49], v[102:105], v[46:49], v[70:73]
	s_nop 1
	ds_read_b128 v[74:77], v161 offset:18432
	v_mfma_f32_16x16x32_bf16 v[62:65], v[102:105], v[62:65], v[78:81]
	ds_read_b128 v[70:73], v161 offset:16384
	ds_read_b128 v[102:105], v161 offset:22528
	s_nop 0
	ds_read_b128 v[78:81], v161 offset:20480
	s_waitcnt lgkmcnt(2)
	v_mfma_f32_16x16x32_bf16 v[42:45], v[66:69], v[70:73], v[42:45]
	v_mfma_f32_16x16x32_bf16 v[50:53], v[66:69], v[74:77], v[50:53]
	s_waitcnt lgkmcnt(0)
	v_mfma_f32_16x16x32_bf16 v[58:61], v[66:69], v[78:81], v[58:61]
	v_mfma_f32_16x16x32_bf16 v[34:37], v[66:69], v[102:105], v[34:37]
	ds_read_b128 v[66:69], v160 offset:2048
	s_waitcnt lgkmcnt(0)
	v_mfma_f32_16x16x32_bf16 v[94:97], v[66:69], v[70:73], v[94:97]
	v_mfma_f32_16x16x32_bf16 v[98:101], v[66:69], v[74:77], v[98:101]
	v_mfma_f32_16x16x32_bf16 v[106:109], v[66:69], v[78:81], v[106:109]
	v_mfma_f32_16x16x32_bf16 v[66:69], v[66:69], v[102:105], v[90:93]
	s_nop 2
	ds_read_b128 v[90:93], v160 offset:4096
	s_waitcnt lgkmcnt(0)
	v_mfma_f32_16x16x32_bf16 v[110:113], v[90:93], v[70:73], v[110:113]
	v_mfma_f32_16x16x32_bf16 v[114:117], v[90:93], v[74:77], v[114:117]
	v_mfma_f32_16x16x32_bf16 v[86:89], v[90:93], v[78:81], v[86:89]
	v_mfma_f32_16x16x32_bf16 v[82:85], v[90:93], v[102:105], v[82:85]
	ds_read_b128 v[90:93], v160 offset:6144
	ds_write_b128 v163, v[2:5] offset:32768
	ds_write_b128 v163, v[26:29] offset:36864
	ds_write_b128 v163, v[22:25] offset:40960
	ds_write_b128 v163, v[18:21] offset:45056
	ds_write_b128 v163, v[6:9] offset:49152
	ds_write_b128 v163, v[14:17] offset:53248
	ds_write_b128 v163, v[10:13] offset:57344
	ds_write_b128 v163, v[30:33] offset:61440
	s_waitcnt lgkmcnt(0)
	s_barrier
; __device__ __forceinline__ float gelu_tanh(float x) {
;   float y = 0.7978845608028654f * (x + 0.044715f * x * x * x);
;   return x / (1.f + __expf(-2.f * y));
; }
; template <int NT, bool BKN, bool MASK = false, bool ROWSS = false, class Epi> ...
;     ...
;   GEMM_COMPUTE(0);
;   GEMM_STORE(ra1, rb1, 1);
;   __syncthreads();
;   GEMM_COMPUTE(1);
	ds_read_b128 v[2:5], v162 offset:32768
	ds_read_b128 v[10:13], v164 offset:49152
	s_waitcnt lgkmcnt(0)
	v_mfma_f32_16x16x32_bf16 v[14:17], v[2:5], v[10:13], v[42:45]
	ds_read_b128 v[18:21], v164 offset:51200
	ds_read_b128 v[26:29], v164 offset:53248
	s_nop 0
	ds_read_b128 v[42:45], v164 offset:55296
	s_waitcnt lgkmcnt(2)
	v_mfma_f32_16x16x32_bf16 v[22:25], v[2:5], v[18:21], v[50:53]
	s_nop 2
	ds_read_b128 v[50:53], v162 offset:36864
	s_waitcnt lgkmcnt(2)
	v_mfma_f32_16x16x32_bf16 v[30:33], v[2:5], v[26:29], v[58:61]
	s_waitcnt lgkmcnt(1)
	v_mfma_f32_16x16x32_bf16 v[2:5], v[2:5], v[42:45], v[34:37]
	s_nop 2
	ds_read_b128 v[34:37], v162 offset:34816
	v_mfma_f32_16x16x32_bf16 v[38:41], v[90:93], v[70:73], v[38:41]
	v_mfma_f32_16x16x32_bf16 v[46:49], v[90:93], v[74:77], v[46:49]
	v_mfma_f32_16x16x32_bf16 v[54:57], v[90:93], v[78:81], v[54:57]
	v_mfma_f32_16x16x32_bf16 v[6:9], v[90:93], v[102:105], v[62:65]
	s_waitcnt lgkmcnt(0)
	v_mfma_f32_16x16x32_bf16 v[70:73], v[34:37], v[10:13], v[94:97]
	v_mfma_f32_16x16x32_bf16 v[74:77], v[34:37], v[18:21], v[98:101]
	v_mfma_f32_16x16x32_bf16 v[78:81], v[34:37], v[26:29], v[106:109]
	v_mfma_f32_16x16x32_bf16 v[34:37], v[34:37], v[42:45], v[66:69]
	s_nop 1
	ds_read_b128 v[106:109], v161 offset:51200
	v_mfma_f32_16x16x32_bf16 v[66:69], v[50:53], v[10:13], v[110:113]
	v_mfma_f32_16x16x32_bf16 v[90:93], v[50:53], v[18:21], v[114:117]
	s_nop 1
	ds_read_b128 v[110:113], v161 offset:53248
	ds_read_b128 v[114:117], v161 offset:55296
	v_mfma_f32_16x16x32_bf16 v[86:89], v[50:53], v[26:29], v[86:89]
	v_mfma_f32_16x16x32_bf16 v[82:85], v[50:53], v[42:45], v[82:85]
	ds_read_b128 v[50:53], v162 offset:38912
	s_waitcnt lgkmcnt(0)
	v_mfma_f32_16x16x32_bf16 v[94:97], v[50:53], v[18:21], v[46:49]
	ds_read_b128 v[18:21], v160 offset:32768
	v_mfma_f32_16x16x32_bf16 v[10:13], v[50:53], v[10:13], v[38:41]
	v_mfma_f32_16x16x32_bf16 v[98:101], v[50:53], v[26:29], v[54:57]
	v_mfma_f32_16x16x32_bf16 v[102:105], v[50:53], v[42:45], v[6:9]
	s_nop 2
	ds_read_b128 v[6:9], v161 offset:49152
	s_waitcnt lgkmcnt(1)
	v_mfma_f32_16x16x32_bf16 v[50:53], v[18:21], v[114:117], v[2:5]
	s_nop 2
	ds_read_b128 v[2:5], v160 offset:34816
	s_waitcnt lgkmcnt(0)
	v_mfma_f32_16x16x32_bf16 v[46:49], v[2:5], v[6:9], v[70:73]
	v_mfma_f32_16x16x32_bf16 v[42:45], v[2:5], v[106:109], v[74:77]
	v_mfma_f32_16x16x32_bf16 v[38:41], v[2:5], v[110:113], v[78:81]
	v_mfma_f32_16x16x32_bf16 v[34:37], v[2:5], v[114:117], v[34:37]
	ds_read_b128 v[2:5], v160 offset:36864
	v_mfma_f32_16x16x32_bf16 v[62:65], v[18:21], v[6:9], v[14:17]
	v_mfma_f32_16x16x32_bf16 v[58:61], v[18:21], v[106:109], v[22:25]
	v_mfma_f32_16x16x32_bf16 v[54:57], v[18:21], v[110:113], v[30:33]
	s_waitcnt lgkmcnt(0)
	v_mfma_f32_16x16x32_bf16 v[30:33], v[2:5], v[6:9], v[66:69]
	v_mfma_f32_16x16x32_bf16 v[26:29], v[2:5], v[106:109], v[90:93]
	s_nop 1
	v_mov_b32_e32 v66, v187
	v_mfma_f32_16x16x32_bf16 v[22:25], v[2:5], v[110:113], v[86:89]
	v_mfma_f32_16x16x32_bf16 v[18:21], v[2:5], v[114:117], v[82:85]
	ds_read_b128 v[2:5], v160 offset:38912
	s_waitcnt lgkmcnt(0)
	v_mfma_f32_16x16x32_bf16 v[14:17], v[2:5], v[6:9], v[10:13]
	s_barrier
	v_mfma_f32_16x16x32_bf16 v[10:13], v[2:5], v[106:109], v[94:97]
	v_mfma_f32_16x16x32_bf16 v[6:9], v[2:5], v[110:113], v[98:101]
	v_mfma_f32_16x16x32_bf16 v[2:5], v[2:5], v[114:117], v[102:105]
	s_cbranch_vccnz .LBB0_247
	v_mul_f32_e32 v0, 0x3d372713, v62
	v_mul_f32_e32 v0, v62, v0
	v_fma_f32 v0, v62, v0, v62
	v_mul_f32_e32 v0, 0x3f4c422a, v0
	v_mul_f32_e32 v0, -2.0, v0
	v_mul_f32_e32 v0, 0x3fb8aa3b, v0
	v_exp_f32_e32 v0, v0
	s_nop 0
	v_add_f32_e32 v0, 1.0, v0
	v_div_scale_f32 v67, s[18:19], v0, v0, v62
	v_rcp_f32_e32 v68, v67
	v_div_scale_f32 v69, vcc, v62, v0, v62
	v_fma_f32 v70, -v67, v68, 1.0
	v_fmac_f32_e32 v68, v70, v68
	v_mul_f32_e32 v70, v69, v68
	v_fma_f32 v71, -v67, v70, v69
	v_fmac_f32_e32 v70, v71, v68
	v_fma_f32 v67, -v67, v70, v69
	v_div_fmas_f32 v67, v67, v68, v70
	v_div_fixup_f32 v62, v67, v0, v62

; #define XCD_FOR(u, T)                                                                                         \
;   for (int _x = bid_() & 7, _gb = gridDim.x >> 3, _hi = (int)(((long)(_x + 1) * (T)) >> 3),                    \
;            u = (int)(((long)_x * (T)) >> 3) + (bid_() >> 3);                                                  \
;        u < _hi; u += _gb)
; template <int NT, bool BKN, bool MASK = false, bool ROWSS = false, class Epi> ...
;     ...
;   float ss_[4] = {0.f, 0.f, 0.f, 0.f};
;   int stk_ = 0;
;   f32x4 acc[4][NT];
; #pragma unroll
;   for (int i = 0; i < 4; ++i)
; #pragma unroll
;     for (int j = 0; j < NT; ++j) acc[i][j] = (f32x4){0.f, 0.f, 0.f, 0.f};
;   const int nk = K >> 6;
;   const int nkm1 = nk - 1;
;   __syncthreads();
;   GEMM_LOAD(ra0, rb0, 0);
;   GEMM_LOAD(ra1, rb1, 1);
;   GEMM_STORE(ra0, rb0, 0);
;   GEMM_LOAD(ra0, rb0, (2 < nkm1 ? 2 : nkm1));
;   __syncthreads();
; __device__ __forceinline__ void phase_out_gemm(const Params& p, int l, bool last, const float* slat, const float* sctx, float* dlat, float* dctx, unsigned char* smem) {
;   const u16* W = p.WoutT + (size_t)l * 1024 * 1024;
;   XCD_FOR(t, 128 * 8) {
;     const int mt = t >> 3, nt = t & 7, row_base = mt * 128;
;     const float* g1 = p.mada + (size_t)(l * 3 + (row_base >> 13)) * 6144 + 2 * 1024 + nt * 128;
;     const float* xs = slat + (size_t)row_base * DM;
;     float* xd = dlat + (size_t)row_base * DM;
;     auto epi = [&](f32x4(&acc)[4][4], int r0, int c0) { epi_staged_residual(acc, r0, c0, smem, g1, xs + nt * 128, xd + nt * 128); };
;     gemm_tile<4, false>(p.YM + (size_t)row_base * 1024, 1024, nullptr, 128, W + (size_t)nt * 128 * 1024, 1024, 1024, smem, epi);
.LBB0_845:
	s_nop 0
	v_mov_b64_e32 v[2:3], s[38:39]
	global_load_dwordx2 v[124:125], v[2:3], off offset:296
	global_load_dwordx2 v[136:137], v[2:3], off offset:184
	v_mov_b32_e32 v159, v187
	s_and_b32 s52, s19, 7
	s_mov_b32 s47, s95
	v_ashrrev_i32_e32 v4, 3, v159
	s_lshl_b32 s46, s52, 18
	v_lshlrev_b32_e32 v123, 4, v159
	v_ashrrev_i32_e32 v5, 31, v4
	v_lshl_add_u64 v[2:3], v[130:131], 0, s[46:47]
	v_and_b32_e32 v0, 0x70, v123
	v_lshlrev_b64 v[154:155], 11, v[4:5]
	s_mov_b64 s[46:47], 0x20000
	s_lshl_b32 s9, s19, 4
	v_lshl_add_u64 v[2:3], v[2:3], 0, v[0:1]
	v_lshl_add_u64 v[8:9], v[154:155], 0, s[46:47]
	s_mov_b64 s[46:47], 0x30000
	s_and_b32 s48, s9, 0xffffff80
	v_lshl_add_u64 v[6:7], v[154:155], 0, s[12:13]
	v_lshl_add_u64 v[22:23], v[154:155], 0, s[46:47]
	v_lshl_add_u64 v[138:139], v[2:3], 0, v[154:155]
	s_waitcnt lgkmcnt(0)
	s_barrier
	s_ashr_i32 s49, s48, 31
	v_lshl_add_u64 v[140:141], v[2:3], 0, v[6:7]
	v_lshl_add_u64 v[142:143], v[2:3], 0, v[8:9]
	v_lshl_add_u64 v[144:145], v[2:3], 0, v[22:23]
	global_load_dwordx4 v[168:171], v[138:139], off
	global_load_dwordx4 v[2:5], v[138:139], off offset:128
	global_load_dwordx4 v[172:175], v[142:143], off
	global_load_dwordx4 v[10:13], v[142:143], off offset:128
	global_load_dwordx4 v[176:179], v[140:141], off
	global_load_dwordx4 v[34:37], v[138:139], off offset:256
	global_load_dwordx4 v[14:17], v[140:141], off offset:128
	global_load_dwordx4 v[38:41], v[140:141], off offset:256
	global_load_dwordx4 v[180:183], v[144:145], off
	global_load_dwordx4 v[42:45], v[142:143], off offset:256
	global_load_dwordx4 v[18:21], v[144:145], off offset:128
	global_load_dwordx4 v[46:49], v[144:145], off offset:256
	s_lshl_b64 s[34:35], s[48:49], 11
	s_and_b32 s1, s50, 7
	s_and_b32 s0, s51, 0xffffff80
	v_and_b32_e32 v162, 15, v159
	v_bfe_u32 v160, v159, 4, 2
	v_bfe_u32 v156, v159, 1, 3
	s_lshl_b32 s94, s1, 18
	s_ashr_i32 s1, s0, 31
	v_bfe_u32 v161, v159, 6, 1
	v_ashrrev_i32_e32 v158, 7, v159
	v_lshlrev_b32_e32 v163, 7, v162
	v_and_b32_e32 v123, 0xffffff80, v123
	v_lshl_or_b32 v164, v158, 13, v163
	v_lshl_or_b32 v184, v161, 13, v163
	v_mov_b32_e32 v78, 0
	v_and_b32_e32 v204, 7, v159
	s_mov_b32 s8, -2
	v_mov_b32_e32 v79, v78
	v_mov_b32_e32 v80, v78
	v_mov_b32_e32 v81, v78
	v_mov_b32_e32 v66, v78
	v_mov_b32_e32 v67, v78
	v_mov_b32_e32 v68, v78
	v_mov_b32_e32 v69, v78
	v_mov_b32_e32 v70, v78
	v_mov_b32_e32 v71, v78
	v_mov_b32_e32 v72, v78
	v_mov_b32_e32 v73, v78
	v_mov_b32_e32 v74, v78
	v_mov_b32_e32 v75, v78
	v_mov_b32_e32 v76, v78
	v_mov_b32_e32 v77, v78
	v_mov_b32_e32 v86, v78
	v_mov_b32_e32 v87, v78
	v_mov_b32_e32 v88, v78
	v_mov_b32_e32 v89, v78
	v_mov_b32_e32 v90, v78
	v_mov_b32_e32 v91, v78
	v_mov_b32_e32 v92, v78
	v_mov_b32_e32 v93, v78
	v_mov_b32_e32 v82, v78
	v_mov_b32_e32 v83, v78
	v_mov_b32_e32 v84, v78
	v_mov_b32_e32 v85, v78
	v_mov_b32_e32 v126, v78
	v_mov_b32_e32 v127, v78
	v_mov_b32_e32 v128, v78
	v_mov_b32_e32 v129, v78
	v_mov_b32_e32 v106, v78
	v_mov_b32_e32 v107, v78
	s_waitcnt vmcnt(0)
	v_lshl_add_u64 v[24:25], v[124:125], 0, s[34:35]
	v_lshl_add_u64 v[24:25], v[24:25], 0, v[0:1]
	v_lshl_add_u64 v[146:147], v[24:25], 0, v[154:155]
	v_lshl_add_u64 v[148:149], v[24:25], 0, v[6:7]
	v_lshl_add_u64 v[150:151], v[24:25], 0, v[8:9]
	v_lshl_add_u64 v[152:153], v[24:25], 0, v[22:23]
	global_load_dwordx4 v[188:191], v[146:147], off
	global_load_dwordx4 v[192:195], v[148:149], off
	global_load_dwordx4 v[196:199], v[150:151], off
	global_load_dwordx4 v[200:203], v[152:153], off
	global_load_dwordx4 v[6:9], v[146:147], off offset:128
	global_load_dwordx4 v[22:25], v[150:151], off offset:128
	global_load_dwordx4 v[50:53], v[146:147], off offset:256
	global_load_dwordx4 v[26:29], v[148:149], off offset:128
	global_load_dwordx4 v[54:57], v[148:149], off offset:256
	global_load_dwordx4 v[58:61], v[150:151], off offset:256
	global_load_dwordx4 v[30:33], v[152:153], off offset:128
	global_load_dwordx4 v[62:65], v[152:153], off offset:256
	v_lshrrev_b32_e32 v0, 4, v159
	v_xor_b32_e32 v157, v0, v159
	v_bitop3_b32 v0, v0, v156, 3 bitop3:0x6c
	v_bitop3_b32 v156, v160, v156, 4 bitop3:0x36
	s_lshl_b64 s[34:35], s[0:1], 11
	v_lshlrev_b32_e32 v157, 4, v157
	v_lshlrev_b32_e32 v0, 4, v0
	v_lshlrev_b32_e32 v156, 4, v156
	v_and_or_b32 v167, v157, s14, v123
	v_or_b32_e32 v165, v0, v164
	v_or_b32_e32 v166, v0, v184
	v_or_b32_e32 v163, v156, v164
	v_or_b32_e32 v164, v156, v184
	v_lshl_add_u64 v[156:157], s[94:95], 0, v[154:155]
	v_lshl_add_u64 v[184:185], v[154:155], 0, s[34:35]
	v_mov_b32_e32 v108, v78
	v_mov_b32_e32 v109, v78
	v_mov_b32_e32 v114, v78
	v_mov_b32_e32 v115, v78
	v_mov_b32_e32 v116, v78
	v_mov_b32_e32 v117, v78
	v_mov_b32_e32 v118, v78
	v_mov_b32_e32 v119, v78
	v_mov_b32_e32 v120, v78
	v_mov_b32_e32 v121, v78
	v_mov_b32_e32 v98, v78
	v_mov_b32_e32 v99, v78
	v_mov_b32_e32 v100, v78
	v_mov_b32_e32 v101, v78
	v_mov_b32_e32 v94, v78
	v_mov_b32_e32 v95, v78
	v_mov_b32_e32 v96, v78
	v_mov_b32_e32 v97, v78
	v_mov_b32_e32 v102, v78
	v_mov_b32_e32 v103, v78
	v_mov_b32_e32 v104, v78
	v_mov_b32_e32 v105, v78
	v_mov_b32_e32 v110, v78
	v_mov_b32_e32 v111, v78
	v_mov_b32_e32 v112, v78
	v_mov_b32_e32 v113, v78
	v_mov_b32_e32 v122, v78
	s_lshl_b64 s[0:1], s[48:49], 10
	v_lshl_add_u64 v[154:155], v[134:135], 0, v[156:157]
	v_lshl_add_u64 v[156:157], v[124:125], 0, v[184:185]
	v_lshlrev_b32_e32 v0, 4, v204
	v_mov_b32_e32 v123, v78
	v_mov_b32_e32 v124, v78
	v_mov_b32_e32 v125, v78
	s_waitcnt lgkmcnt(0)
	ds_write_b128 v167, v[168:171] offset:16384
	ds_write_b128 v167, v[176:179] offset:20480
	ds_write_b128 v167, v[172:175] offset:24576
	ds_write_b128 v167, v[180:183] offset:28672
	s_waitcnt vmcnt(0)
	ds_write_b128 v167, v[188:191]
	ds_write_b128 v167, v[192:195] offset:4096
	ds_write_b128 v167, v[196:199] offset:8192
	ds_write_b128 v167, v[200:203] offset:12288
	s_waitcnt lgkmcnt(0)
	s_barrier
	ds_read_b128 v[168:171], v165
	ds_read_b128 v[188:191], v166 offset:16384
	ds_read_b128 v[192:195], v166 offset:18432
	ds_read_b128 v[196:199], v166 offset:20480
	ds_read_b128 v[200:203], v166 offset:22528
	ds_read_b128 v[172:175], v165 offset:2048
	ds_read_b128 v[176:179], v165 offset:4096
	ds_read_b128 v[180:183], v165 offset:6144
; template <int NT, bool BKN, bool MASK = false, bool ROWSS = false, class Epi> ...
;     ...
;   for (int kt = 0; kt < nk - 2; kt += 2) {
;     GEMM_COMPUTE(0);
;     GEMM_STORE(ra1, rb1, 1);
;     GEMM_LOAD(ra1, rb1, kt + 3);
;     __syncthreads();
;     GEMM_COMPUTE(1);
;     GEMM_STORE(ra0, rb0, 0);
;     GEMM_LOAD(ra0, rb0, (kt + 4 < nkm1 ? kt + 4 : nkm1));
;     __syncthreads();
;   }
.LBB0_846:
	s_add_i32 s8, s8, 2
	s_min_u32 s9, s8, 11
	s_lshl_b32 s94, s9, 7
	s_cmp_lt_u32 s8, 12
	s_waitcnt lgkmcnt(3)
	v_mfma_f32_16x16x32_bf16 v[122:125], v[168:171], v[188:191], v[122:125]
	v_mfma_f32_16x16x32_bf16 v[110:113], v[168:171], v[192:195], v[110:113]
	v_mfma_f32_16x16x32_bf16 v[102:105], v[168:171], v[196:199], v[102:105]
	v_mfma_f32_16x16x32_bf16 v[94:97], v[168:171], v[200:203], v[94:97]
	ds_read_b128 v[236:239], v163
	ds_read_b128 v[204:207], v164 offset:16384
	ds_read_b128 v[208:211], v164 offset:18432
	ds_read_b128 v[216:219], v164 offset:20480
	ds_read_b128 v[220:223], v164 offset:22528
	s_waitcnt lgkmcnt(7)
	v_mfma_f32_16x16x32_bf16 v[98:101], v[172:175], v[188:191], v[98:101]
	v_mfma_f32_16x16x32_bf16 v[118:121], v[172:175], v[192:195], v[118:121]
	v_mfma_f32_16x16x32_bf16 v[114:117], v[172:175], v[196:199], v[114:117]
	v_mfma_f32_16x16x32_bf16 v[106:109], v[172:175], v[200:203], v[106:109]
	s_waitcnt lgkmcnt(6)
	v_mfma_f32_16x16x32_bf16 v[126:129], v[176:179], v[188:191], v[126:129]
	v_mfma_f32_16x16x32_bf16 v[82:85], v[176:179], v[192:195], v[82:85]
	v_mfma_f32_16x16x32_bf16 v[90:93], v[176:179], v[196:199], v[90:93]
	v_mfma_f32_16x16x32_bf16 v[86:89], v[176:179], v[200:203], v[86:89]
	ds_read_b128 v[172:175], v163 offset:2048
	ds_read_b128 v[240:243], v163 offset:4096
	ds_read_b128 v[244:247], v163 offset:6144
	s_waitcnt lgkmcnt(8)
	v_mfma_f32_16x16x32_bf16 v[74:77], v[180:183], v[188:191], v[74:77]
	v_mfma_f32_16x16x32_bf16 v[70:73], v[180:183], v[192:195], v[70:73]
	v_mfma_f32_16x16x32_bf16 v[66:69], v[180:183], v[196:199], v[66:69]
	v_mfma_f32_16x16x32_bf16 v[78:81], v[180:183], v[200:203], v[78:81]
	s_waitcnt lgkmcnt(3)
	v_mfma_f32_16x16x32_bf16 v[122:125], v[236:239], v[204:207], v[122:125]
	s_waitcnt vmcnt(8)
	ds_write_b128 v167, v[6:9] offset:32768
	ds_write_b128 v167, v[26:29] offset:36864
	ds_write_b128 v167, v[22:25] offset:40960
	ds_write_b128 v167, v[30:33] offset:45056
	v_mfma_f32_16x16x32_bf16 v[110:113], v[236:239], v[208:211], v[110:113]
	ds_write_b128 v167, v[2:5] offset:49152
	ds_write_b128 v167, v[14:17] offset:53248
	ds_write_b128 v167, v[10:13] offset:57344
	v_lshl_add_u64 v[2:3], v[156:157], 0, v[0:1]
	v_mfma_f32_16x16x32_bf16 v[102:105], v[236:239], v[216:219], v[102:105]
	v_add_co_u32_e32 v12, vcc, s15, v2
	v_lshl_add_u64 v[10:11], v[154:155], 0, v[0:1]
	s_nop 0
	v_addc_co_u32_e32 v13, vcc, 0, v3, vcc
	v_add_co_u32_e32 v14, vcc, s16, v2
	v_mfma_f32_16x16x32_bf16 v[94:97], v[236:239], v[220:223], v[94:97]
	ds_write_b128 v167, v[18:21] offset:61440
	s_nop 0
	v_addc_co_u32_e32 v15, vcc, 0, v3, vcc
	v_add_co_u32_e32 v16, vcc, s17, v2
	v_addc_co_u32_e32 v17, vcc, 0, v3, vcc
	s_waitcnt lgkmcnt(10)
	v_mfma_f32_16x16x32_bf16 v[98:101], v[172:175], v[204:207], v[98:101]
	v_add_co_u32_e32 v18, vcc, s15, v10
	v_addc_co_u32_e32 v19, vcc, 0, v11, vcc
	v_add_co_u32_e32 v20, vcc, s16, v10
	v_addc_co_u32_e32 v21, vcc, 0, v11, vcc
	v_mfma_f32_16x16x32_bf16 v[118:121], v[172:175], v[208:211], v[118:121]
	global_load_dwordx4 v[6:9], v[2:3], off offset:384
	v_add_co_u32_e32 v184, vcc, s17, v10
	global_load_dwordx4 v[2:5], v[10:11], off offset:384
	s_nop 0
	v_addc_co_u32_e32 v185, vcc, 0, v11, vcc
	v_mfma_f32_16x16x32_bf16 v[114:117], v[172:175], v[216:219], v[114:117]
	global_load_dwordx4 v[26:29], v[12:13], off offset:384
	global_load_dwordx4 v[22:25], v[14:15], off offset:384
	global_load_dwordx4 v[30:33], v[16:17], off offset:384
	s_nop 0
	global_load_dwordx4 v[14:17], v[18:19], off offset:384
	v_mfma_f32_16x16x32_bf16 v[106:109], v[172:175], v[220:223], v[106:109]
	global_load_dwordx4 v[10:13], v[20:21], off offset:384
	s_nop 0
	global_load_dwordx4 v[18:21], v[184:185], off offset:384
	s_waitcnt lgkmcnt(0)
	s_barrier
	ds_read_b128 v[168:171], v165 offset:32768
	ds_read_b128 v[188:191], v166 offset:49152
	ds_read_b128 v[192:195], v166 offset:51200
	ds_read_b128 v[196:199], v166 offset:53248
	ds_read_b128 v[200:203], v166 offset:55296
	ds_read_b128 v[172:175], v165 offset:34816
	ds_read_b128 v[176:179], v165 offset:36864
	ds_read_b128 v[180:183], v165 offset:38912
	v_mfma_f32_16x16x32_bf16 v[126:129], v[240:243], v[204:207], v[126:129]
	v_mfma_f32_16x16x32_bf16 v[82:85], v[240:243], v[208:211], v[82:85]
	v_mfma_f32_16x16x32_bf16 v[90:93], v[240:243], v[216:219], v[90:93]
	v_mfma_f32_16x16x32_bf16 v[86:89], v[240:243], v[220:223], v[86:89]
	v_mfma_f32_16x16x32_bf16 v[74:77], v[244:247], v[204:207], v[74:77]
	v_mfma_f32_16x16x32_bf16 v[70:73], v[244:247], v[208:211], v[70:73]
	v_mfma_f32_16x16x32_bf16 v[66:69], v[244:247], v[216:219], v[66:69]
	v_mfma_f32_16x16x32_bf16 v[78:81], v[244:247], v[220:223], v[78:81]
	s_waitcnt lgkmcnt(3)
	v_mfma_f32_16x16x32_bf16 v[122:125], v[168:171], v[188:191], v[122:125]
	v_mfma_f32_16x16x32_bf16 v[110:113], v[168:171], v[192:195], v[110:113]
	v_mfma_f32_16x16x32_bf16 v[102:105], v[168:171], v[196:199], v[102:105]
	v_mfma_f32_16x16x32_bf16 v[94:97], v[168:171], v[200:203], v[94:97]
	ds_read_b128 v[236:239], v163 offset:32768
	ds_read_b128 v[204:207], v164 offset:49152
	ds_read_b128 v[208:211], v164 offset:51200
	ds_read_b128 v[216:219], v164 offset:53248
	ds_read_b128 v[220:223], v164 offset:55296
	s_waitcnt lgkmcnt(7)
	v_mfma_f32_16x16x32_bf16 v[98:101], v[172:175], v[188:191], v[98:101]
	v_mfma_f32_16x16x32_bf16 v[118:121], v[172:175], v[192:195], v[118:121]
	v_mfma_f32_16x16x32_bf16 v[114:117], v[172:175], v[196:199], v[114:117]
	v_mfma_f32_16x16x32_bf16 v[106:109], v[172:175], v[200:203], v[106:109]
	s_waitcnt lgkmcnt(6)
; template <int NT, bool BKN, bool MASK = false, bool ROWSS = false, class Epi> ...
;     ...
;   for (int kt = 0; kt < nk - 2; kt += 2) {
;     GEMM_COMPUTE(0);
;     GEMM_STORE(ra1, rb1, 1);
;     GEMM_LOAD(ra1, rb1, kt + 3);
;     __syncthreads();
;     GEMM_COMPUTE(1);
;     GEMM_STORE(ra0, rb0, 0);
;     GEMM_LOAD(ra0, rb0, (kt + 4 < nkm1 ? kt + 4 : nkm1));
;     __syncthreads();
;   }
	v_mfma_f32_16x16x32_bf16 v[126:129], v[176:179], v[188:191], v[126:129]
	v_mfma_f32_16x16x32_bf16 v[82:85], v[176:179], v[192:195], v[82:85]
	v_mfma_f32_16x16x32_bf16 v[90:93], v[176:179], v[196:199], v[90:93]
	v_mfma_f32_16x16x32_bf16 v[86:89], v[176:179], v[200:203], v[86:89]
	ds_read_b128 v[172:175], v163 offset:34816
	ds_read_b128 v[240:243], v163 offset:36864
	ds_read_b128 v[244:247], v163 offset:38912
	s_waitcnt lgkmcnt(8)
	v_mfma_f32_16x16x32_bf16 v[74:77], v[180:183], v[188:191], v[74:77]
	v_mfma_f32_16x16x32_bf16 v[70:73], v[180:183], v[192:195], v[70:73]
	v_mfma_f32_16x16x32_bf16 v[66:69], v[180:183], v[196:199], v[66:69]
	v_mfma_f32_16x16x32_bf16 v[78:81], v[180:183], v[200:203], v[78:81]
	s_waitcnt lgkmcnt(3)
	v_mfma_f32_16x16x32_bf16 v[122:125], v[236:239], v[204:207], v[122:125]
	v_lshl_add_u64 v[154:155], v[154:155], 0, s[6:7]
	v_lshl_add_u64 v[156:157], v[156:157], 0, s[6:7]
	s_waitcnt vmcnt(8)
	ds_write_b128 v167, v[50:53]
	ds_write_b128 v167, v[54:57] offset:4096
	v_mfma_f32_16x16x32_bf16 v[110:113], v[236:239], v[208:211], v[110:113]
	ds_write_b128 v167, v[58:61] offset:8192
	ds_write_b128 v167, v[62:65] offset:12288
	ds_write_b128 v167, v[34:37] offset:16384
	ds_write_b128 v167, v[38:41] offset:20480
	v_mfma_f32_16x16x32_bf16 v[102:105], v[236:239], v[216:219], v[102:105]
	ds_write_b128 v167, v[42:45] offset:24576
	ds_write_b128 v167, v[46:49] offset:28672
	v_lshl_add_u64 v[34:35], v[146:147], 0, s[94:95]
	v_lshl_add_u64 v[36:37], v[148:149], 0, s[94:95]
	v_mfma_f32_16x16x32_bf16 v[94:97], v[236:239], v[220:223], v[94:97]
	v_lshl_add_u64 v[38:39], v[150:151], 0, s[94:95]
	v_lshl_add_u64 v[40:41], v[152:153], 0, s[94:95]
	v_lshl_add_u64 v[42:43], v[138:139], 0, s[94:95]
	v_lshl_add_u64 v[44:45], v[140:141], 0, s[94:95]
	s_waitcnt lgkmcnt(10)
	v_mfma_f32_16x16x32_bf16 v[98:101], v[172:175], v[204:207], v[98:101]
	v_lshl_add_u64 v[46:47], v[142:143], 0, s[94:95]
	v_lshl_add_u64 v[48:49], v[144:145], 0, s[94:95]
	global_load_dwordx4 v[50:53], v[34:35], off offset:512
	global_load_dwordx4 v[54:57], v[36:37], off offset:512
	v_mfma_f32_16x16x32_bf16 v[118:121], v[172:175], v[208:211], v[118:121]
	global_load_dwordx4 v[58:61], v[38:39], off offset:512
	global_load_dwordx4 v[62:65], v[40:41], off offset:512
	s_nop 0
	global_load_dwordx4 v[34:37], v[42:43], off offset:512
	global_load_dwordx4 v[38:41], v[44:45], off offset:512
	v_mfma_f32_16x16x32_bf16 v[114:117], v[172:175], v[216:219], v[114:117]
	s_nop 0
	global_load_dwordx4 v[42:45], v[46:47], off offset:512
	global_load_dwordx4 v[46:49], v[48:49], off offset:512
	v_mfma_f32_16x16x32_bf16 v[106:109], v[172:175], v[220:223], v[106:109]
	s_waitcnt lgkmcnt(0)
	s_barrier
	ds_read_b128 v[168:171], v165
	ds_read_b128 v[188:191], v166 offset:16384
	ds_read_b128 v[192:195], v166 offset:18432
	ds_read_b128 v[196:199], v166 offset:20480
	ds_read_b128 v[200:203], v166 offset:22528
	ds_read_b128 v[172:175], v165 offset:2048
	ds_read_b128 v[176:179], v165 offset:4096
	ds_read_b128 v[180:183], v165 offset:6144
	v_mfma_f32_16x16x32_bf16 v[126:129], v[240:243], v[204:207], v[126:129]
	v_mfma_f32_16x16x32_bf16 v[82:85], v[240:243], v[208:211], v[82:85]
	v_mfma_f32_16x16x32_bf16 v[90:93], v[240:243], v[216:219], v[90:93]
	v_mfma_f32_16x16x32_bf16 v[86:89], v[240:243], v[220:223], v[86:89]
	v_mfma_f32_16x16x32_bf16 v[74:77], v[244:247], v[204:207], v[74:77]
	v_mfma_f32_16x16x32_bf16 v[70:73], v[244:247], v[208:211], v[70:73]
	v_mfma_f32_16x16x32_bf16 v[66:69], v[244:247], v[216:219], v[66:69]
	v_mfma_f32_16x16x32_bf16 v[78:81], v[244:247], v[220:223], v[78:81]
	s_cbranch_scc1 .LBB0_846
	s_waitcnt vmcnt(0)
	ds_read_b128 v[34:37], v165
	ds_read_b128 v[38:41], v166 offset:16384
	ds_read_b128 v[46:49], v166 offset:18432
	ds_read_b128 v[54:57], v166 offset:20480
	ds_read_b128 v[62:65], v166 offset:22528
	s_ashr_i32 s8, s19, 9
	s_waitcnt lgkmcnt(3)
	v_mfma_f32_16x16x32_bf16 v[42:45], v[34:37], v[38:41], v[122:125]
	s_mul_i32 s9, s36, 3
	s_add_i32 s8, s8, s9
	v_mov_b32_e32 v0, 0x6000
	s_waitcnt lgkmcnt(2)
	v_mfma_f32_16x16x32_bf16 v[50:53], v[34:37], v[46:49], v[110:113]
	s_lshl_b32 s94, s52, 9
	s_waitcnt lgkmcnt(1)
	v_mfma_f32_16x16x32_bf16 v[58:61], v[34:37], v[54:57], v[102:105]
	s_waitcnt lgkmcnt(0)
	v_mfma_f32_16x16x32_bf16 v[34:37], v[34:37], v[62:65], v[94:97]
	s_nop 2
	ds_read_b128 v[94:97], v165 offset:2048
	s_waitcnt lgkmcnt(0)
	v_mfma_f32_16x16x32_bf16 v[98:101], v[94:97], v[38:41], v[98:101]
	v_mfma_f32_16x16x32_bf16 v[102:105], v[94:97], v[46:49], v[118:121]
	v_mfma_f32_16x16x32_bf16 v[110:113], v[94:97], v[54:57], v[114:117]
	v_mfma_f32_16x16x32_bf16 v[94:97], v[94:97], v[62:65], v[106:109]
	s_nop 2
	ds_read_b128 v[106:109], v165 offset:4096
	s_waitcnt lgkmcnt(0)
	v_mfma_f32_16x16x32_bf16 v[114:117], v[106:109], v[38:41], v[126:129]
	v_mfma_f32_16x16x32_bf16 v[82:85], v[106:109], v[46:49], v[82:85]
	v_mfma_f32_16x16x32_bf16 v[90:93], v[106:109], v[54:57], v[90:93]
	v_mfma_f32_16x16x32_bf16 v[86:89], v[106:109], v[62:65], v[86:89]
	ds_read_b128 v[106:109], v165 offset:6144
	s_waitcnt lgkmcnt(0)
	v_mfma_f32_16x16x32_bf16 v[54:57], v[106:109], v[54:57], v[66:69]
	s_nop 2
	ds_read_b128 v[66:69], v163
	v_mfma_f32_16x16x32_bf16 v[38:41], v[106:109], v[38:41], v[74:77]
	v_mfma_f32_16x16x32_bf16 v[46:49], v[106:109], v[46:49], v[70:73]
	s_nop 1
	ds_read_b128 v[74:77], v164 offset:18432
	v_mfma_f32_16x16x32_bf16 v[62:65], v[106:109], v[62:65], v[78:81]
	ds_read_b128 v[70:73], v164 offset:16384
	ds_read_b128 v[106:109], v164 offset:22528
	s_nop 0
	ds_read_b128 v[78:81], v164 offset:20480
	s_waitcnt lgkmcnt(2)
	v_mfma_f32_16x16x32_bf16 v[42:45], v[66:69], v[70:73], v[42:45]
	v_mfma_f32_16x16x32_bf16 v[50:53], v[66:69], v[74:77], v[50:53]
	s_waitcnt lgkmcnt(0)
	v_mfma_f32_16x16x32_bf16 v[58:61], v[66:69], v[78:81], v[58:61]
	v_mfma_f32_16x16x32_bf16 v[34:37], v[66:69], v[106:109], v[34:37]
	ds_read_b128 v[66:69], v163 offset:2048
	s_waitcnt lgkmcnt(0)
	v_mfma_f32_16x16x32_bf16 v[98:101], v[66:69], v[70:73], v[98:101]
	v_mfma_f32_16x16x32_bf16 v[102:105], v[66:69], v[74:77], v[102:105]
	v_mfma_f32_16x16x32_bf16 v[110:113], v[66:69], v[78:81], v[110:113]
	v_mfma_f32_16x16x32_bf16 v[66:69], v[66:69], v[106:109], v[94:97]
	s_nop 2
	ds_read_b128 v[94:97], v163 offset:4096
	s_waitcnt lgkmcnt(0)
	v_mfma_f32_16x16x32_bf16 v[114:117], v[94:97], v[70:73], v[114:117]
	v_mfma_f32_16x16x32_bf16 v[82:85], v[94:97], v[74:77], v[82:85]
	v_mfma_f32_16x16x32_bf16 v[90:93], v[94:97], v[78:81], v[90:93]
	v_mfma_f32_16x16x32_bf16 v[86:89], v[94:97], v[106:109], v[86:89]
	ds_read_b128 v[94:97], v163 offset:6144
	ds_write_b128 v167, v[6:9] offset:32768
	ds_write_b128 v167, v[26:29] offset:36864
	ds_write_b128 v167, v[22:25] offset:40960
	ds_write_b128 v167, v[30:33] offset:45056
	ds_write_b128 v167, v[2:5] offset:49152
	ds_write_b128 v167, v[14:17] offset:53248
	ds_write_b128 v167, v[10:13] offset:57344
	ds_write_b128 v167, v[18:21] offset:61440
	s_waitcnt lgkmcnt(0)
	s_barrier
; __device__ __forceinline__ int tid_() { int t = threadIdx.x; asm volatile("" : "+v"(t)); return t; }
; template <int NT, bool BKN, bool MASK = false, bool ROWSS = false, class Epi> ...
;     ...
;   GEMM_COMPUTE(0);
;   GEMM_STORE(ra1, rb1, 1);
;   __syncthreads();
;   GEMM_COMPUTE(1);
; __device__ __forceinline__ void epi_staged_residual(f32x4 (&acc)[4][4], int r0, int c0, unsigned char* smem, const float* __restrict__ g,
;                                                     const float* __restrict__ xs, float* __restrict__ xd) {
;   constexpr int PITCH = 132;
;   float* Ts = (float*)smem;
;   const int t = tid_();
;   const int wr = r0 >> 6;
; #pragma unroll
;   for (int pass = 0; pass < 2; ++pass) {
;     __syncthreads();
;     if (wr == pass) {
; #pragma unroll
;       for (int mi = 0; mi < 4; ++mi)
; #pragma unroll
;         for (int ni = 0; ni < 4; ++ni)
; #pragma unroll
;           for (int j = 0; j < 4; ++j) Ts[((r0 & 63) + mi * 16 + j) * PITCH + c0 + ni * 16] = acc[mi][ni][j];
;     }
	ds_read_b128 v[2:5], v165 offset:32768
	ds_read_b128 v[10:13], v166 offset:49152
	s_waitcnt lgkmcnt(0)
	v_mfma_f32_16x16x32_bf16 v[14:17], v[2:5], v[10:13], v[42:45]
	ds_read_b128 v[18:21], v166 offset:51200
	ds_read_b128 v[26:29], v166 offset:53248
	s_nop 0
	ds_read_b128 v[42:45], v166 offset:55296
	s_waitcnt lgkmcnt(2)
	v_mfma_f32_16x16x32_bf16 v[22:25], v[2:5], v[18:21], v[50:53]
	s_waitcnt lgkmcnt(1)
	v_mfma_f32_16x16x32_bf16 v[30:33], v[2:5], v[26:29], v[58:61]
	s_waitcnt lgkmcnt(0)
	v_mfma_f32_16x16x32_bf16 v[2:5], v[2:5], v[42:45], v[34:37]
	s_nop 2
	ds_read_b128 v[34:37], v165 offset:34816
	v_mfma_f32_16x16x32_bf16 v[6:9], v[94:97], v[106:109], v[62:65]
	ds_read_b128 v[106:109], v164 offset:53248
	s_waitcnt lgkmcnt(1)
	v_mfma_f32_16x16x32_bf16 v[50:53], v[34:37], v[10:13], v[98:101]
	v_mfma_f32_16x16x32_bf16 v[58:61], v[34:37], v[18:21], v[102:105]
	v_mfma_f32_16x16x32_bf16 v[62:65], v[34:37], v[26:29], v[110:113]
	s_nop 1
	ds_read_b128 v[102:105], v164 offset:51200
	v_mfma_f32_16x16x32_bf16 v[34:37], v[34:37], v[42:45], v[66:69]
	ds_read_b128 v[110:113], v164 offset:55296
	s_nop 1
	ds_read_b128 v[66:69], v165 offset:36864
	v_mfma_f32_16x16x32_bf16 v[46:49], v[94:97], v[74:77], v[46:49]
	s_waitcnt lgkmcnt(0)
	v_mfma_f32_16x16x32_bf16 v[74:77], v[66:69], v[18:21], v[82:85]
	s_nop 2
	ds_read_b128 v[82:85], v165 offset:38912
	v_mfma_f32_16x16x32_bf16 v[54:57], v[94:97], v[78:81], v[54:57]
	v_mfma_f32_16x16x32_bf16 v[78:81], v[66:69], v[26:29], v[90:93]
	s_waitcnt lgkmcnt(0)
	v_mfma_f32_16x16x32_bf16 v[90:93], v[82:85], v[18:21], v[46:49]
	ds_read_b128 v[18:21], v163 offset:32768
	v_mfma_f32_16x16x32_bf16 v[38:41], v[94:97], v[70:73], v[38:41]
	v_mfma_f32_16x16x32_bf16 v[94:97], v[82:85], v[26:29], v[54:57]
	s_nop 2
	ds_read_b128 v[54:57], v164 offset:49152
	v_mfma_f32_16x16x32_bf16 v[70:73], v[66:69], v[10:13], v[114:117]
	v_mfma_f32_16x16x32_bf16 v[66:69], v[66:69], v[42:45], v[86:89]
	s_nop 1
	ds_read_b128 v[114:117], v163 offset:38912
	v_mfma_f32_16x16x32_bf16 v[86:89], v[82:85], v[10:13], v[38:41]
	v_mfma_f32_16x16x32_bf16 v[98:101], v[82:85], v[42:45], v[6:9]
	v_mov_b32_e32 v84, v187
	s_waitcnt lgkmcnt(1)
	v_mfma_f32_16x16x32_bf16 v[6:9], v[18:21], v[54:57], v[14:17]
	v_mfma_f32_16x16x32_bf16 v[14:17], v[18:21], v[102:105], v[22:25]
	v_mfma_f32_16x16x32_bf16 v[10:13], v[18:21], v[106:109], v[30:33]
	v_mfma_f32_16x16x32_bf16 v[18:21], v[18:21], v[110:113], v[2:5]
	s_nop 2
	ds_read_b128 v[2:5], v163 offset:34816
	s_waitcnt lgkmcnt(0)
	v_mfma_f32_16x16x32_bf16 v[26:29], v[2:5], v[54:57], v[50:53]
	s_nop 2
	ds_read_b128 v[50:53], v163 offset:36864
	v_mfma_f32_16x16x32_bf16 v[38:41], v[2:5], v[102:105], v[58:61]
	v_mfma_f32_16x16x32_bf16 v[22:25], v[2:5], v[106:109], v[62:65]
	v_mfma_f32_16x16x32_bf16 v[30:33], v[2:5], v[110:113], v[34:37]
	v_mad_i64_i32 v[2:3], s[8:9], s8, v0, v[136:137]
	v_lshlrev_b32_e32 v0, 2, v84
	v_and_b32_e32 v0, 0x7c, v0
	v_lshl_add_u64 v[2:3], v[2:3], 0, s[94:95]
	v_lshlrev_b32_e32 v0, 2, v0
	v_lshl_add_u64 v[2:3], v[2:3], 0, v[0:1]
	v_add_co_u32_e32 v2, vcc, 0x2000, v2
	s_waitcnt lgkmcnt(0)
	v_mfma_f32_16x16x32_bf16 v[34:37], v[50:53], v[54:57], v[70:73]
	v_addc_co_u32_e32 v3, vcc, 0, v3, vcc
	global_load_dwordx4 v[2:5], v[2:3], off
	v_mfma_f32_16x16x32_bf16 v[42:45], v[50:53], v[102:105], v[74:77]
	s_movk_i32 s8, 0x80
	v_cmp_gt_u32_e32 vcc, s8, v159
	s_waitcnt lgkmcnt(0)
	v_mfma_f32_16x16x32_bf16 v[46:49], v[50:53], v[106:109], v[78:81]
	s_barrier
	v_mfma_f32_16x16x32_bf16 v[50:53], v[50:53], v[110:113], v[66:69]
	s_nop 2
	v_mul_u32_u24_e32 v66, 0x210, v160
	v_mfma_f32_16x16x32_bf16 v[54:57], v[114:117], v[54:57], v[86:89]
	v_mfma_f32_16x16x32_bf16 v[58:61], v[114:117], v[102:105], v[90:93]
	s_nop 1
	v_lshlrev_b32_e32 v87, 2, v66
	v_lshl_or_b32 v86, v161, 6, v162
	v_mfma_f32_16x16x32_bf16 v[62:65], v[114:117], v[106:109], v[94:97]
	v_mfma_f32_16x16x32_bf16 v[66:69], v[114:117], v[110:113], v[98:101]
	s_and_saveexec_b64 s[8:9], vcc
	s_cbranch_execz .LBB0_849
	v_lshl_add_u32 v70, v86, 2, v87
	v_add_u32_e32 v71, 0x400, v70
	ds_write2_b32 v70, v6, v14 offset1:16
	ds_write2_b32 v70, v7, v15 offset0:132 offset1:148
	ds_write2_b32 v71, v8, v16 offset0:8 offset1:24
	ds_write2_b32 v71, v9, v17 offset0:140 offset1:156
	ds_write2_b32 v70, v10, v18 offset0:32 offset1:48
	ds_write2_b32 v70, v11, v19 offset0:164 offset1:180
	ds_write2_b32 v71, v12, v20 offset0:40 offset1:56
	ds_write2_b32 v71, v13, v21 offset0:172 offset1:188
	v_add_u32_e32 v71, 0x2000, v70
	v_add_u32_e32 v72, 0x2400, v70
	ds_write2_b32 v71, v26, v38 offset0:64 offset1:80
	ds_write2_b32 v71, v27, v39 offset0:196 offset1:212
	ds_write2_b32 v72, v28, v40 offset0:72 offset1:88
	ds_write2_b32 v72, v29, v41 offset0:204 offset1:220
	ds_write2_b32 v71, v22, v30 offset0:96 offset1:112
	ds_write2_b32 v71, v23, v31 offset0:228 offset1:244
	ds_write2_b32 v72, v24, v32 offset0:104 offset1:120
	ds_write2_b32 v72, v25, v33 offset0:236 offset1:252
	v_add_u32_e32 v71, 0x4000, v70
	v_add_u32_e32 v72, 0x4400, v70
	v_add_u32_e32 v73, 0x4800, v70
	ds_write2_b32 v71, v34, v42 offset0:128 offset1:144
	ds_write2_b32 v72, v35, v43 offset0:4 offset1:20
	ds_write2_b32 v72, v36, v44 offset0:136 offset1:152
	ds_write2_b32 v73, v37, v45 offset0:12 offset1:28
	ds_write2_b32 v71, v46, v50 offset0:160 offset1:176
	ds_write2_b32 v72, v47, v51 offset0:36 offset1:52
	ds_write2_b32 v72, v48, v52 offset0:168 offset1:184
	ds_write2_b32 v73, v49, v53 offset0:44 offset1:60
	v_add_u32_e32 v71, 0x6000, v70
	v_add_u32_e32 v72, 0x6400, v70
	v_add_u32_e32 v70, 0x6800, v70
	ds_write2_b32 v71, v54, v58 offset0:192 offset1:208
	ds_write2_b32 v72, v55, v59 offset0:68 offset1:84
	ds_write2_b32 v72, v56, v60 offset0:200 offset1:216
	ds_write2_b32 v70, v57, v61 offset0:76 offset1:92
	ds_write2_b32 v71, v62, v66 offset0:224 offset1:240
	ds_write2_b32 v72, v63, v67 offset0:100 offset1:116
	ds_write2_b32 v72, v64, v68 offset0:232 offset1:248
	ds_write2_b32 v70, v65, v69 offset0:108 offset1:124

; __device__ __forceinline__ int tid_() { int t = threadIdx.x; asm volatile("" : "+v"(t)); return t; }
; template <int NT, bool BKN, bool MASK = false, bool ROWSS = false, class Epi> ...
;     ...
;   const int t = tid_(), lane = t & 63, wid = t >> 6, wr = wid >> 1, wc = wid & 1, l16 = lane & 15, quad = lane >> 4;
;   const u16* ap[4];
;   const u16* bp[NT];
;   unsigned amask = 0u;
; #pragma unroll
;   for (int i = 0; i < 4; ++i) {
;     const int row = (t >> 3) + 32 * i;
;     const bool v = MASK ? (row < mvalid) : true;
;     amask |= v ? (1u << i) : 0u;
;     int r = v ? row : 0;
;     if (arows) r = arows[r];
;     ap[i] = A + (size_t)r * lda + (t & 7) * 8;
;   }
; #pragma unroll
;   for (int i = 0; i < NT; ++i) {
;     if (!BKN) bp[i] = B + (size_t)((t >> 3) + 32 * i) * ldb + (t & 7) * 8;
;     else { const int c = t + 256 * i; bp[i] = B + (size_t)(c / CPR) * ldb + (c % CPR) * 8; }
;   }
;     ...
;   float ss_[4] = {0.f, 0.f, 0.f, 0.f};
;   int stk_ = 0;
;   f32x4 acc[4][NT];
; #pragma unroll
;   for (int i = 0; i < 4; ++i)
; #pragma unroll
;     for (int j = 0; j < NT; ++j) acc[i][j] = (f32x4){0.f, 0.f, 0.f, 0.f};
;   const int nk = K >> 6;
;   const int nkm1 = nk - 1;
;   __syncthreads();
;   GEMM_LOAD(ra0, rb0, 0);
;   GEMM_LOAD(ra1, rb1, 1);
;   GEMM_STORE(ra0, rb0, 0);
;   GEMM_LOAD(ra0, rb0, (2 < nkm1 ? 2 : nkm1));
;   __syncthreads();
.LBB0_1159:
	s_or_saveexec_b64 s[0:1], s[0:1]
	v_add_u32_e32 v12, 0x60, v66
	v_ashrrev_i32_e32 v13, 31, v12
	s_xor_b64 exec, exec, s[0:1]
	v_mov_b64_e32 v[14:15], v[12:13]
	s_or_b64 exec, exec, s[0:1]
	v_lshlrev_b32_e32 v18, 4, v68
	v_and_b32_e32 v0, 0x70, v18
	s_waitcnt vmcnt(0) lgkmcnt(0)
	v_ashrrev_i32_e32 v5, 31, v4
	v_ashrrev_i32_e32 v3, 31, v2
	v_lshlrev_b64 v[106:107], 11, v[4:5]
	v_lshl_add_u64 v[4:5], v[162:163], 0, v[0:1]
	v_lshlrev_b64 v[2:3], 11, v[2:3]
	v_ashrrev_i32_e32 v7, 31, v6
	v_lshl_add_u64 v[140:141], v[4:5], 0, v[2:3]
	v_lshlrev_b64 v[2:3], 11, v[6:7]
	v_lshl_add_u64 v[142:143], v[4:5], 0, v[2:3]
	v_lshlrev_b64 v[2:3], 11, v[12:13]
	v_lshl_add_u64 v[16:17], v[160:161], 0, v[0:1]
	v_lshlrev_b64 v[110:111], 11, v[66:67]
	v_lshl_add_u64 v[144:145], v[4:5], 0, v[2:3]
	v_lshrrev_b32_e32 v0, 4, v68
	v_and_b32_e32 v162, 15, v68
	v_bfe_u32 v165, v68, 4, 2
	v_bfe_u32 v2, v68, 1, 3
	v_ashrrev_i32_e32 v11, 31, v10
	v_ashrrev_i32_e32 v9, 31, v8
	v_lshl_add_u64 v[138:139], v[4:5], 0, v[110:111]
	v_ashrrev_i32_e32 v164, 7, v68
	v_lshlrev_b32_e32 v3, 7, v68
	v_xor_b32_e32 v4, v0, v68
	v_bitop3_b32 v0, v0, v2, 3 bitop3:0x6c
	v_lshlrev_b32_e32 v6, 7, v162
	v_bitop3_b32 v2, v165, v2, 4 bitop3:0x36
	v_lshlrev_b64 v[102:103], 11, v[10:11]
	v_lshlrev_b64 v[104:105], 11, v[8:9]
	v_lshl_add_u64 v[134:135], v[16:17], 0, v[106:107]
	v_lshlrev_b64 v[108:109], 11, v[14:15]
	v_and_b32_e32 v5, 0xffffff80, v18
	v_lshlrev_b32_e32 v4, 4, v4
	v_lshlrev_b32_e32 v0, 4, v0
	v_lshl_or_b32 v7, v164, 13, v6
	v_and_or_b32 v3, v3, s70, v6
	v_lshlrev_b32_e32 v2, 4, v2
	v_lshl_add_u64 v[130:131], v[16:17], 0, v[102:103]
	v_lshl_add_u64 v[132:133], v[16:17], 0, v[104:105]
	v_lshl_add_u64 v[136:137], v[16:17], 0, v[108:109]
	s_barrier
	global_load_dwordx4 v[70:73], v[134:135], off
	global_load_dwordx4 v[74:77], v[132:133], off
	global_load_dwordx4 v[78:81], v[130:131], off
	global_load_dwordx4 v[82:85], v[136:137], off
	global_load_dwordx4 v[86:89], v[138:139], off
	global_load_dwordx4 v[90:93], v[140:141], off
	global_load_dwordx4 v[94:97], v[142:143], off
	global_load_dwordx4 v[98:101], v[144:145], off
	v_and_or_b32 v170, v4, s14, v5
	v_or_b32_e32 v169, v0, v7
	v_or_b32_e32 v168, v0, v3
	v_or_b32_e32 v167, v2, v7
	v_or_b32_e32 v166, v2, v3
	global_load_dwordx4 v[14:17], v[134:135], off offset:128
	global_load_dwordx4 v[6:9], v[130:131], off offset:128
	global_load_dwordx4 v[2:5], v[138:139], off offset:128
	global_load_dwordx4 v[22:25], v[142:143], off offset:128
	global_load_dwordx4 v[34:37], v[134:135], off offset:256
	global_load_dwordx4 v[10:13], v[132:133], off offset:128
	global_load_dwordx4 v[38:41], v[132:133], off offset:256
	global_load_dwordx4 v[42:45], v[130:131], off offset:256
	global_load_dwordx4 v[18:21], v[136:137], off offset:128
	global_load_dwordx4 v[46:49], v[136:137], off offset:256
	global_load_dwordx4 v[50:53], v[138:139], off offset:256
	global_load_dwordx4 v[30:33], v[140:141], off offset:128
	global_load_dwordx4 v[58:61], v[140:141], off offset:256
	global_load_dwordx4 v[54:57], v[142:143], off offset:256
	global_load_dwordx4 v[26:29], v[144:145], off offset:128
	global_load_dwordx4 v[62:65], v[144:145], off offset:256
	s_add_i32 s94, s18, s9
	s_lshl_b64 s[0:1], s[94:95], 1
	s_add_u32 s0, s0, s8
	v_lshlrev_b64 v[66:67], 11, v[66:67]
	s_addc_u32 s1, s1, 0
	v_lshl_add_u64 v[66:67], s[0:1], 0, v[66:67]
	v_lshl_add_u64 v[146:147], v[158:159], 0, v[66:67]
	v_lshl_add_u64 v[66:67], s[0:1], 0, v[110:111]
	v_lshl_add_u64 v[66:67], v[158:159], 0, v[66:67]
	v_and_b32_e32 v0, 7, v68
	v_lshl_add_u64 v[148:149], v[66:67], 0, s[30:31]
	v_lshl_add_u64 v[66:67], v[160:161], 0, s[30:31]
	v_mov_b32_e32 v118, 0
	v_lshrrev_b32_e32 v163, 6, v68
	v_lshlrev_b32_e32 v0, 4, v0
	v_lshl_add_u64 v[150:151], v[66:67], 0, v[108:109]
	v_lshl_add_u64 v[152:153], v[66:67], 0, v[102:103]
	v_lshl_add_u64 v[154:155], v[66:67], 0, v[104:105]
	v_lshl_add_u64 v[156:157], v[66:67], 0, v[106:107]
	s_mov_b32 s0, -2
	v_mov_b32_e32 v119, v118
	v_mov_b32_e32 v120, v118
	v_mov_b32_e32 v121, v118
	v_mov_b32_e32 v122, v118
	v_mov_b32_e32 v123, v118
	v_mov_b32_e32 v124, v118
	v_mov_b32_e32 v125, v118
	v_mov_b32_e32 v126, v118
	v_mov_b32_e32 v127, v118
	v_mov_b32_e32 v128, v118
	v_mov_b32_e32 v129, v118
	v_mov_b32_e32 v106, v118
	v_mov_b32_e32 v107, v118
	v_mov_b32_e32 v108, v118
	s_waitcnt vmcnt(0) lgkmcnt(0)
	ds_write_b128 v170, v[70:73]
	ds_write_b128 v170, v[74:77] offset:4096
	ds_write_b128 v170, v[78:81] offset:8192
	ds_write_b128 v170, v[82:85] offset:12288
	ds_write_b128 v170, v[86:89] offset:16384
	ds_write_b128 v170, v[90:93] offset:20480
	ds_write_b128 v170, v[94:97] offset:24576
	ds_write_b128 v170, v[98:101] offset:28672
	v_mov_b32_e32 v94, v118
	v_mov_b32_e32 v95, v118
	v_mov_b32_e32 v96, v118
	v_mov_b32_e32 v97, v118
	v_mov_b32_e32 v98, v118
	v_mov_b32_e32 v99, v118
	v_mov_b32_e32 v100, v118
	v_mov_b32_e32 v101, v118
	v_mov_b32_e32 v109, v118
	v_mov_b32_e32 v110, v118
	v_mov_b32_e32 v111, v118
	v_mov_b32_e32 v112, v118
	v_mov_b32_e32 v113, v118
	v_mov_b32_e32 v102, v118
	v_mov_b32_e32 v103, v118
	v_mov_b32_e32 v104, v118
	v_mov_b32_e32 v105, v118
	v_mov_b32_e32 v114, v118
	v_mov_b32_e32 v115, v118
	v_mov_b32_e32 v116, v118
	v_mov_b32_e32 v117, v118
	v_mov_b32_e32 v82, v118
	v_mov_b32_e32 v83, v118
	v_mov_b32_e32 v84, v118
	v_mov_b32_e32 v85, v118
	v_mov_b32_e32 v86, v118
	v_mov_b32_e32 v87, v118
	v_mov_b32_e32 v88, v118
	v_mov_b32_e32 v89, v118
	v_mov_b32_e32 v90, v118
	v_mov_b32_e32 v91, v118
	v_mov_b32_e32 v92, v118
	v_mov_b32_e32 v93, v118
	v_mov_b32_e32 v70, v118
	v_mov_b32_e32 v71, v118
	v_mov_b32_e32 v72, v118
	v_mov_b32_e32 v73, v118
	v_mov_b32_e32 v66, v118
	v_mov_b32_e32 v67, v118
	v_mov_b32_e32 v68, v118
	v_mov_b32_e32 v69, v118
	v_mov_b32_e32 v74, v118
	v_mov_b32_e32 v75, v118
	v_mov_b32_e32 v76, v118
	v_mov_b32_e32 v77, v118
	v_mov_b32_e32 v78, v118
	v_mov_b32_e32 v79, v118
	v_mov_b32_e32 v80, v118
	v_mov_b32_e32 v81, v118
	s_waitcnt lgkmcnt(0)
	s_barrier
	ds_read_b128 v[158:161], v169
	ds_read_b128 v[188:191], v168 offset:16384
	ds_read_b128 v[192:195], v168 offset:18432
	ds_read_b128 v[196:199], v168 offset:20480
	ds_read_b128 v[200:203], v168 offset:22528
	ds_read_b128 v[172:175], v169 offset:2048
	ds_read_b128 v[176:179], v169 offset:4096
	ds_read_b128 v[180:183], v169 offset:6144
; template <int NT, bool BKN, bool MASK = false, bool ROWSS = false, class Epi> ...
;     ...
;   float ss_[4] = {0.f, 0.f, 0.f, 0.f};
;   int stk_ = 0;
;   f32x4 acc[4][NT];
; #pragma unroll
;   for (int i = 0; i < 4; ++i)
; #pragma unroll
;     for (int j = 0; j < NT; ++j) acc[i][j] = (f32x4){0.f, 0.f, 0.f, 0.f};
;   const int nk = K >> 6;
;   const int nkm1 = nk - 1;
;   __syncthreads();
;   GEMM_LOAD(ra0, rb0, 0);
;   GEMM_LOAD(ra1, rb1, 1);
;   GEMM_STORE(ra0, rb0, 0);
;   GEMM_LOAD(ra0, rb0, (2 < nkm1 ? 2 : nkm1));
;   __syncthreads();
;   for (int kt = 0; kt < nk - 2; kt += 2) {
;     GEMM_COMPUTE(0);
;     GEMM_STORE(ra1, rb1, 1);
;     GEMM_LOAD(ra1, rb1, kt + 3);
;     __syncthreads();
;     GEMM_COMPUTE(1);
;     GEMM_STORE(ra0, rb0, 0);
;     GEMM_LOAD(ra0, rb0, (kt + 4 < nkm1 ? kt + 4 : nkm1));
;     __syncthreads();
;   }
.LBB0_1162:
	s_add_i32 s0, s0, 2
	s_min_u32 s1, s0, 11
	s_lshl_b32 s94, s1, 7
	s_cmp_lt_u32 s0, 12
	s_waitcnt lgkmcnt(3)
	v_mfma_f32_16x16x32_bf16 v[78:81], v[158:161], v[188:191], v[78:81]
	v_mfma_f32_16x16x32_bf16 v[74:77], v[158:161], v[192:195], v[74:77]
	v_mfma_f32_16x16x32_bf16 v[66:69], v[158:161], v[196:199], v[66:69]
	v_mfma_f32_16x16x32_bf16 v[70:73], v[158:161], v[200:203], v[70:73]
	ds_read_b128 v[230:233], v167
	ds_read_b128 v[204:207], v166 offset:16384
	ds_read_b128 v[208:211], v166 offset:18432
	ds_read_b128 v[216:219], v166 offset:20480
	ds_read_b128 v[220:223], v166 offset:22528
	s_waitcnt lgkmcnt(7)
	v_mfma_f32_16x16x32_bf16 v[90:93], v[172:175], v[188:191], v[90:93]
	v_mfma_f32_16x16x32_bf16 v[86:89], v[172:175], v[192:195], v[86:89]
	v_mfma_f32_16x16x32_bf16 v[82:85], v[172:175], v[196:199], v[82:85]
	v_mfma_f32_16x16x32_bf16 v[114:117], v[172:175], v[200:203], v[114:117]
	s_waitcnt lgkmcnt(6)
	v_mfma_f32_16x16x32_bf16 v[102:105], v[176:179], v[188:191], v[102:105]
	v_mfma_f32_16x16x32_bf16 v[110:113], v[176:179], v[192:195], v[110:113]
	v_mfma_f32_16x16x32_bf16 v[106:109], v[176:179], v[196:199], v[106:109]
	v_mfma_f32_16x16x32_bf16 v[98:101], v[176:179], v[200:203], v[98:101]
	ds_read_b128 v[242:245], v167 offset:2048
	ds_read_b128 v[234:237], v167 offset:4096
	ds_read_b128 v[238:241], v167 offset:6144
	s_waitcnt lgkmcnt(8)
	v_mfma_f32_16x16x32_bf16 v[94:97], v[180:183], v[188:191], v[94:97]
	v_mfma_f32_16x16x32_bf16 v[126:129], v[180:183], v[192:195], v[126:129]
	v_mfma_f32_16x16x32_bf16 v[122:125], v[180:183], v[196:199], v[122:125]
	v_mfma_f32_16x16x32_bf16 v[118:121], v[180:183], v[200:203], v[118:121]
	s_waitcnt lgkmcnt(3)
	v_mfma_f32_16x16x32_bf16 v[78:81], v[230:233], v[204:207], v[78:81]
	s_waitcnt vmcnt(8)
	ds_write_b128 v170, v[14:17] offset:32768
	ds_write_b128 v170, v[10:13] offset:36864
	ds_write_b128 v170, v[6:9] offset:40960
	ds_write_b128 v170, v[18:21] offset:45056
	v_mfma_f32_16x16x32_bf16 v[74:77], v[230:233], v[208:211], v[74:77]
	ds_write_b128 v170, v[2:5] offset:49152
	ds_write_b128 v170, v[30:33] offset:53248
	ds_write_b128 v170, v[22:25] offset:57344
	ds_write_b128 v170, v[26:29] offset:61440
	v_mfma_f32_16x16x32_bf16 v[66:69], v[230:233], v[216:219], v[66:69]
	v_lshl_add_u64 v[2:3], v[156:157], 0, v[0:1]
	v_lshl_add_u64 v[4:5], v[154:155], 0, v[0:1]
	v_lshl_add_u64 v[6:7], v[152:153], 0, v[0:1]
	v_lshl_add_u64 v[18:19], v[150:151], 0, v[0:1]
	v_mfma_f32_16x16x32_bf16 v[70:73], v[230:233], v[220:223], v[70:73]
	v_lshl_add_u64 v[22:23], v[148:149], 0, v[0:1]
	v_lshl_add_u64 v[24:25], v[146:147], 0, v[0:1]
	global_load_dwordx4 v[14:17], v[2:3], off
	global_load_dwordx4 v[10:13], v[4:5], off
	s_waitcnt lgkmcnt(10)
	v_mfma_f32_16x16x32_bf16 v[90:93], v[242:245], v[204:207], v[90:93]
	s_nop 0
	global_load_dwordx4 v[6:9], v[6:7], off
	s_nop 0
	global_load_dwordx4 v[18:21], v[18:19], off
	s_nop 0
	global_load_dwordx4 v[2:5], v[22:23], off
	v_add_co_u32_e32 v22, vcc, s15, v24
	v_mfma_f32_16x16x32_bf16 v[86:89], v[242:245], v[208:211], v[86:89]
	v_addc_co_u32_e32 v23, vcc, 0, v25, vcc
	v_add_co_u32_e32 v26, vcc, s16, v24
	v_addc_co_u32_e32 v27, vcc, 0, v25, vcc
	v_add_co_u32_e32 v28, vcc, s17, v24
	v_mfma_f32_16x16x32_bf16 v[82:85], v[242:245], v[216:219], v[82:85]
	v_addc_co_u32_e32 v29, vcc, 0, v25, vcc
	global_load_dwordx4 v[30:33], v[22:23], off offset:384
	s_nop 0
	global_load_dwordx4 v[22:25], v[26:27], off offset:384
	s_nop 0
	global_load_dwordx4 v[26:29], v[28:29], off offset:384
	v_mfma_f32_16x16x32_bf16 v[114:117], v[242:245], v[220:223], v[114:117]
	s_waitcnt lgkmcnt(0)
	s_barrier
	ds_read_b128 v[158:161], v169 offset:32768
	ds_read_b128 v[188:191], v168 offset:49152
	ds_read_b128 v[192:195], v168 offset:51200
	ds_read_b128 v[196:199], v168 offset:53248
	ds_read_b128 v[200:203], v168 offset:55296
	ds_read_b128 v[172:175], v169 offset:34816
	ds_read_b128 v[176:179], v169 offset:36864
	ds_read_b128 v[180:183], v169 offset:38912
	v_mfma_f32_16x16x32_bf16 v[102:105], v[234:237], v[204:207], v[102:105]
	v_mfma_f32_16x16x32_bf16 v[110:113], v[234:237], v[208:211], v[110:113]
	v_mfma_f32_16x16x32_bf16 v[106:109], v[234:237], v[216:219], v[106:109]
	v_mfma_f32_16x16x32_bf16 v[98:101], v[234:237], v[220:223], v[98:101]
	v_mfma_f32_16x16x32_bf16 v[94:97], v[238:241], v[204:207], v[94:97]
	v_mfma_f32_16x16x32_bf16 v[126:129], v[238:241], v[208:211], v[126:129]
	v_mfma_f32_16x16x32_bf16 v[122:125], v[238:241], v[216:219], v[122:125]
	v_mfma_f32_16x16x32_bf16 v[118:121], v[238:241], v[220:223], v[118:121]
	s_waitcnt lgkmcnt(3)
	v_mfma_f32_16x16x32_bf16 v[78:81], v[158:161], v[188:191], v[78:81]
	v_mfma_f32_16x16x32_bf16 v[74:77], v[158:161], v[192:195], v[74:77]
	v_mfma_f32_16x16x32_bf16 v[66:69], v[158:161], v[196:199], v[66:69]
	v_mfma_f32_16x16x32_bf16 v[70:73], v[158:161], v[200:203], v[70:73]
	ds_read_b128 v[230:233], v167 offset:32768
	ds_read_b128 v[204:207], v166 offset:49152
	ds_read_b128 v[208:211], v166 offset:51200
	ds_read_b128 v[216:219], v166 offset:53248
	ds_read_b128 v[220:223], v166 offset:55296
	s_waitcnt lgkmcnt(7)
	v_mfma_f32_16x16x32_bf16 v[90:93], v[172:175], v[188:191], v[90:93]
	v_mfma_f32_16x16x32_bf16 v[86:89], v[172:175], v[192:195], v[86:89]
	v_mfma_f32_16x16x32_bf16 v[82:85], v[172:175], v[196:199], v[82:85]
	v_mfma_f32_16x16x32_bf16 v[114:117], v[172:175], v[200:203], v[114:117]
	s_waitcnt lgkmcnt(6)
	v_mfma_f32_16x16x32_bf16 v[102:105], v[176:179], v[188:191], v[102:105]
	v_mfma_f32_16x16x32_bf16 v[110:113], v[176:179], v[192:195], v[110:113]
	v_mfma_f32_16x16x32_bf16 v[106:109], v[176:179], v[196:199], v[106:109]
	v_mfma_f32_16x16x32_bf16 v[98:101], v[176:179], v[200:203], v[98:101]
	ds_read_b128 v[242:245], v167 offset:34816
	ds_read_b128 v[234:237], v167 offset:36864
	ds_read_b128 v[238:241], v167 offset:38912
	s_waitcnt lgkmcnt(8)
; template <int NT, bool BKN, bool MASK = false, bool ROWSS = false, class Epi> ...
;     ...
;   for (int kt = 0; kt < nk - 2; kt += 2) {
;     GEMM_COMPUTE(0);
;     GEMM_STORE(ra1, rb1, 1);
;     GEMM_LOAD(ra1, rb1, kt + 3);
;     __syncthreads();
;     GEMM_COMPUTE(1);
;     GEMM_STORE(ra0, rb0, 0);
;     GEMM_LOAD(ra0, rb0, (kt + 4 < nkm1 ? kt + 4 : nkm1));
;     __syncthreads();
;   }
;   GEMM_COMPUTE(0);
;   GEMM_STORE(ra1, rb1, 1);
;   __syncthreads();
;   GEMM_COMPUTE(1);
	v_mfma_f32_16x16x32_bf16 v[94:97], v[180:183], v[188:191], v[94:97]
	v_mfma_f32_16x16x32_bf16 v[126:129], v[180:183], v[192:195], v[126:129]
	v_mfma_f32_16x16x32_bf16 v[122:125], v[180:183], v[196:199], v[122:125]
	v_mfma_f32_16x16x32_bf16 v[118:121], v[180:183], v[200:203], v[118:121]
	s_waitcnt lgkmcnt(3)
	v_mfma_f32_16x16x32_bf16 v[78:81], v[230:233], v[204:207], v[78:81]
	v_lshl_add_u64 v[146:147], v[146:147], 0, s[6:7]
	v_lshl_add_u64 v[148:149], v[148:149], 0, s[6:7]
	v_lshl_add_u64 v[150:151], v[150:151], 0, s[6:7]
	v_lshl_add_u64 v[152:153], v[152:153], 0, s[6:7]
	v_mfma_f32_16x16x32_bf16 v[74:77], v[230:233], v[208:211], v[74:77]
	v_lshl_add_u64 v[154:155], v[154:155], 0, s[6:7]
	v_lshl_add_u64 v[156:157], v[156:157], 0, s[6:7]
	s_waitcnt vmcnt(8)
	ds_write_b128 v170, v[34:37]
	ds_write_b128 v170, v[38:41] offset:4096
	v_mfma_f32_16x16x32_bf16 v[66:69], v[230:233], v[216:219], v[66:69]
	ds_write_b128 v170, v[42:45] offset:8192
	ds_write_b128 v170, v[46:49] offset:12288
	ds_write_b128 v170, v[50:53] offset:16384
	ds_write_b128 v170, v[58:61] offset:20480
	v_mfma_f32_16x16x32_bf16 v[70:73], v[230:233], v[220:223], v[70:73]
	ds_write_b128 v170, v[54:57] offset:24576
	ds_write_b128 v170, v[62:65] offset:28672
	v_lshl_add_u64 v[34:35], v[134:135], 0, s[94:95]
	v_lshl_add_u64 v[38:39], v[132:133], 0, s[94:95]
	s_waitcnt lgkmcnt(10)
	v_mfma_f32_16x16x32_bf16 v[90:93], v[242:245], v[204:207], v[90:93]
	v_lshl_add_u64 v[42:43], v[130:131], 0, s[94:95]
	v_lshl_add_u64 v[46:47], v[136:137], 0, s[94:95]
	v_lshl_add_u64 v[50:51], v[138:139], 0, s[94:95]
	v_lshl_add_u64 v[54:55], v[140:141], 0, s[94:95]
	v_mfma_f32_16x16x32_bf16 v[86:89], v[242:245], v[208:211], v[86:89]
	v_lshl_add_u64 v[56:57], v[142:143], 0, s[94:95]
	v_lshl_add_u64 v[62:63], v[144:145], 0, s[94:95]
	global_load_dwordx4 v[34:37], v[34:35], off offset:512
	s_nop 0
	global_load_dwordx4 v[38:41], v[38:39], off offset:512
	v_mfma_f32_16x16x32_bf16 v[82:85], v[242:245], v[216:219], v[82:85]
	s_nop 0
	global_load_dwordx4 v[42:45], v[42:43], off offset:512
	s_nop 0
	global_load_dwordx4 v[46:49], v[46:47], off offset:512
	s_nop 0
	global_load_dwordx4 v[50:53], v[50:51], off offset:512
	s_nop 0
	global_load_dwordx4 v[58:61], v[54:55], off offset:512
	v_mfma_f32_16x16x32_bf16 v[114:117], v[242:245], v[220:223], v[114:117]
	s_nop 0
	global_load_dwordx4 v[54:57], v[56:57], off offset:512
	global_load_dwordx4 v[62:65], v[62:63], off offset:512
	s_waitcnt lgkmcnt(0)
	s_barrier
	ds_read_b128 v[158:161], v169
	ds_read_b128 v[188:191], v168 offset:16384
	ds_read_b128 v[192:195], v168 offset:18432
	ds_read_b128 v[196:199], v168 offset:20480
	ds_read_b128 v[200:203], v168 offset:22528
	ds_read_b128 v[172:175], v169 offset:2048
	ds_read_b128 v[176:179], v169 offset:4096
	ds_read_b128 v[180:183], v169 offset:6144
	v_mfma_f32_16x16x32_bf16 v[102:105], v[234:237], v[204:207], v[102:105]
	v_mfma_f32_16x16x32_bf16 v[110:113], v[234:237], v[208:211], v[110:113]
	v_mfma_f32_16x16x32_bf16 v[106:109], v[234:237], v[216:219], v[106:109]
	v_mfma_f32_16x16x32_bf16 v[98:101], v[234:237], v[220:223], v[98:101]
	v_mfma_f32_16x16x32_bf16 v[94:97], v[238:241], v[204:207], v[94:97]
	v_mfma_f32_16x16x32_bf16 v[126:129], v[238:241], v[208:211], v[126:129]
	v_mfma_f32_16x16x32_bf16 v[122:125], v[238:241], v[216:219], v[122:125]
	v_mfma_f32_16x16x32_bf16 v[118:121], v[238:241], v[220:223], v[118:121]
	s_cbranch_scc1 .LBB0_1162
	s_waitcnt vmcnt(0)
	ds_read_b128 v[34:37], v169
	ds_read_b128 v[38:41], v169 offset:2048
	ds_read_b128 v[42:45], v169 offset:4096
	ds_read_b128 v[46:49], v169 offset:6144
	ds_read_b128 v[50:53], v168 offset:16384
	ds_read_b128 v[54:57], v168 offset:18432
	ds_read_b128 v[58:61], v168 offset:20480
	ds_read_b128 v[62:65], v168 offset:22528
	v_lshlrev_b32_e32 v0, 6, v164
	s_waitcnt lgkmcnt(3)
	v_mfma_f32_16x16x32_bf16 v[78:81], v[34:37], v[50:53], v[78:81]
	v_lshl_or_b32 v0, v165, 2, v0
	v_mul_lo_u32 v0, v0, s96
	s_waitcnt lgkmcnt(2)
	v_mfma_f32_16x16x32_bf16 v[74:77], v[34:37], v[54:57], v[74:77]
	s_waitcnt lgkmcnt(1)
	v_mfma_f32_16x16x32_bf16 v[66:69], v[34:37], v[58:61], v[66:69]
	s_waitcnt lgkmcnt(0)
	v_mfma_f32_16x16x32_bf16 v[34:37], v[34:37], v[62:65], v[70:73]
	v_mfma_f32_16x16x32_bf16 v[70:73], v[38:41], v[50:53], v[90:93]
	v_mfma_f32_16x16x32_bf16 v[86:89], v[38:41], v[54:57], v[86:89]
	v_mfma_f32_16x16x32_bf16 v[82:85], v[38:41], v[58:61], v[82:85]
	v_mfma_f32_16x16x32_bf16 v[38:41], v[38:41], v[62:65], v[114:117]
	v_mfma_f32_16x16x32_bf16 v[90:93], v[42:45], v[50:53], v[102:105]
	v_mfma_f32_16x16x32_bf16 v[102:105], v[42:45], v[54:57], v[110:113]
	v_mfma_f32_16x16x32_bf16 v[106:109], v[42:45], v[58:61], v[106:109]
	v_mfma_f32_16x16x32_bf16 v[42:45], v[42:45], v[62:65], v[98:101]
	v_mfma_f32_16x16x32_bf16 v[50:53], v[46:49], v[50:53], v[94:97]
	v_mfma_f32_16x16x32_bf16 v[54:57], v[46:49], v[54:57], v[126:129]
	v_mfma_f32_16x16x32_bf16 v[58:61], v[46:49], v[58:61], v[122:125]
	v_mfma_f32_16x16x32_bf16 v[46:49], v[46:49], v[62:65], v[118:121]
	ds_read_b128 v[62:65], v167
	ds_read_b128 v[94:97], v167 offset:2048
	ds_read_b128 v[98:101], v167 offset:4096
	ds_read_b128 v[110:113], v167 offset:6144
	ds_read_b128 v[114:117], v166 offset:16384
	ds_read_b128 v[118:121], v166 offset:18432
	ds_read_b128 v[122:125], v166 offset:20480
	ds_read_b128 v[126:129], v166 offset:22528
	ds_write_b128 v170, v[14:17] offset:32768
	ds_write_b128 v170, v[10:13] offset:36864
	ds_write_b128 v170, v[6:9] offset:40960
	ds_write_b128 v170, v[18:21] offset:45056
	ds_write_b128 v170, v[2:5] offset:49152
	ds_write_b128 v170, v[30:33] offset:53248
	ds_write_b128 v170, v[22:25] offset:57344
	ds_write_b128 v170, v[26:29] offset:61440
	s_waitcnt lgkmcnt(0)
	v_mfma_f32_16x16x32_bf16 v[78:81], v[62:65], v[114:117], v[78:81]
	s_barrier
; __device__ __forceinline__ u16 f2bf(float f) { return (u16)(pack2(f, 0.f) & 0xffffu); }
; __device__ __forceinline__ int tid_() { int t = threadIdx.x; asm volatile("" : "+v"(t)); return t; }
; __device__ __forceinline__ float silu_f(float x) { return x / (1.f + __expf(-x)); }
; template <int NT, bool BKN, bool MASK = false, bool ROWSS = false, class Epi> ...
;     ...
;   GEMM_COMPUTE(0);
;   GEMM_STORE(ra1, rb1, 1);
;   __syncthreads();
;   GEMM_COMPUTE(1);
; __device__ __forceinline__ void phase_moe_up(const Params& p, int l, bool last, unsigned char* smem) {
;     ...
;     auto epi = [&](f32x4(&acc)[4][4], int r0, int c0) {
;       u16* Ts = (u16*)smem;
;       const int t2 = tid_();
;       __syncthreads();
; #pragma unroll
;       for (int mi = 0; mi < 4; ++mi)
; #pragma unroll
;         for (int n2 = 0; n2 < 2; ++n2)
; #pragma unroll
;           for (int j = 0; j < 4; ++j) {
;             const int m = r0 + mi * 16 + j;
;             const int fl = (c0 >> 6) * 32 + n2 * 16 + (c0 & 15);
;             Ts[m * 72 + fl] = f2bf(silu_f(acc[mi][2 * n2][j]) * acc[mi][2 * n2 + 1][j]);
;           }
	ds_read_b128 v[2:5], v169 offset:32768
	ds_read_b128 v[6:9], v169 offset:34816
	ds_read_b128 v[10:13], v169 offset:36864
	ds_read_b128 v[14:17], v169 offset:38912
	ds_read_b128 v[18:21], v168 offset:49152
	ds_read_b128 v[22:25], v168 offset:51200
	ds_read_b128 v[26:29], v168 offset:53248
	ds_read_b128 v[30:33], v168 offset:55296
	v_mfma_f32_16x16x32_bf16 v[74:77], v[62:65], v[118:121], v[74:77]
	v_mfma_f32_16x16x32_bf16 v[66:69], v[62:65], v[122:125], v[66:69]
	v_mfma_f32_16x16x32_bf16 v[34:37], v[62:65], v[126:129], v[34:37]
	v_mfma_f32_16x16x32_bf16 v[62:65], v[94:97], v[114:117], v[70:73]
	v_mfma_f32_16x16x32_bf16 v[70:73], v[94:97], v[118:121], v[86:89]
	v_mfma_f32_16x16x32_bf16 v[86:89], v[98:101], v[114:117], v[90:93]
	v_mfma_f32_16x16x32_bf16 v[90:93], v[98:101], v[118:121], v[102:105]
	v_mfma_f32_16x16x32_bf16 v[50:53], v[110:113], v[114:117], v[50:53]
	v_mfma_f32_16x16x32_bf16 v[54:57], v[110:113], v[118:121], v[54:57]
	v_mfma_f32_16x16x32_bf16 v[58:61], v[110:113], v[122:125], v[58:61]
	v_mfma_f32_16x16x32_bf16 v[46:49], v[110:113], v[126:129], v[46:49]
	s_waitcnt lgkmcnt(3)
	v_mfma_f32_16x16x32_bf16 v[78:81], v[2:5], v[18:21], v[78:81]
	v_mfma_f32_16x16x32_bf16 v[82:85], v[94:97], v[122:125], v[82:85]
	v_mfma_f32_16x16x32_bf16 v[38:41], v[94:97], v[126:129], v[38:41]
	v_mfma_f32_16x16x32_bf16 v[94:97], v[98:101], v[122:125], v[106:109]
	v_mfma_f32_16x16x32_bf16 v[42:45], v[98:101], v[126:129], v[42:45]
	s_waitcnt lgkmcnt(2)
	v_mfma_f32_16x16x32_bf16 v[74:77], v[2:5], v[22:25], v[74:77]
	s_waitcnt lgkmcnt(1)
	v_mfma_f32_16x16x32_bf16 v[66:69], v[2:5], v[26:29], v[66:69]
	s_waitcnt lgkmcnt(0)
	v_mfma_f32_16x16x32_bf16 v[2:5], v[2:5], v[30:33], v[34:37]
	v_mfma_f32_16x16x32_bf16 v[34:37], v[6:9], v[18:21], v[62:65]
	v_mfma_f32_16x16x32_bf16 v[70:73], v[6:9], v[22:25], v[70:73]
	v_mfma_f32_16x16x32_bf16 v[86:89], v[10:13], v[18:21], v[86:89]
	v_mfma_f32_16x16x32_bf16 v[90:93], v[10:13], v[22:25], v[90:93]
	v_mfma_f32_16x16x32_bf16 v[98:101], v[14:17], v[18:21], v[50:53]
	v_mfma_f32_16x16x32_bf16 v[102:105], v[14:17], v[22:25], v[54:57]
	v_mfma_f32_16x16x32_bf16 v[106:109], v[14:17], v[26:29], v[58:61]
	v_mfma_f32_16x16x32_bf16 v[110:113], v[14:17], v[30:33], v[46:49]
	ds_read_b128 v[14:17], v167 offset:32768
	ds_read_b128 v[18:21], v167 offset:34816
	ds_read_b128 v[22:25], v167 offset:36864
	ds_read_b128 v[114:117], v167 offset:38912
	ds_read_b128 v[118:121], v166 offset:49152
	ds_read_b128 v[122:125], v166 offset:51200
	ds_read_b128 v[126:129], v166 offset:53248
	ds_read_b128 v[130:133], v166 offset:55296
	s_waitcnt lgkmcnt(3)
	v_mfma_f32_16x16x32_bf16 v[58:61], v[14:17], v[118:121], v[78:81]
	s_waitcnt lgkmcnt(1)
	v_mfma_f32_16x16x32_bf16 v[50:53], v[14:17], v[126:129], v[66:69]
	v_mfma_f32_16x16x32_bf16 v[46:49], v[18:21], v[122:125], v[70:73]
	s_nop 4
	v_mul_f32_e32 v68, 0xbfb8aa3b, v58
	v_exp_f32_e32 v68, v68
	v_lshlrev_b32_e32 v67, 5, v163
	v_mfma_f32_16x16x32_bf16 v[62:65], v[14:17], v[122:125], v[74:77]
	v_and_or_b32 v67, v67, 32, v162
	v_add_f32_e32 v68, 1.0, v68
	v_div_scale_f32 v69, s[0:1], v68, v68, v58
	v_rcp_f32_e32 v70, v69
	v_mov_b32_e32 v66, v187
	v_lshl_add_u32 v0, v67, 1, v0
	v_fma_f32 v71, -v69, v70, 1.0
	v_fmac_f32_e32 v70, v71, v70
	v_div_scale_f32 v71, vcc, v58, v68, v58
	v_mul_f32_e32 v72, v71, v70
	v_fma_f32 v73, -v69, v72, v71
	v_fmac_f32_e32 v72, v73, v70
	v_fma_f32 v69, -v69, v72, v71
	v_div_fmas_f32 v69, v69, v70, v72
	v_div_fixup_f32 v58, v69, v68, v58
	v_mul_f32_e32 v58, v62, v58
	v_cvt_pk_bf16_f32 v58, v58, s0
	s_waitcnt lgkmcnt(0)
	s_barrier
	ds_write_b16 v0, v58
	v_mul_f32_e32 v58, 0xbfb8aa3b, v59
	v_exp_f32_e32 v58, v58
	v_mfma_f32_16x16x32_bf16 v[54:57], v[14:17], v[130:133], v[2:5]
	v_add_f32_e32 v58, 1.0, v58
	v_div_scale_f32 v62, s[0:1], v58, v58, v59
	v_rcp_f32_e32 v67, v62
	v_mfma_f32_16x16x32_bf16 v[94:97], v[10:13], v[26:29], v[94:97]
	v_fma_f32 v68, -v62, v67, 1.0
	v_fmac_f32_e32 v67, v68, v67
	v_div_scale_f32 v68, vcc, v59, v58, v59
	v_mul_f32_e32 v69, v68, v67
	v_fma_f32 v70, -v62, v69, v68
	v_fmac_f32_e32 v69, v70, v67
	v_fma_f32 v62, -v62, v69, v68
	v_div_fmas_f32 v62, v62, v67, v69
	v_div_fixup_f32 v58, v62, v58, v59
	v_mul_f32_e32 v58, v63, v58
	v_cvt_pk_bf16_f32 v58, v58, s0
	ds_write_b16 v0, v58 offset:144
	v_mul_f32_e32 v58, 0xbfb8aa3b, v60
	v_exp_f32_e32 v58, v58
	v_mfma_f32_16x16x32_bf16 v[10:13], v[10:13], v[30:33], v[42:45]
	v_add_f32_e32 v58, 1.0, v58
	v_div_scale_f32 v59, s[0:1], v58, v58, v60
	v_rcp_f32_e32 v62, v59
	v_mfma_f32_16x16x32_bf16 v[42:45], v[18:21], v[118:121], v[34:37]
	v_fma_f32 v63, -v59, v62, 1.0
	v_fmac_f32_e32 v62, v63, v62
	v_div_scale_f32 v63, vcc, v60, v58, v60
	v_mul_f32_e32 v67, v63, v62
	v_fma_f32 v68, -v59, v67, v63
	v_fmac_f32_e32 v67, v68, v62
	v_fma_f32 v59, -v59, v67, v63
	v_div_fmas_f32 v59, v59, v62, v67
	v_div_fixup_f32 v58, v59, v58, v60
	v_mul_f32_e32 v58, v64, v58
	v_cvt_pk_bf16_f32 v58, v58, s0
	ds_write_b16 v0, v58 offset:288
	v_mul_f32_e32 v58, 0xbfb8aa3b, v61
	v_exp_f32_e32 v58, v58
	v_mfma_f32_16x16x32_bf16 v[82:85], v[6:9], v[26:29], v[82:85]
	v_add_f32_e32 v58, 1.0, v58
	v_div_scale_f32 v59, s[0:1], v58, v58, v61
	v_rcp_f32_e32 v60, v59
	v_mfma_f32_16x16x32_bf16 v[34:37], v[18:21], v[126:129], v[82:85]
	v_fma_f32 v62, -v59, v60, 1.0
	v_fmac_f32_e32 v60, v62, v60
	v_div_scale_f32 v62, vcc, v61, v58, v61
	v_mul_f32_e32 v63, v62, v60
	v_fma_f32 v64, -v59, v63, v62
	v_fmac_f32_e32 v63, v64, v60
	v_fma_f32 v59, -v59, v63, v62
	v_div_fmas_f32 v59, v59, v60, v63
	v_div_fixup_f32 v58, v59, v58, v61
	v_mul_f32_e32 v58, v65, v58
	v_cvt_pk_bf16_f32 v58, v58, s0
	ds_write_b16 v0, v58 offset:432
	v_mul_f32_e32 v58, 0xbfb8aa3b, v50
; __device__ __forceinline__ u16 f2bf(float f) { return (u16)(pack2(f, 0.f) & 0xffffu); }
; __device__ __forceinline__ float silu_f(float x) { return x / (1.f + __expf(-x)); }
; __device__ __forceinline__ void phase_moe_up(const Params& p, int l, bool last, unsigned char* smem) {
;     ...
; #pragma unroll
;       for (int mi = 0; mi < 4; ++mi)
; #pragma unroll
;         for (int n2 = 0; n2 < 2; ++n2)
; #pragma unroll
;           for (int j = 0; j < 4; ++j) {
;             const int m = r0 + mi * 16 + j;
;             const int fl = (c0 >> 6) * 32 + n2 * 16 + (c0 & 15);
;             Ts[m * 72 + fl] = f2bf(silu_f(acc[mi][2 * n2][j]) * acc[mi][2 * n2 + 1][j]);
;           }
	v_exp_f32_e32 v58, v58
	v_mfma_f32_16x16x32_bf16 v[6:9], v[6:9], v[30:33], v[38:41]
	v_add_f32_e32 v58, 1.0, v58
	v_div_scale_f32 v59, s[0:1], v58, v58, v50
	v_rcp_f32_e32 v60, v59
	v_mfma_f32_16x16x32_bf16 v[38:41], v[18:21], v[130:133], v[6:9]
	v_fma_f32 v61, -v59, v60, 1.0
	v_fmac_f32_e32 v60, v61, v60
	v_div_scale_f32 v61, vcc, v50, v58, v50
	v_mul_f32_e32 v62, v61, v60
	v_fma_f32 v63, -v59, v62, v61
	v_fmac_f32_e32 v62, v63, v60
	v_fma_f32 v59, -v59, v62, v61
	v_div_fmas_f32 v59, v59, v60, v62
	v_div_fixup_f32 v50, v59, v58, v50
	v_mul_f32_e32 v50, v54, v50
	v_cvt_pk_bf16_f32 v50, v50, s0
	ds_write_b16 v0, v50 offset:32
	v_mul_f32_e32 v50, 0xbfb8aa3b, v51
	v_exp_f32_e32 v50, v50
	v_mfma_f32_16x16x32_bf16 v[26:29], v[22:25], v[118:121], v[86:89]
	v_add_f32_e32 v50, 1.0, v50
	v_div_scale_f32 v54, s[0:1], v50, v50, v51
	v_rcp_f32_e32 v58, v54
	v_mfma_f32_16x16x32_bf16 v[30:33], v[22:25], v[122:125], v[90:93]
	v_fma_f32 v59, -v54, v58, 1.0
	v_fmac_f32_e32 v58, v59, v58
	v_div_scale_f32 v59, vcc, v51, v50, v51
	v_mul_f32_e32 v60, v59, v58
	v_fma_f32 v61, -v54, v60, v59
	v_fmac_f32_e32 v60, v61, v58
	v_fma_f32 v54, -v54, v60, v59
	v_div_fmas_f32 v54, v54, v58, v60
	v_div_fixup_f32 v50, v54, v50, v51
	v_mul_f32_e32 v50, v55, v50
	v_cvt_pk_bf16_f32 v50, v50, s0
	ds_write_b16 v0, v50 offset:176
	v_mul_f32_e32 v50, 0xbfb8aa3b, v52
	v_exp_f32_e32 v50, v50
	v_mfma_f32_16x16x32_bf16 v[18:21], v[22:25], v[126:129], v[94:97]
	v_add_f32_e32 v50, 1.0, v50
	v_div_scale_f32 v51, s[0:1], v50, v50, v52
	v_rcp_f32_e32 v54, v51
	v_mfma_f32_16x16x32_bf16 v[22:25], v[22:25], v[130:133], v[10:13]
	v_fma_f32 v55, -v51, v54, 1.0
	v_fmac_f32_e32 v54, v55, v54
	v_div_scale_f32 v55, vcc, v52, v50, v52
	v_mul_f32_e32 v58, v55, v54
	v_fma_f32 v59, -v51, v58, v55
	v_fmac_f32_e32 v58, v59, v54
	v_fma_f32 v51, -v51, v58, v55
	v_div_fmas_f32 v51, v51, v54, v58
	v_div_fixup_f32 v50, v51, v50, v52
	v_mul_f32_e32 v50, v56, v50
	v_cvt_pk_bf16_f32 v50, v50, s0
	ds_write_b16 v0, v50 offset:320
	v_mul_f32_e32 v50, 0xbfb8aa3b, v53
	v_exp_f32_e32 v50, v50
	v_mfma_f32_16x16x32_bf16 v[10:13], v[114:117], v[118:121], v[98:101]
	v_add_f32_e32 v50, 1.0, v50
	v_div_scale_f32 v51, s[0:1], v50, v50, v53
	v_rcp_f32_e32 v52, v51
	v_mfma_f32_16x16x32_bf16 v[14:17], v[114:117], v[122:125], v[102:105]
	v_fma_f32 v54, -v51, v52, 1.0
	v_fmac_f32_e32 v52, v54, v52
	v_div_scale_f32 v54, vcc, v53, v50, v53
	v_mul_f32_e32 v55, v54, v52
	v_fma_f32 v56, -v51, v55, v54
	v_fmac_f32_e32 v55, v56, v52
	v_fma_f32 v51, -v51, v55, v54
	v_div_fmas_f32 v51, v51, v52, v55
	v_div_fixup_f32 v50, v51, v50, v53
	v_mul_f32_e32 v50, v57, v50
	v_cvt_pk_bf16_f32 v50, v50, s0
	ds_write_b16 v0, v50 offset:464
	v_mul_f32_e32 v50, 0xbfb8aa3b, v42
	v_exp_f32_e32 v50, v50
	v_mfma_f32_16x16x32_bf16 v[2:5], v[114:117], v[126:129], v[106:109]
	v_add_f32_e32 v50, 1.0, v50
	v_div_scale_f32 v51, s[0:1], v50, v50, v42
	v_rcp_f32_e32 v52, v51
	v_mfma_f32_16x16x32_bf16 v[6:9], v[114:117], v[130:133], v[110:113]
	v_fma_f32 v53, -v51, v52, 1.0
	v_fmac_f32_e32 v52, v53, v52
	v_div_scale_f32 v53, vcc, v42, v50, v42
	v_mul_f32_e32 v54, v53, v52
	v_fma_f32 v55, -v51, v54, v53
	v_fmac_f32_e32 v54, v55, v52
	v_fma_f32 v51, -v51, v54, v53
	v_div_fmas_f32 v51, v51, v52, v54
	v_div_fixup_f32 v42, v51, v50, v42
	v_mul_f32_e32 v42, v46, v42
	v_cvt_pk_bf16_f32 v42, v42, s0
	ds_write_b16 v0, v42 offset:2304
	v_mul_f32_e32 v42, 0xbfb8aa3b, v43
	v_exp_f32_e32 v42, v42
	s_nop 0
	v_add_f32_e32 v42, 1.0, v42
	v_div_scale_f32 v46, s[0:1], v42, v42, v43
	v_rcp_f32_e32 v50, v46
	s_nop 0
	v_fma_f32 v51, -v46, v50, 1.0
	v_fmac_f32_e32 v50, v51, v50
	v_div_scale_f32 v51, vcc, v43, v42, v43
	v_mul_f32_e32 v52, v51, v50
	v_fma_f32 v53, -v46, v52, v51
	v_fmac_f32_e32 v52, v53, v50
	v_fma_f32 v46, -v46, v52, v51
	v_div_fmas_f32 v46, v46, v50, v52
	v_div_fixup_f32 v42, v46, v42, v43
	v_mul_f32_e32 v42, v47, v42
	v_cvt_pk_bf16_f32 v42, v42, s0
	ds_write_b16 v0, v42 offset:2448
	v_mul_f32_e32 v42, 0xbfb8aa3b, v44
	v_exp_f32_e32 v42, v42
	s_nop 0
	v_add_f32_e32 v42, 1.0, v42
	v_div_scale_f32 v43, s[0:1], v42, v42, v44
	v_rcp_f32_e32 v46, v43
	s_nop 0
	v_fma_f32 v47, -v43, v46, 1.0
	v_fmac_f32_e32 v46, v47, v46
	v_div_scale_f32 v47, vcc, v44, v42, v44
	v_mul_f32_e32 v50, v47, v46
	v_fma_f32 v51, -v43, v50, v47
	v_fmac_f32_e32 v50, v51, v46
	v_fma_f32 v43, -v43, v50, v47
	v_div_fmas_f32 v43, v43, v46, v50
	v_div_fixup_f32 v42, v43, v42, v44
	v_mul_f32_e32 v42, v48, v42
	v_cvt_pk_bf16_f32 v42, v42, s0
	ds_write_b16 v0, v42 offset:2592
	v_mul_f32_e32 v42, 0xbfb8aa3b, v45
	v_exp_f32_e32 v42, v42
	s_nop 0
	v_add_f32_e32 v42, 1.0, v42
	v_div_scale_f32 v43, s[0:1], v42, v42, v45
	v_rcp_f32_e32 v44, v43
	s_nop 0
	v_fma_f32 v46, -v43, v44, 1.0
	v_fmac_f32_e32 v44, v46, v44
	v_div_scale_f32 v46, vcc, v45, v42, v45
	v_mul_f32_e32 v47, v46, v44
	v_fma_f32 v48, -v43, v47, v46
	v_fmac_f32_e32 v47, v48, v44
	v_fma_f32 v43, -v43, v47, v46
	v_div_fmas_f32 v43, v43, v44, v47
	v_div_fixup_f32 v42, v43, v42, v45
	v_mul_f32_e32 v42, v49, v42
	v_cvt_pk_bf16_f32 v42, v42, s0
	ds_write_b16 v0, v42 offset:2736
	v_mul_f32_e32 v42, 0xbfb8aa3b, v34
	v_exp_f32_e32 v42, v42
	s_nop 0
	v_add_f32_e32 v42, 1.0, v42
	v_div_scale_f32 v43, s[0:1], v42, v42, v34
	v_rcp_f32_e32 v44, v43
	s_nop 0
	v_fma_f32 v45, -v43, v44, 1.0
	v_fmac_f32_e32 v44, v45, v44
	v_div_scale_f32 v45, vcc, v34, v42, v34
	v_mul_f32_e32 v46, v45, v44
	v_fma_f32 v47, -v43, v46, v45
	v_fmac_f32_e32 v46, v47, v44
	v_fma_f32 v43, -v43, v46, v45
	v_div_fmas_f32 v43, v43, v44, v46
	v_div_fixup_f32 v34, v43, v42, v34
	v_mul_f32_e32 v34, v38, v34
	v_cvt_pk_bf16_f32 v34, v34, s0
	ds_write_b16 v0, v34 offset:2336
	v_mul_f32_e32 v34, 0xbfb8aa3b, v35
; __device__ __forceinline__ u16 f2bf(float f) { return (u16)(pack2(f, 0.f) & 0xffffu); }
; __device__ __forceinline__ float silu_f(float x) { return x / (1.f + __expf(-x)); }
; __device__ __forceinline__ void phase_moe_up(const Params& p, int l, bool last, unsigned char* smem) {
;     ...
; #pragma unroll
;       for (int mi = 0; mi < 4; ++mi)
; #pragma unroll
;         for (int n2 = 0; n2 < 2; ++n2)
; #pragma unroll
;           for (int j = 0; j < 4; ++j) {
;             const int m = r0 + mi * 16 + j;
;             const int fl = (c0 >> 6) * 32 + n2 * 16 + (c0 & 15);
;             Ts[m * 72 + fl] = f2bf(silu_f(acc[mi][2 * n2][j]) * acc[mi][2 * n2 + 1][j]);
;           }
	v_exp_f32_e32 v34, v34
	s_nop 0
	v_add_f32_e32 v34, 1.0, v34
	v_div_scale_f32 v38, s[0:1], v34, v34, v35
	v_rcp_f32_e32 v42, v38
	s_nop 0
	v_fma_f32 v43, -v38, v42, 1.0
	v_fmac_f32_e32 v42, v43, v42
	v_div_scale_f32 v43, vcc, v35, v34, v35
	v_mul_f32_e32 v44, v43, v42
	v_fma_f32 v45, -v38, v44, v43
	v_fmac_f32_e32 v44, v45, v42
	v_fma_f32 v38, -v38, v44, v43
	v_div_fmas_f32 v38, v38, v42, v44
	v_div_fixup_f32 v34, v38, v34, v35
	v_mul_f32_e32 v34, v39, v34
	v_cvt_pk_bf16_f32 v34, v34, s0
	ds_write_b16 v0, v34 offset:2480
	v_mul_f32_e32 v34, 0xbfb8aa3b, v36
	v_exp_f32_e32 v34, v34
	s_nop 0
	v_add_f32_e32 v34, 1.0, v34
	v_div_scale_f32 v35, s[0:1], v34, v34, v36
	v_rcp_f32_e32 v38, v35
	s_nop 0
	v_fma_f32 v39, -v35, v38, 1.0
	v_fmac_f32_e32 v38, v39, v38
	v_div_scale_f32 v39, vcc, v36, v34, v36
	v_mul_f32_e32 v42, v39, v38
	v_fma_f32 v43, -v35, v42, v39
	v_fmac_f32_e32 v42, v43, v38
	v_fma_f32 v35, -v35, v42, v39
	v_div_fmas_f32 v35, v35, v38, v42
	v_div_fixup_f32 v34, v35, v34, v36
	v_mul_f32_e32 v34, v40, v34
	v_cvt_pk_bf16_f32 v34, v34, s0
	ds_write_b16 v0, v34 offset:2624
	v_mul_f32_e32 v34, 0xbfb8aa3b, v37
	v_exp_f32_e32 v34, v34
	s_nop 0
	v_add_f32_e32 v34, 1.0, v34
	v_div_scale_f32 v35, s[0:1], v34, v34, v37
	v_rcp_f32_e32 v36, v35
	s_nop 0
	v_fma_f32 v38, -v35, v36, 1.0
	v_fmac_f32_e32 v36, v38, v36
	v_div_scale_f32 v38, vcc, v37, v34, v37
	v_mul_f32_e32 v39, v38, v36
	v_fma_f32 v40, -v35, v39, v38
	v_fmac_f32_e32 v39, v40, v36
	v_fma_f32 v35, -v35, v39, v38
	v_div_fmas_f32 v35, v35, v36, v39
	v_div_fixup_f32 v34, v35, v34, v37
	v_mul_f32_e32 v34, v41, v34
	v_cvt_pk_bf16_f32 v34, v34, s0
	ds_write_b16 v0, v34 offset:2768
	v_mul_f32_e32 v34, 0xbfb8aa3b, v26
	v_exp_f32_e32 v34, v34
	s_nop 0
	v_add_f32_e32 v34, 1.0, v34
	v_div_scale_f32 v35, s[0:1], v34, v34, v26
	v_rcp_f32_e32 v36, v35
	s_nop 0
	v_fma_f32 v37, -v35, v36, 1.0
	v_fmac_f32_e32 v36, v37, v36
	v_div_scale_f32 v37, vcc, v26, v34, v26
	v_mul_f32_e32 v38, v37, v36
	v_fma_f32 v39, -v35, v38, v37
	v_fmac_f32_e32 v38, v39, v36
	v_fma_f32 v35, -v35, v38, v37
	v_div_fmas_f32 v35, v35, v36, v38
	v_div_fixup_f32 v26, v35, v34, v26
	v_mul_f32_e32 v26, v30, v26
	v_cvt_pk_bf16_f32 v26, v26, s0
	ds_write_b16 v0, v26 offset:4608
	v_mul_f32_e32 v26, 0xbfb8aa3b, v27
	v_exp_f32_e32 v26, v26
	s_nop 0
	v_add_f32_e32 v26, 1.0, v26
	v_div_scale_f32 v30, s[0:1], v26, v26, v27
	v_rcp_f32_e32 v34, v30
	s_nop 0
	v_fma_f32 v35, -v30, v34, 1.0
	v_fmac_f32_e32 v34, v35, v34
	v_div_scale_f32 v35, vcc, v27, v26, v27
	v_mul_f32_e32 v36, v35, v34
	v_fma_f32 v37, -v30, v36, v35
	v_fmac_f32_e32 v36, v37, v34
	v_fma_f32 v30, -v30, v36, v35
	v_div_fmas_f32 v30, v30, v34, v36
	v_div_fixup_f32 v26, v30, v26, v27
	v_mul_f32_e32 v26, v31, v26
	v_cvt_pk_bf16_f32 v26, v26, s0
	ds_write_b16 v0, v26 offset:4752
	v_mul_f32_e32 v26, 0xbfb8aa3b, v28
	v_exp_f32_e32 v26, v26
	s_nop 0
	v_add_f32_e32 v26, 1.0, v26
	v_div_scale_f32 v27, s[0:1], v26, v26, v28
	v_rcp_f32_e32 v30, v27
	s_nop 0
	v_fma_f32 v31, -v27, v30, 1.0
	v_fmac_f32_e32 v30, v31, v30
	v_div_scale_f32 v31, vcc, v28, v26, v28
	v_mul_f32_e32 v34, v31, v30
	v_fma_f32 v35, -v27, v34, v31
	v_fmac_f32_e32 v34, v35, v30
	v_fma_f32 v27, -v27, v34, v31
	v_div_fmas_f32 v27, v27, v30, v34
	v_div_fixup_f32 v26, v27, v26, v28
	v_mul_f32_e32 v26, v32, v26
	v_cvt_pk_bf16_f32 v26, v26, s0
	ds_write_b16 v0, v26 offset:4896
	v_mul_f32_e32 v26, 0xbfb8aa3b, v29
	v_exp_f32_e32 v26, v26
	s_nop 0
	v_add_f32_e32 v26, 1.0, v26
	v_div_scale_f32 v27, s[0:1], v26, v26, v29
	v_rcp_f32_e32 v28, v27
	s_nop 0
	v_fma_f32 v30, -v27, v28, 1.0
	v_fmac_f32_e32 v28, v30, v28
	v_div_scale_f32 v30, vcc, v29, v26, v29
	v_mul_f32_e32 v31, v30, v28
	v_fma_f32 v32, -v27, v31, v30
	v_fmac_f32_e32 v31, v32, v28
	v_fma_f32 v27, -v27, v31, v30
	v_div_fmas_f32 v27, v27, v28, v31
	v_div_fixup_f32 v26, v27, v26, v29
	v_mul_f32_e32 v26, v33, v26
	v_cvt_pk_bf16_f32 v26, v26, s0
	ds_write_b16 v0, v26 offset:5040
	v_mul_f32_e32 v26, 0xbfb8aa3b, v18
	v_exp_f32_e32 v26, v26
	s_nop 0
	v_add_f32_e32 v26, 1.0, v26
	v_div_scale_f32 v27, s[0:1], v26, v26, v18
	v_rcp_f32_e32 v28, v27
	s_nop 0
	v_fma_f32 v29, -v27, v28, 1.0
	v_fmac_f32_e32 v28, v29, v28
	v_div_scale_f32 v29, vcc, v18, v26, v18
	v_mul_f32_e32 v30, v29, v28
	v_fma_f32 v31, -v27, v30, v29
	v_fmac_f32_e32 v30, v31, v28
	v_fma_f32 v27, -v27, v30, v29
	v_div_fmas_f32 v27, v27, v28, v30
	v_div_fixup_f32 v18, v27, v26, v18
	v_mul_f32_e32 v18, v22, v18
	v_cvt_pk_bf16_f32 v18, v18, s0
	ds_write_b16 v0, v18 offset:4640
	v_mul_f32_e32 v18, 0xbfb8aa3b, v19
	v_exp_f32_e32 v18, v18
	s_nop 0
	v_add_f32_e32 v18, 1.0, v18
	v_div_scale_f32 v22, s[0:1], v18, v18, v19
	v_rcp_f32_e32 v26, v22
	s_nop 0
	v_fma_f32 v27, -v22, v26, 1.0
	v_fmac_f32_e32 v26, v27, v26
	v_div_scale_f32 v27, vcc, v19, v18, v19
	v_mul_f32_e32 v28, v27, v26
	v_fma_f32 v29, -v22, v28, v27
	v_fmac_f32_e32 v28, v29, v26
	v_fma_f32 v22, -v22, v28, v27
	v_div_fmas_f32 v22, v22, v26, v28
	v_div_fixup_f32 v18, v22, v18, v19
	v_mul_f32_e32 v18, v23, v18
	v_cvt_pk_bf16_f32 v18, v18, s0
	ds_write_b16 v0, v18 offset:4784
	v_mul_f32_e32 v18, 0xbfb8aa3b, v20
	v_exp_f32_e32 v18, v18
	s_nop 0
	v_add_f32_e32 v18, 1.0, v18
	v_div_scale_f32 v19, s[0:1], v18, v18, v20
	v_rcp_f32_e32 v22, v19
	s_nop 0
	v_fma_f32 v23, -v19, v22, 1.0
	v_fmac_f32_e32 v22, v23, v22
	v_div_scale_f32 v23, vcc, v20, v18, v20
	v_mul_f32_e32 v26, v23, v22
	v_fma_f32 v27, -v19, v26, v23
	v_fmac_f32_e32 v26, v27, v22
	v_fma_f32 v19, -v19, v26, v23
	v_div_fmas_f32 v19, v19, v22, v26
	v_div_fixup_f32 v18, v19, v18, v20
	v_mul_f32_e32 v18, v24, v18
	v_cvt_pk_bf16_f32 v18, v18, s0
	ds_write_b16 v0, v18 offset:4928
	v_mul_f32_e32 v18, 0xbfb8aa3b, v21
; __device__ __forceinline__ u16 f2bf(float f) { return (u16)(pack2(f, 0.f) & 0xffffu); }
; __device__ __forceinline__ float silu_f(float x) { return x / (1.f + __expf(-x)); }
; __device__ __forceinline__ void phase_moe_up(const Params& p, int l, bool last, unsigned char* smem) {
;     ...
; #pragma unroll
;       for (int mi = 0; mi < 4; ++mi)
; #pragma unroll
;         for (int n2 = 0; n2 < 2; ++n2)
; #pragma unroll
;           for (int j = 0; j < 4; ++j) {
;             const int m = r0 + mi * 16 + j;
;             const int fl = (c0 >> 6) * 32 + n2 * 16 + (c0 & 15);
;             Ts[m * 72 + fl] = f2bf(silu_f(acc[mi][2 * n2][j]) * acc[mi][2 * n2 + 1][j]);
;           }
;       __syncthreads();
; #pragma unroll
;       for (int i = 0; i < 4; ++i) {
;         const int c = t2 + 256 * i, row = c >> 3, ch = c & 7;
;         if (row < mvalid) *(u32x4*)(p.HID + (size_t)(hid_row + row) * 512 + nt * 64 + ch * 8) = *(const u32x4*)(Ts + row * 72 + ch * 8);
;       }
	v_exp_f32_e32 v18, v18
	s_nop 0
	v_add_f32_e32 v18, 1.0, v18
	v_div_scale_f32 v19, s[0:1], v18, v18, v21
	v_rcp_f32_e32 v20, v19
	s_nop 0
	v_fma_f32 v22, -v19, v20, 1.0
	v_fmac_f32_e32 v20, v22, v20
	v_div_scale_f32 v22, vcc, v21, v18, v21
	v_mul_f32_e32 v23, v22, v20
	v_fma_f32 v24, -v19, v23, v22
	v_fmac_f32_e32 v23, v24, v20
	v_fma_f32 v19, -v19, v23, v22
	v_div_fmas_f32 v19, v19, v20, v23
	v_div_fixup_f32 v18, v19, v18, v21
	v_mul_f32_e32 v18, v25, v18
	v_cvt_pk_bf16_f32 v18, v18, s0
	ds_write_b16 v0, v18 offset:5072
	v_mul_f32_e32 v18, 0xbfb8aa3b, v10
	v_exp_f32_e32 v18, v18
	s_nop 0
	v_add_f32_e32 v18, 1.0, v18
	v_div_scale_f32 v19, s[0:1], v18, v18, v10
	v_rcp_f32_e32 v20, v19
	s_nop 0
	v_fma_f32 v21, -v19, v20, 1.0
	v_fmac_f32_e32 v20, v21, v20
	v_div_scale_f32 v21, vcc, v10, v18, v10
	v_mul_f32_e32 v22, v21, v20
	v_fma_f32 v23, -v19, v22, v21
	v_fmac_f32_e32 v22, v23, v20
	v_fma_f32 v19, -v19, v22, v21
	v_div_fmas_f32 v19, v19, v20, v22
	v_div_fixup_f32 v10, v19, v18, v10
	v_mul_f32_e32 v10, v14, v10
	v_cvt_pk_bf16_f32 v10, v10, s0
	ds_write_b16 v0, v10 offset:6912
	v_mul_f32_e32 v10, 0xbfb8aa3b, v11
	v_exp_f32_e32 v10, v10
	s_nop 0
	v_add_f32_e32 v10, 1.0, v10
	v_div_scale_f32 v14, s[0:1], v10, v10, v11
	v_rcp_f32_e32 v18, v14
	s_nop 0
	v_fma_f32 v19, -v14, v18, 1.0
	v_fmac_f32_e32 v18, v19, v18
	v_div_scale_f32 v19, vcc, v11, v10, v11
	v_mul_f32_e32 v20, v19, v18
	v_fma_f32 v21, -v14, v20, v19
	v_fmac_f32_e32 v20, v21, v18
	v_fma_f32 v14, -v14, v20, v19
	v_div_fmas_f32 v14, v14, v18, v20
	v_div_fixup_f32 v10, v14, v10, v11
	v_mul_f32_e32 v10, v15, v10
	v_cvt_pk_bf16_f32 v10, v10, s0
	ds_write_b16 v0, v10 offset:7056
	v_mul_f32_e32 v10, 0xbfb8aa3b, v12
	v_exp_f32_e32 v10, v10
	s_nop 0
	v_add_f32_e32 v10, 1.0, v10
	v_div_scale_f32 v11, s[0:1], v10, v10, v12
	v_rcp_f32_e32 v14, v11
	s_nop 0
	v_fma_f32 v15, -v11, v14, 1.0
	v_fmac_f32_e32 v14, v15, v14
	v_div_scale_f32 v15, vcc, v12, v10, v12
	v_mul_f32_e32 v18, v15, v14
	v_fma_f32 v19, -v11, v18, v15
	v_fmac_f32_e32 v18, v19, v14
	v_fma_f32 v11, -v11, v18, v15
	v_div_fmas_f32 v11, v11, v14, v18
	v_div_fixup_f32 v10, v11, v10, v12
	v_mul_f32_e32 v10, v16, v10
	v_cvt_pk_bf16_f32 v10, v10, s0
	ds_write_b16 v0, v10 offset:7200
	v_mul_f32_e32 v10, 0xbfb8aa3b, v13
	v_exp_f32_e32 v10, v10
	s_nop 0
	v_add_f32_e32 v10, 1.0, v10
	v_div_scale_f32 v11, s[0:1], v10, v10, v13
	v_rcp_f32_e32 v12, v11
	s_nop 0
	v_fma_f32 v14, -v11, v12, 1.0
	v_fmac_f32_e32 v12, v14, v12
	v_div_scale_f32 v14, vcc, v13, v10, v13
	v_mul_f32_e32 v15, v14, v12
	v_fma_f32 v16, -v11, v15, v14
	v_fmac_f32_e32 v15, v16, v12
	v_fma_f32 v11, -v11, v15, v14
	v_div_fmas_f32 v11, v11, v12, v15
	v_div_fixup_f32 v10, v11, v10, v13
	v_mul_f32_e32 v10, v17, v10
	v_cvt_pk_bf16_f32 v10, v10, s0
	ds_write_b16 v0, v10 offset:7344
	v_mul_f32_e32 v10, 0xbfb8aa3b, v2
	v_exp_f32_e32 v10, v10
	s_nop 0
	v_add_f32_e32 v10, 1.0, v10
	v_div_scale_f32 v11, s[0:1], v10, v10, v2
	v_rcp_f32_e32 v12, v11
	s_nop 0
	v_fma_f32 v13, -v11, v12, 1.0
	v_fmac_f32_e32 v12, v13, v12
	v_div_scale_f32 v13, vcc, v2, v10, v2
	v_mul_f32_e32 v14, v13, v12
	v_fma_f32 v15, -v11, v14, v13
	v_fmac_f32_e32 v14, v15, v12
	v_fma_f32 v11, -v11, v14, v13
	v_div_fmas_f32 v11, v11, v12, v14
	v_div_fixup_f32 v2, v11, v10, v2
	v_mul_f32_e32 v2, v6, v2
	v_cvt_pk_bf16_f32 v2, v2, s0
	ds_write_b16 v0, v2 offset:6944
	v_mul_f32_e32 v2, 0xbfb8aa3b, v3
	v_exp_f32_e32 v2, v2
	s_nop 0
	v_add_f32_e32 v2, 1.0, v2
	v_div_scale_f32 v6, s[0:1], v2, v2, v3
	v_rcp_f32_e32 v10, v6
	s_nop 0
	v_fma_f32 v11, -v6, v10, 1.0
	v_fmac_f32_e32 v10, v11, v10
	v_div_scale_f32 v11, vcc, v3, v2, v3
	v_mul_f32_e32 v12, v11, v10
	v_fma_f32 v13, -v6, v12, v11
	v_fmac_f32_e32 v12, v13, v10
	v_fma_f32 v6, -v6, v12, v11
	v_div_fmas_f32 v6, v6, v10, v12
	v_div_fixup_f32 v2, v6, v2, v3
	v_mul_f32_e32 v2, v7, v2
	v_cvt_pk_bf16_f32 v2, v2, s0
	ds_write_b16 v0, v2 offset:7088
	v_mul_f32_e32 v2, 0xbfb8aa3b, v4
	v_exp_f32_e32 v2, v2
	s_nop 0
	v_add_f32_e32 v2, 1.0, v2
	v_div_scale_f32 v3, s[0:1], v2, v2, v4
	v_rcp_f32_e32 v6, v3
	s_nop 0
	v_fma_f32 v7, -v3, v6, 1.0
	v_fmac_f32_e32 v6, v7, v6
	v_div_scale_f32 v7, vcc, v4, v2, v4
	v_mul_f32_e32 v10, v7, v6
	v_fma_f32 v11, -v3, v10, v7
	v_fmac_f32_e32 v10, v11, v6
	v_fma_f32 v3, -v3, v10, v7
	v_div_fmas_f32 v3, v3, v6, v10
	v_div_fixup_f32 v2, v3, v2, v4
	v_mul_f32_e32 v2, v8, v2
	v_cvt_pk_bf16_f32 v2, v2, s0
	ds_write_b16 v0, v2 offset:7232
	v_mul_f32_e32 v2, 0xbfb8aa3b, v5
	v_exp_f32_e32 v2, v2
	s_nop 0
	v_add_f32_e32 v2, 1.0, v2
	v_div_scale_f32 v3, s[0:1], v2, v2, v5
	v_rcp_f32_e32 v4, v3
	s_nop 0
	v_fma_f32 v6, -v3, v4, 1.0
	v_fmac_f32_e32 v4, v6, v4
	v_div_scale_f32 v6, vcc, v5, v2, v5
	v_mul_f32_e32 v7, v6, v4
	v_fma_f32 v8, -v3, v7, v6
	v_fmac_f32_e32 v7, v8, v4
	v_fma_f32 v3, -v3, v7, v6
	v_div_fmas_f32 v3, v3, v4, v7
	v_div_fixup_f32 v2, v3, v2, v5
	v_mul_f32_e32 v2, v9, v2
	v_cvt_pk_bf16_f32 v2, v2, s0
	ds_write_b16 v0, v2 offset:7376
	v_lshlrev_b32_e32 v0, 3, v66
	v_and_b32_e32 v0, 56, v0
	v_ashrrev_i32_e32 v3, 3, v66
	v_lshlrev_b32_e32 v2, 1, v0
	v_cmp_gt_i32_e32 vcc, s86, v3
	s_waitcnt lgkmcnt(0)
	s_barrier
	s_and_saveexec_b64 s[0:1], vcc
	s_cbranch_execz .LBB0_1165
	v_mov_b64_e32 v[4:5], s[4:5]
	s_load_dwordx2 s[100:101], s[4:5], 0x170
	s_waitcnt lgkmcnt(0)
	v_mov_b32_e32 v8, s100
	v_mov_b32_e32 v9, s101
	v_mad_u64_u32 v[4:5], s[8:9], v3, s96, v[2:3]
	v_add_u32_e32 v10, s82, v3
	ds_read_b128 v[4:7], v4
	v_ashrrev_i32_e32 v11, 31, v10
	v_lshlrev_b64 v[10:11], 10, v[10:11]
	s_lshl_b32 s94, s83, 7
	v_mov_b32_e32 v3, v1
	s_waitcnt lgkmcnt(0)
	v_lshl_add_u64 v[8:9], v[8:9], 0, v[10:11]
	v_lshl_add_u64 v[8:9], v[8:9], 0, s[94:95]
	v_lshl_add_u64 v[8:9], v[8:9], 0, v[2:3]
	global_store_dwordx4 v[8:9], v[4:7], off

; template <bool COMBINE, bool MOD>
; __device__ __forceinline__ void phase_combine_modulate(const Params& p, int lprev, int lnext, const float* xlat, const float* xctx,
;                                                        float* olat, float* octx, int nrows) {
;     ...
;   for (int row0 = gw * R; row0 < nrows; row0 += nw * R) {
;     const bool lat = row0 < T_LAT;
;     const float* xr = lat ? xlat + (size_t)row0 * DM : xctx + (size_t)(row0 - T_LAT) * DM;
;     const int cond = row_cond(row0);
;     float4 v[R][4];
; #pragma unroll
;     for (int r = 0; r < R; ++r)
; #pragma unroll
;       for (int i = 0; i < 4; ++i) v[r][i] = *(const float4*)(xr + (size_t)r * DM + i * 256 + lane * 4);
;     if (COMBINE) {
;       const int b = row_batch(row0);
;       const int myinv = p.INV[(size_t)row0 * 16 + (lane & 31)];
;       const float* g2 = p.mada + (size_t)(lprev * 3 + cond) * 6144 + 5 * 1024;
;       float* orow = lat ? olat + (size_t)row0 * DM : octx + (size_t)(row0 - T_LAT) * DM;
; #pragma unroll
;       for (int r = 0; r < R; ++r) {
;         float4 s[4];
; #pragma unroll
;         for (int i = 0; i < 4; ++i) s[i] = make_float4(0.f, 0.f, 0.f, 0.f);
;         unsigned mask = (unsigned)((__ballot(myinv >= 0) >> (16 * r)) & 0xFFFFull);
;         while (mask) {
;           const int e0 = __builtin_ctz(mask);
;           mask &= mask - 1;
;           const bool two = mask != 0u;
;           const int e1 = two ? __builtin_ctz(mask) : e0;
;           mask &= mask - 1;
;           const int s0 = __shfl(myinv, 16 * r + e0), s1 = __shfl(myinv, 16 * r + e1);
;           const size_t y0 = lat ? (size_t)(b * 16 + e0) * 1024 + s0 : (size_t)32768 + (size_t)(b * 16 + e0) * 128 + s0;
;           const size_t y1 = lat ? (size_t)(b * 16 + e1) * 1024 + s1 : (size_t)32768 + (size_t)(b * 16 + e1) * 128 + s1;
;           u32x2 a0[4], a1[4];
; #pragma unroll
;           for (int i = 0; i < 4; ++i) { a0[i] = *(const u32x2*)(p.YB + y0 * 1024 + lane * 4 + i * 256); a1[i] = *(const u32x2*)(p.YB + y1 * 1024 + lane * 4 + i * 256); }
;           const float w1 = two ? 1.f : 0.f;
; #pragma unroll
;           for (int i = 0; i < 4; ++i) {
;             s[i].x += bf2f((u16)(a0[i].x & 0xffffu)); s[i].y += bf2f((u16)(a0[i].x >> 16));
;             s[i].z += bf2f((u16)(a0[i].y & 0xffffu)); s[i].w += bf2f((u16)(a0[i].y >> 16));
.LBB0_1742:
	s_mov_b64 s[4:5], s[64:65]
	s_movk_i32 s0, 0x4000
	v_ashrrev_i32_e32 v0, 5, v187
	v_and_b32_e32 v0, -2, v0
	v_lshl_add_u32 v32, s2, 3, v0
	v_cmp_gt_i32_e32 vcc, s0, v32
	s_and_saveexec_b64 s[0:1], vcc
	s_cbranch_execz .LBB0_1751
	s_load_dwordx2 s[8:9], s[64:65], 0xa8
	s_load_dwordx2 s[34:35], s[64:65], 0x110
	s_load_dwordx2 s[38:39], s[64:65], 0x1a0
	s_load_dwordx2 s[40:41], s[64:65], 0xb8
	s_load_dwordx2 s[48:49], s[64:65], 0x1a8
	s_load_dwordx2 s[50:51], s[64:65], 0x118
	v_readfirstlane_b32 s52, v32
	v_readlane_b32 s53, v254, 54
	s_mov_b32 s18, 0x3a800000
	v_and_b32_e32 v0, 63, v187
	v_lshlrev_b32_e32 v188, 4, v0
	v_or_b32_e32 v189, 0x1000, v188
	v_lshlrev_b32_e32 v190, 3, v0
	v_xor_b32_e32 v208, 16, v0
	v_xor_b32_e32 v209, 32, v0
	v_lshlrev_b32_e32 v208, 2, v208
	v_lshlrev_b32_e32 v209, 2, v209
	v_and_b32_e32 v210, 31, v0
	v_lshlrev_b32_e32 v210, 2, v210
	v_and_b32_e32 v246, 15, v0
	s_waitcnt lgkmcnt(0)
	s_cmpk_lt_i32 s52, 0x4000
	s_cselect_b32 s0, s8, s34
	s_cselect_b32 s1, s9, s35
	s_cselect_b32 s98, 0, 0x4000
	s_sub_i32 s98, s52, s98
	s_lshl_b32 s98, s98, 12
	s_add_u32 s98, s0, s98
	s_addc_u32 s99, s1, 0
	global_load_dwordx4 v[100:103], v188, s[98:99]
	global_load_dwordx4 v[104:107], v188, s[98:99] offset:1024
	global_load_dwordx4 v[108:111], v188, s[98:99] offset:2048
	global_load_dwordx4 v[112:115], v188, s[98:99] offset:3072
	global_load_dwordx4 v[116:119], v189, s[98:99]
	global_load_dwordx4 v[120:123], v189, s[98:99] offset:1024
	global_load_dwordx4 v[124:127], v189, s[98:99] offset:2048
	global_load_dwordx4 v[128:131], v189, s[98:99] offset:3072
	s_lshl_b32 s0, s52, 6
	s_add_u32 s0, s38, s0
	s_addc_u32 s1, s39, 0
	global_load_dword v199, v210, s[0:1]
.Lcb2_loop:
	s_add_i32 s94, s52, s53
	s_cmp_lt_i32 s94, 0x4000
	s_cselect_b32 s32, s94, s52
	s_min_i32 s0, s52, 0x4000
	s_ashr_i32 s0, s0, 13
	s_mul_i32 s0, s0, 0x6000
	s_add_u32 s56, s40, s0
	s_addc_u32 s57, s41, 0
	s_add_u32 s56, s56, 0x17000
	s_addc_u32 s57, s57, 0
	global_load_dwordx4 v[34:37], v188, s[56:57]
	global_load_dwordx4 v[38:41], v188, s[56:57] offset:1024
	global_load_dwordx4 v[42:45], v188, s[56:57] offset:2048
	global_load_dwordx4 v[46:49], v188, s[56:57] offset:3072
	s_cmpk_lt_i32 s32, 0x4000
	s_cselect_b32 s0, s8, s34
	s_cselect_b32 s1, s9, s35
	s_cselect_b32 s100, 0, 0x4000
	s_sub_i32 s100, s32, s100
	s_lshl_b32 s100, s100, 12
	s_add_u32 s100, s0, s100
	s_addc_u32 s101, s1, 0
	global_load_dwordx4 v[132:135], v188, s[100:101]
	global_load_dwordx4 v[136:139], v188, s[100:101] offset:1024
	global_load_dwordx4 v[140:143], v188, s[100:101] offset:2048
	global_load_dwordx4 v[144:147], v188, s[100:101] offset:3072
	global_load_dwordx4 v[148:151], v189, s[100:101]
	global_load_dwordx4 v[152:155], v189, s[100:101] offset:1024
	global_load_dwordx4 v[156:159], v189, s[100:101] offset:2048
	global_load_dwordx4 v[160:163], v189, s[100:101] offset:3072
	s_lshl_b32 s0, s32, 6
	s_add_u32 s0, s38, s0
	s_addc_u32 s1, s39, 0
	global_load_dword v211, v210, s[0:1]
	s_cmpk_lt_i32 s52, 0x4000
	s_cselect_b32 s1, 10, 7
	s_cselect_b32 s0, 13, 8
	s_cselect_b32 s37, 0, 0x4000
	s_cselect_b32 s71, 0, 0x8000
	s_sub_i32 s37, s52, s37
	s_lshr_b32 s37, s37, s0
	s_lshl_b32 s37, s37, 4
	s_lshl_b32 s37, s37, s1
	s_add_i32 s37, s37, s71
	v_mov_b32_e32 v2, 0
	v_mov_b32_e32 v3, 0
	v_mov_b32_e32 v4, 0
	v_mov_b32_e32 v5, 0
	v_mov_b32_e32 v6, 0
	v_mov_b32_e32 v7, 0
	v_mov_b32_e32 v8, 0
	v_mov_b32_e32 v9, 0
	v_mov_b32_e32 v10, 0
	v_mov_b32_e32 v11, 0
	v_mov_b32_e32 v12, 0
	v_mov_b32_e32 v13, 0
	v_mov_b32_e32 v14, 0
	v_mov_b32_e32 v15, 0
	v_mov_b32_e32 v16, 0
	v_mov_b32_e32 v17, 0
	v_mov_b32_e32 v18, 0
	v_mov_b32_e32 v19, 0
	v_mov_b32_e32 v20, 0
	v_mov_b32_e32 v21, 0
	v_mov_b32_e32 v22, 0
	v_mov_b32_e32 v23, 0
	v_mov_b32_e32 v24, 0
	v_mov_b32_e32 v25, 0
	v_mov_b32_e32 v26, 0
	v_mov_b32_e32 v27, 0
	v_mov_b32_e32 v28, 0
	v_mov_b32_e32 v29, 0
	v_mov_b32_e32 v30, 0
	v_mov_b32_e32 v31, 0
	v_mov_b32_e32 v32, 0
	v_mov_b32_e32 v33, 0
	s_waitcnt vmcnt(13)
	v_cmp_lt_i32_e32 vcc, -1, v199
	v_lshlrev_b32_e32 v184, s1, v246
	v_add3_u32 v184, v184, s37, v199
	s_and_b32 s59, vcc_lo, 0xffff
	s_lshr_b32 s60, vcc_lo, 16
	s_mov_b32 s71, 0
	s_mov_b32 s32, 0
	s_cmp_eq_u32 s59, 0
	s_cbranch_scc1 .Lcb2_iss0
	s_ff1_i32_b32 s0, s59
	s_bitset0_b32 s59, s0
	v_readlane_b32 s1, v184, s0
	s_lshl_b32 s1, s1, 11
	s_add_u32 s0, s48, s1
	s_addc_u32 s1, s49, 0
	global_load_dwordx2 v[164:165], v190, s[0:1]
	global_load_dwordx2 v[166:167], v190, s[0:1] offset:512
	global_load_dwordx2 v[168:169], v190, s[0:1] offset:1024
	global_load_dwordx2 v[170:171], v190, s[0:1] offset:1536
	s_add_i32 s71, s71, 1
	s_cmp_eq_u32 s59, 0
	s_cbranch_scc1 .Lcb2_iss0
	s_ff1_i32_b32 s0, s59
	s_bitset0_b32 s59, s0
	v_readlane_b32 s1, v184, s0
	s_lshl_b32 s1, s1, 11
	s_add_u32 s0, s48, s1
	s_addc_u32 s1, s49, 0
	global_load_dwordx2 v[172:173], v190, s[0:1]
	global_load_dwordx2 v[174:175], v190, s[0:1] offset:512
	global_load_dwordx2 v[176:177], v190, s[0:1] offset:1024
	global_load_dwordx2 v[178:179], v190, s[0:1] offset:1536
	s_add_i32 s71, s71, 1
	s_cmp_eq_u32 s59, 0
	s_cbranch_scc1 .Lcb2_iss0
	s_ff1_i32_b32 s0, s59
	s_bitset0_b32 s59, s0
	v_readlane_b32 s1, v184, s0
	s_lshl_b32 s1, s1, 11
	s_add_u32 s0, s48, s1
	s_addc_u32 s1, s49, 0
	global_load_dwordx2 v[82:83], v190, s[0:1]
	global_load_dwordx2 v[84:85], v190, s[0:1] offset:512
	global_load_dwordx2 v[86:87], v190, s[0:1] offset:1024
	global_load_dwordx2 v[88:89], v190, s[0:1] offset:1536
	s_add_i32 s71, s71, 1
	s_cmp_eq_u32 s59, 0
	s_cbranch_scc1 .Lcb2_iss0
	s_ff1_i32_b32 s0, s59
	s_bitset0_b32 s59, s0
	v_readlane_b32 s1, v184, s0
	s_lshl_b32 s1, s1, 11
	s_add_u32 s0, s48, s1
	s_addc_u32 s1, s49, 0
	global_load_dwordx2 v[90:91], v190, s[0:1]
	global_load_dwordx2 v[92:93], v190, s[0:1] offset:512
	global_load_dwordx2 v[94:95], v190, s[0:1] offset:1024
	global_load_dwordx2 v[96:97], v190, s[0:1] offset:1536
	s_add_i32 s71, s71, 1

; template <bool COMBINE, bool MOD>
; __device__ __forceinline__ void phase_combine_modulate(const Params& p, int lprev, int lnext, const float* xlat, const float* xctx,
;                                                        float* olat, float* octx, int nrows) {
;     ...
;   for (int row0 = gw * R; row0 < nrows; row0 += nw * R) {
;     ...
; #pragma unroll
;         for (int i = 0; i < 4; ++i) {
;           const int col = i * 256 + lane * 4;
;           const float4 g4 = *(const float4*)(g2 + col);
;           v[r][i].x += g4.x * s[i].x; v[r][i].y += g4.y * s[i].y; v[r][i].z += g4.z * s[i].z; v[r][i].w += g4.w * s[i].w;
;           *(float4*)(orow + (size_t)r * DM + col) = v[r][i];
;         }
;       }
.Lcb2_acc1:
	v_pk_fma_f32 v[100:101], v[34:35], v[2:3], v[100:101]
	v_pk_fma_f32 v[102:103], v[36:37], v[4:5], v[102:103]
	global_store_dwordx4 v188, v[100:103], s[98:99]
	v_pk_fma_f32 v[104:105], v[38:39], v[6:7], v[104:105]
	v_pk_fma_f32 v[106:107], v[40:41], v[8:9], v[106:107]
	global_store_dwordx4 v188, v[104:107], s[98:99] offset:1024
	v_pk_fma_f32 v[108:109], v[42:43], v[10:11], v[108:109]
	v_pk_fma_f32 v[110:111], v[44:45], v[12:13], v[110:111]
	global_store_dwordx4 v188, v[108:111], s[98:99] offset:2048
	v_pk_fma_f32 v[112:113], v[46:47], v[14:15], v[112:113]
	v_pk_fma_f32 v[114:115], v[48:49], v[16:17], v[114:115]
	global_store_dwordx4 v188, v[112:115], s[98:99] offset:3072
	v_pk_fma_f32 v[116:117], v[34:35], v[18:19], v[116:117]
	v_pk_fma_f32 v[118:119], v[36:37], v[20:21], v[118:119]
	global_store_dwordx4 v189, v[116:119], s[98:99]
	v_pk_fma_f32 v[120:121], v[38:39], v[22:23], v[120:121]
	v_pk_fma_f32 v[122:123], v[40:41], v[24:25], v[122:123]
	global_store_dwordx4 v189, v[120:123], s[98:99] offset:1024
	v_pk_fma_f32 v[124:125], v[42:43], v[26:27], v[124:125]
	v_pk_fma_f32 v[126:127], v[44:45], v[28:29], v[126:127]
	global_store_dwordx4 v189, v[124:127], s[98:99] offset:2048
	v_pk_fma_f32 v[128:129], v[46:47], v[30:31], v[128:129]
	v_pk_fma_f32 v[130:131], v[48:49], v[32:33], v[130:131]
	global_store_dwordx4 v189, v[128:131], s[98:99] offset:3072
	v_mov_b32_e32 v100, v132
	v_mov_b32_e32 v101, v133
	v_mov_b32_e32 v102, v134
	v_mov_b32_e32 v103, v135
	v_mov_b32_e32 v104, v136
	v_mov_b32_e32 v105, v137
	v_mov_b32_e32 v106, v138
	v_mov_b32_e32 v107, v139
	v_mov_b32_e32 v108, v140
	v_mov_b32_e32 v109, v141
	v_mov_b32_e32 v110, v142
	v_mov_b32_e32 v111, v143
	v_mov_b32_e32 v112, v144
	v_mov_b32_e32 v113, v145
	v_mov_b32_e32 v114, v146
	v_mov_b32_e32 v115, v147
	v_mov_b32_e32 v116, v148
	v_mov_b32_e32 v117, v149
	v_mov_b32_e32 v118, v150
	v_mov_b32_e32 v119, v151
	v_mov_b32_e32 v120, v152
	v_mov_b32_e32 v121, v153
	v_mov_b32_e32 v122, v154
	v_mov_b32_e32 v123, v155
	v_mov_b32_e32 v124, v156
	v_mov_b32_e32 v125, v157
	v_mov_b32_e32 v126, v158
	v_mov_b32_e32 v127, v159
	v_mov_b32_e32 v128, v160
	v_mov_b32_e32 v129, v161
	v_mov_b32_e32 v130, v162
	v_mov_b32_e32 v131, v163
	v_mov_b32_e32 v199, v211
	s_mov_b64 s[98:99], s[100:101]
	s_mov_b32 s52, s94
	s_cmp_lt_i32 s52, 0x4000
	s_cbranch_scc1 .Lcb2_loop
	s_waitcnt vmcnt(0)
